# same as previous plus: s_setprio pairs removed from the GEMM K-loops whose load segments no longer contain VALU work
# speedup vs baseline: 1.0199x; 1.0007x over previous
; #define PG8_STAGE(bufoff, gbase, voff) do { _Pragma("unroll") for (int _i = 0; _i < 2; ++_i) \
;         __builtin_amdgcn_global_load_lds((const unsigned*)((const char*)(gbase) + (voff)[_i]), (LAS unsigned*)(lds + (bufoff) + ldsw + _i * 8192), 16, 0, 0); } while (0)
; #define PG8_LDA(dst, b, h) do { _Pragma("unroll") for (int m = 0; m < 4; ++m) _Pragma("unroll") for (int k = 0; k < 2; ++k) dst[m][k] = *(const LAS bf16x8*)(lds + PG8_SA(b, h) + aoff + m * 2048 + k * 1024); } while (0)
; #define PG8_LDB(dst, b, h) do { _Pragma("unroll") for (int n = 0; n < 2; ++n) _Pragma("unroll") for (int k = 0; k < 2; ++k) dst[n][k] = *(const LAS bf16x8*)(lds + PG8_SB(b, h) + boff + n * 2048 + k * 1024); } while (0)
; #define PG8_MMA(ai, bj, At, Bt) do { __builtin_amdgcn_s_setprio(1); _Pragma("unroll") for (int m = 0; m < 4; ++m) _Pragma("unroll") for (int n = 0; n < 2; ++n) _Pragma("unroll") for (int k = 0; k < 2; ++k) \
;         acc[ai][bj][m][n] = __builtin_amdgcn_mfma_f32_16x16x32_bf16(Bt[n][k], At[m][k], acc[ai][bj][m][n], 0, 0, 0); __builtin_amdgcn_s_setprio(0); } while (0)
; #define PG8_WAIT_V(n) asm volatile("s_waitcnt vmcnt(" #n ")" ::: "memory")
; #define PG8_WAIT_L(n) asm volatile("s_waitcnt lgkmcnt(" #n ")" ::: "memory")
; template <class Epi, class Sched>
; __device__ __forceinline__ void gemm_phase(LAS unsigned char* lds, const Gemm g, const Sched& S, const Epi& E) {
;     ...
;         const bool has_next = S.next(ui + 1, nxt);
;         const char* nA = has_next ? (const char*)g.A + (size_t)nxt.pm * tstepA + (size_t)nxt.pn * g.a_pn_off * 2 : cA; const char* nB = has_next ? (const char*)g.Bt + (size_t)nxt.pn * tstepB : cB;
;         for (int t = 0; t < nt; t += 2) {
;             const bool last = (t == nt - 2);
;             const char* a1 = cA + (size_t)(t + 1) * kstep;
;             const char* a2 = last ? nA : cA + (size_t)(t + 2) * kstep; const char* b2 = last ? nB : cB + (size_t)(t + 2) * kstep;
;             const char* a3 = a2 + kstep; const char* b3 = b2 + kstep;
;             PG8_LDB(B0, 0, 0); PG8_LDB(B1, 0, 1); PG8_SCHED; PG8_LDA(At, 0, 0); PG8_STAGE(PG8_SA(1, 1), a1 + hstepA, voffA);
;             PG8_WAIT_V(8); PG8_WAIT_L(0); PG8_BAR; PG8_MMA(0, 0, At, B0); PG8_MMA(0, 1, At, B1); PG8_BAR; PG8_SCHED;
;             PG8_LDA(At, 0, 1); PG8_STAGE(PG8_SB(0, 0), b2, voffB); PG8_STAGE(PG8_SB(0, 1), b2 + hstepB, voffB); PG8_STAGE(PG8_SA(0, 0), a2, voffA);
.LBB0_231:
	s_ashr_i32 s83, s82, 31
	s_lshl_b64 s[36:37], s[82:83], 19
	s_add_u32 s84, s4, s36
	s_addc_u32 s85, s5, s37
	s_and_b64 s[36:37], s[70:71], exec
	s_cselect_b32 s43, s85, s19
	s_cselect_b32 s48, s84, s18
	s_ashr_i32 s81, s80, 31
	s_lshl_b64 s[36:37], s[80:81], 19
	v_readlane_b32 s12, v248, 5
	s_add_u32 s36, s12, s36
	v_readlane_b32 s12, v248, 6
	s_addc_u32 s37, s12, s37
	s_and_b64 s[86:87], s[70:71], exec
	s_cselect_b32 s49, s37, s21
	s_cselect_b32 s53, s36, s20
	s_add_u32 s18, s18, 0x40080
	s_addc_u32 s19, s19, 0
	s_add_u32 s54, s20, 0x100
	s_addc_u32 s81, s21, 0
	s_mov_b32 s83, -2
	s_add_u32 s20, s18, 0xfffc0080
	s_addc_u32 s21, s19, -1
	s_add_i32 s88, 0, 0x10000
	s_cmp_eq_u32 s83, 12
	s_cselect_b32 s21, s43, s21
	s_cselect_b32 s20, s48, s20
	s_cselect_b32 s87, s49, s81
	s_cselect_b32 s86, s53, s54
	s_add_i32 s90, 0, 0x14000
	s_add_u32 s100, s20, 0x80
	s_addc_u32 s101, s21, 0
	ds_read_b128 v[130:133], v246
	ds_read_b128 v[134:137], v246 offset:1024
	ds_read_b128 v[138:141], v246 offset:2048
	ds_read_b128 v[142:145], v246 offset:3072
	ds_read_b128 v[146:149], v246 offset:16384
	ds_read_b128 v[150:153], v246 offset:17408
	ds_read_b128 v[154:157], v246 offset:18432
	ds_read_b128 v[158:161], v246 offset:19456
	s_add_i32 m0, s9, 0xc000
	ds_read_b128 v[162:165], v222
	ds_read_b128 v[166:169], v222 offset:1024
	ds_read_b128 v[194:197], v222 offset:2048
	ds_read_b128 v[198:201], v222 offset:3072
	ds_read_b128 v[202:205], v222 offset:4096
	ds_read_b128 v[224:227], v222 offset:5120
	ds_read_b128 v[228:231], v222 offset:6144
	ds_read_b128 v[232:235], v222 offset:7168
	global_load_lds_dwordx4 v170, s[18:19]
	s_add_i32 m0, s9, 0xe000
	s_nop 0
	global_load_lds_dwordx4 v190, s[18:19]
	s_waitcnt vmcnt(8)
	s_waitcnt lgkmcnt(0)
	s_barrier
	s_waitcnt lgkmcnt(0)
	v_mfma_f32_16x16x32_bf16 v[126:129], v[130:133], v[162:165], 0
	v_mfma_f32_16x16x32_bf16 v[118:121], v[138:141], v[162:165], 0
	v_mfma_f32_16x16x32_bf16 v[110:113], v[130:133], v[194:197], 0
	v_mfma_f32_16x16x32_bf16 v[102:105], v[138:141], v[194:197], 0
	v_mfma_f32_16x16x32_bf16 v[94:97], v[130:133], v[202:205], 0
	v_mfma_f32_16x16x32_bf16 v[86:89], v[138:141], v[202:205], 0
	v_mfma_f32_16x16x32_bf16 v[78:81], v[130:133], v[228:231], 0
	v_mfma_f32_16x16x32_bf16 v[70:73], v[138:141], v[228:231], 0
	v_mfma_f32_16x16x32_bf16 v[126:129], v[134:137], v[166:169], v[126:129]
	v_mfma_f32_16x16x32_bf16 v[118:121], v[142:145], v[166:169], v[118:121]
	v_mfma_f32_16x16x32_bf16 v[110:113], v[134:137], v[198:201], v[110:113]
	v_mfma_f32_16x16x32_bf16 v[102:105], v[142:145], v[198:201], v[102:105]
	v_mfma_f32_16x16x32_bf16 v[94:97], v[134:137], v[224:227], v[94:97]
	v_mfma_f32_16x16x32_bf16 v[86:89], v[142:145], v[224:227], v[86:89]
	v_mfma_f32_16x16x32_bf16 v[78:81], v[134:137], v[232:235], v[78:81]
	v_mfma_f32_16x16x32_bf16 v[70:73], v[142:145], v[232:235], v[70:73]
	v_mfma_f32_16x16x32_bf16 v[122:125], v[146:149], v[162:165], 0
	v_mfma_f32_16x16x32_bf16 v[114:117], v[154:157], v[162:165], 0
	v_mfma_f32_16x16x32_bf16 v[106:109], v[146:149], v[194:197], 0
	v_mfma_f32_16x16x32_bf16 v[98:101], v[154:157], v[194:197], 0
	v_mfma_f32_16x16x32_bf16 v[90:93], v[146:149], v[202:205], 0
	v_mfma_f32_16x16x32_bf16 v[82:85], v[154:157], v[202:205], 0
	v_mfma_f32_16x16x32_bf16 v[74:77], v[146:149], v[228:231], 0
	v_mfma_f32_16x16x32_bf16 v[66:69], v[154:157], v[228:231], 0
	v_mfma_f32_16x16x32_bf16 v[122:125], v[150:153], v[166:169], v[122:125]
	v_mfma_f32_16x16x32_bf16 v[114:117], v[158:161], v[166:169], v[114:117]
	v_mfma_f32_16x16x32_bf16 v[106:109], v[150:153], v[198:201], v[106:109]
	v_mfma_f32_16x16x32_bf16 v[98:101], v[158:161], v[198:201], v[98:101]
	v_mfma_f32_16x16x32_bf16 v[90:93], v[150:153], v[224:227], v[90:93]
	v_mfma_f32_16x16x32_bf16 v[82:85], v[158:161], v[224:227], v[82:85]
	v_mfma_f32_16x16x32_bf16 v[74:77], v[150:153], v[232:235], v[74:77]
	v_mfma_f32_16x16x32_bf16 v[66:69], v[158:161], v[232:235], v[66:69]
	s_barrier
	s_add_i32 s88, s88, s8
	s_mov_b32 m0, s88
	ds_read_b128 v[162:165], v222 offset:16384
	ds_read_b128 v[166:169], v222 offset:17408
	ds_read_b128 v[194:197], v222 offset:18432
	ds_read_b128 v[198:201], v222 offset:19456
	ds_read_b128 v[202:205], v222 offset:20480
	ds_read_b128 v[224:227], v222 offset:21504
	ds_read_b128 v[228:231], v222 offset:22528
	ds_read_b128 v[232:235], v222 offset:23552
	global_load_lds_dwordx4 v172, s[86:87]
	s_add_i32 m0, s88, 0x2000
	s_add_u32 s88, s86, 0x40000
	s_addc_u32 s89, s87, 0
	s_add_i32 s90, s90, s8
	global_load_lds_dwordx4 v192, s[86:87]
	s_mov_b32 m0, s90
	s_nop 0
	global_load_lds_dwordx4 v172, s[88:89]
	s_add_i32 m0, s90, 0x2000
	s_nop 0
	global_load_lds_dwordx4 v192, s[88:89]
	s_mov_b32 m0, s9
	s_nop 0
	global_load_lds_dwordx4 v170, s[20:21]
	s_mov_b32 m0, s28
	s_nop 0
	global_load_lds_dwordx4 v190, s[20:21]
	s_waitcnt vmcnt(8)
	s_waitcnt lgkmcnt(0)
	s_barrier
; #define PG8_STAGE(bufoff, gbase, voff) do { _Pragma("unroll") for (int _i = 0; _i < 2; ++_i) \
;         __builtin_amdgcn_global_load_lds((const unsigned*)((const char*)(gbase) + (voff)[_i]), (LAS unsigned*)(lds + (bufoff) + ldsw + _i * 8192), 16, 0, 0); } while (0)
; #define PG8_LDA(dst, b, h) do { _Pragma("unroll") for (int m = 0; m < 4; ++m) _Pragma("unroll") for (int k = 0; k < 2; ++k) dst[m][k] = *(const LAS bf16x8*)(lds + PG8_SA(b, h) + aoff + m * 2048 + k * 1024); } while (0)
; #define PG8_LDB(dst, b, h) do { _Pragma("unroll") for (int n = 0; n < 2; ++n) _Pragma("unroll") for (int k = 0; k < 2; ++k) dst[n][k] = *(const LAS bf16x8*)(lds + PG8_SB(b, h) + boff + n * 2048 + k * 1024); } while (0)
; #define PG8_MMA(ai, bj, At, Bt) do { __builtin_amdgcn_s_setprio(1); _Pragma("unroll") for (int m = 0; m < 4; ++m) _Pragma("unroll") for (int n = 0; n < 2; ++n) _Pragma("unroll") for (int k = 0; k < 2; ++k) \
;         acc[ai][bj][m][n] = __builtin_amdgcn_mfma_f32_16x16x32_bf16(Bt[n][k], At[m][k], acc[ai][bj][m][n], 0, 0, 0); __builtin_amdgcn_s_setprio(0); } while (0)
; #define PG8_WAIT_V(n) asm volatile("s_waitcnt vmcnt(" #n ")" ::: "memory")
; #define PG8_WAIT_L(n) asm volatile("s_waitcnt lgkmcnt(" #n ")" ::: "memory")
; #define PG8_BAR __builtin_amdgcn_s_barrier()
; #define PG8_SCHED __builtin_amdgcn_sched_barrier(0)
; template <class Epi, class Sched>
; __device__ __forceinline__ void gemm_phase(LAS unsigned char* lds, const Gemm g, const Sched& S, const Epi& E) {
;     ...
;             PG8_WAIT_V(8); PG8_WAIT_L(0); PG8_BAR; PG8_MMA(1, 0, At, B0); PG8_MMA(1, 1, At, B1); PG8_BAR; PG8_SCHED;
;             PG8_LDB(B0, 1, 0); PG8_LDB(B1, 1, 1); PG8_SCHED; PG8_LDA(At, 1, 0); PG8_STAGE(PG8_SA(0, 1), a2 + hstepA, voffA);
;             PG8_WAIT_V(8); PG8_WAIT_L(0); PG8_BAR; PG8_MMA(0, 0, At, B0); PG8_MMA(0, 1, At, B1); PG8_BAR; PG8_SCHED;
	s_waitcnt lgkmcnt(0)
	v_mfma_f32_16x16x32_bf16 v[62:65], v[130:133], v[162:165], 0
	v_mfma_f32_16x16x32_bf16 v[54:57], v[138:141], v[162:165], 0
	v_mfma_f32_16x16x32_bf16 v[46:49], v[130:133], v[194:197], 0
	v_mfma_f32_16x16x32_bf16 v[38:41], v[138:141], v[194:197], 0
	v_mfma_f32_16x16x32_bf16 v[30:33], v[130:133], v[202:205], 0
	v_mfma_f32_16x16x32_bf16 v[22:25], v[138:141], v[202:205], 0
	v_mfma_f32_16x16x32_bf16 v[14:17], v[130:133], v[228:231], 0
	v_mfma_f32_16x16x32_bf16 v[6:9], v[138:141], v[228:231], 0
	v_mfma_f32_16x16x32_bf16 v[62:65], v[134:137], v[166:169], v[62:65]
	v_mfma_f32_16x16x32_bf16 v[54:57], v[142:145], v[166:169], v[54:57]
	v_mfma_f32_16x16x32_bf16 v[46:49], v[134:137], v[198:201], v[46:49]
	v_mfma_f32_16x16x32_bf16 v[38:41], v[142:145], v[198:201], v[38:41]
	v_mfma_f32_16x16x32_bf16 v[30:33], v[134:137], v[224:227], v[30:33]
	v_mfma_f32_16x16x32_bf16 v[22:25], v[142:145], v[224:227], v[22:25]
	v_mfma_f32_16x16x32_bf16 v[14:17], v[134:137], v[232:235], v[14:17]
	v_mfma_f32_16x16x32_bf16 v[6:9], v[142:145], v[232:235], v[6:9]
	v_mfma_f32_16x16x32_bf16 v[58:61], v[146:149], v[162:165], 0
	v_mfma_f32_16x16x32_bf16 v[50:53], v[154:157], v[162:165], 0
	v_mfma_f32_16x16x32_bf16 v[42:45], v[146:149], v[194:197], 0
	v_mfma_f32_16x16x32_bf16 v[34:37], v[154:157], v[194:197], 0
	v_mfma_f32_16x16x32_bf16 v[26:29], v[146:149], v[202:205], 0
	v_mfma_f32_16x16x32_bf16 v[18:21], v[154:157], v[202:205], 0
	v_mfma_f32_16x16x32_bf16 v[10:13], v[146:149], v[228:231], 0
	v_mfma_f32_16x16x32_bf16 v[2:5], v[154:157], v[228:231], 0
	v_mfma_f32_16x16x32_bf16 v[58:61], v[150:153], v[166:169], v[58:61]
	v_mfma_f32_16x16x32_bf16 v[50:53], v[158:161], v[166:169], v[50:53]
	v_mfma_f32_16x16x32_bf16 v[42:45], v[150:153], v[198:201], v[42:45]
	v_mfma_f32_16x16x32_bf16 v[34:37], v[158:161], v[198:201], v[34:37]
	v_mfma_f32_16x16x32_bf16 v[26:29], v[150:153], v[224:227], v[26:29]
	v_mfma_f32_16x16x32_bf16 v[18:21], v[158:161], v[224:227], v[18:21]
	v_mfma_f32_16x16x32_bf16 v[10:13], v[150:153], v[232:235], v[10:13]
	v_mfma_f32_16x16x32_bf16 v[2:5], v[158:161], v[232:235], v[2:5]
	s_barrier
	s_add_i32 s88, 0, 0x18000
	s_add_i32 s89, 0, 0x1c000
	ds_read_b128 v[130:133], v246 offset:32768
	ds_read_b128 v[134:137], v246 offset:33792
	ds_read_b128 v[138:141], v246 offset:34816
	ds_read_b128 v[142:145], v246 offset:35840
	ds_read_b128 v[146:149], v246 offset:49152
	ds_read_b128 v[150:153], v246 offset:50176
	ds_read_b128 v[154:157], v246 offset:51200
	ds_read_b128 v[158:161], v246 offset:52224
	s_add_u32 s20, s20, 0x40000
	s_addc_u32 s21, s21, 0
	s_mov_b32 m0, s29
	ds_read_b128 v[162:165], v222 offset:32768
	ds_read_b128 v[166:169], v222 offset:33792
	ds_read_b128 v[194:197], v222 offset:34816
	ds_read_b128 v[198:201], v222 offset:35840
	ds_read_b128 v[202:205], v222 offset:36864
	ds_read_b128 v[224:227], v222 offset:37888
	ds_read_b128 v[228:231], v222 offset:38912
	ds_read_b128 v[232:235], v222 offset:39936
	global_load_lds_dwordx4 v170, s[20:21]
	s_mov_b32 m0, s30
	s_nop 0
	global_load_lds_dwordx4 v190, s[20:21]
	s_waitcnt vmcnt(8)
	s_waitcnt lgkmcnt(0)
	s_barrier
	s_waitcnt lgkmcnt(0)
	v_mfma_f32_16x16x32_bf16 v[126:129], v[130:133], v[162:165], v[126:129]
	v_mfma_f32_16x16x32_bf16 v[118:121], v[138:141], v[162:165], v[118:121]
	v_mfma_f32_16x16x32_bf16 v[110:113], v[130:133], v[194:197], v[110:113]
	v_mfma_f32_16x16x32_bf16 v[102:105], v[138:141], v[194:197], v[102:105]
	v_mfma_f32_16x16x32_bf16 v[94:97], v[130:133], v[202:205], v[94:97]
	v_mfma_f32_16x16x32_bf16 v[86:89], v[138:141], v[202:205], v[86:89]
	v_mfma_f32_16x16x32_bf16 v[78:81], v[130:133], v[228:231], v[78:81]
	v_mfma_f32_16x16x32_bf16 v[70:73], v[138:141], v[228:231], v[70:73]
	v_mfma_f32_16x16x32_bf16 v[126:129], v[134:137], v[166:169], v[126:129]
	v_mfma_f32_16x16x32_bf16 v[118:121], v[142:145], v[166:169], v[118:121]
	v_mfma_f32_16x16x32_bf16 v[110:113], v[134:137], v[198:201], v[110:113]
	v_mfma_f32_16x16x32_bf16 v[102:105], v[142:145], v[198:201], v[102:105]
	v_mfma_f32_16x16x32_bf16 v[94:97], v[134:137], v[224:227], v[94:97]
	v_mfma_f32_16x16x32_bf16 v[86:89], v[142:145], v[224:227], v[86:89]
	v_mfma_f32_16x16x32_bf16 v[78:81], v[134:137], v[232:235], v[78:81]
	v_mfma_f32_16x16x32_bf16 v[70:73], v[142:145], v[232:235], v[70:73]
	v_mfma_f32_16x16x32_bf16 v[122:125], v[146:149], v[162:165], v[122:125]
	v_mfma_f32_16x16x32_bf16 v[114:117], v[154:157], v[162:165], v[114:117]
	v_mfma_f32_16x16x32_bf16 v[106:109], v[146:149], v[194:197], v[106:109]
	v_mfma_f32_16x16x32_bf16 v[98:101], v[154:157], v[194:197], v[98:101]
	v_mfma_f32_16x16x32_bf16 v[90:93], v[146:149], v[202:205], v[90:93]
	v_mfma_f32_16x16x32_bf16 v[82:85], v[154:157], v[202:205], v[82:85]
	v_mfma_f32_16x16x32_bf16 v[74:77], v[146:149], v[228:231], v[74:77]
	v_mfma_f32_16x16x32_bf16 v[66:69], v[154:157], v[228:231], v[66:69]
	v_mfma_f32_16x16x32_bf16 v[122:125], v[150:153], v[166:169], v[122:125]
	v_mfma_f32_16x16x32_bf16 v[114:117], v[158:161], v[166:169], v[114:117]
	v_mfma_f32_16x16x32_bf16 v[106:109], v[150:153], v[198:201], v[106:109]
	v_mfma_f32_16x16x32_bf16 v[98:101], v[158:161], v[198:201], v[98:101]
	v_mfma_f32_16x16x32_bf16 v[90:93], v[150:153], v[224:227], v[90:93]
	v_mfma_f32_16x16x32_bf16 v[82:85], v[158:161], v[224:227], v[82:85]
	v_mfma_f32_16x16x32_bf16 v[74:77], v[150:153], v[232:235], v[74:77]
	v_mfma_f32_16x16x32_bf16 v[66:69], v[158:161], v[232:235], v[66:69]
	s_barrier
; #define PG8_STAGE(bufoff, gbase, voff) do { _Pragma("unroll") for (int _i = 0; _i < 2; ++_i) \
;         __builtin_amdgcn_global_load_lds((const unsigned*)((const char*)(gbase) + (voff)[_i]), (LAS unsigned*)(lds + (bufoff) + ldsw + _i * 8192), 16, 0, 0); } while (0)
; #define PG8_LDA(dst, b, h) do { _Pragma("unroll") for (int m = 0; m < 4; ++m) _Pragma("unroll") for (int k = 0; k < 2; ++k) dst[m][k] = *(const LAS bf16x8*)(lds + PG8_SA(b, h) + aoff + m * 2048 + k * 1024); } while (0)
; #define PG8_LDB(dst, b, h) do { _Pragma("unroll") for (int n = 0; n < 2; ++n) _Pragma("unroll") for (int k = 0; k < 2; ++k) dst[n][k] = *(const LAS bf16x8*)(lds + PG8_SB(b, h) + boff + n * 2048 + k * 1024); } while (0)
; #define PG8_WAIT_V(n) asm volatile("s_waitcnt vmcnt(" #n ")" ::: "memory")
; #define PG8_WAIT_L(n) asm volatile("s_waitcnt lgkmcnt(" #n ")" ::: "memory")
; template <class Epi, class Sched>
; __device__ __forceinline__ void gemm_phase(LAS unsigned char* lds, const Gemm g, const Sched& S, const Epi& E) {
;     ...
;             const bool last = (t == nt - 2);
;             const char* a1 = cA + (size_t)(t + 1) * kstep;
;             const char* a2 = last ? nA : cA + (size_t)(t + 2) * kstep; const char* b2 = last ? nB : cB + (size_t)(t + 2) * kstep;
;             const char* a3 = a2 + kstep; const char* b3 = b2 + kstep;
;             PG8_LDB(B0, 0, 0); PG8_LDB(B1, 0, 1); PG8_SCHED; PG8_LDA(At, 0, 0); PG8_STAGE(PG8_SA(1, 1), a1 + hstepA, voffA);
;             PG8_WAIT_V(8); PG8_WAIT_L(0); PG8_BAR; PG8_MMA(0, 0, At, B0); PG8_MMA(0, 1, At, B1); PG8_BAR; PG8_SCHED;
;             PG8_LDA(At, 0, 1); PG8_STAGE(PG8_SB(0, 0), b2, voffB); PG8_STAGE(PG8_SB(0, 1), b2 + hstepB, voffB); PG8_STAGE(PG8_SA(0, 0), a2, voffA);
;             PG8_WAIT_V(8); PG8_WAIT_L(0); PG8_BAR; PG8_MMA(1, 0, At, B0); PG8_MMA(1, 1, At, B1); PG8_BAR; PG8_SCHED;
;             PG8_LDB(B0, 1, 0); PG8_LDB(B1, 1, 1); PG8_SCHED; PG8_LDA(At, 1, 0); PG8_STAGE(PG8_SA(0, 1), a2 + hstepA, voffA);
;             PG8_WAIT_V(8); PG8_WAIT_L(0); PG8_BAR; PG8_MMA(0, 0, At, B0); PG8_MMA(0, 1, At, B1); PG8_BAR; PG8_SCHED;
;             PG8_LDA(At, 1, 1); PG8_STAGE(PG8_SB(1, 0), b3, voffB); PG8_STAGE(PG8_SB(1, 1), b3 + hstepB, voffB); PG8_STAGE(PG8_SA(1, 0), a3, voffA);
;             PG8_WAIT_V(8); PG8_WAIT_L(0); PG8_BAR; PG8_MMA(1, 0, At, B0); PG8_MMA(1, 1, At, B1); PG8_BAR; PG8_SCHED;
;         }
	s_add_i32 s20, s8, 0x18000
	s_add_u32 s88, s86, 0x80
	s_addc_u32 s89, s87, 0
	s_mov_b32 m0, s20
	ds_read_b128 v[162:165], v222 offset:49152
	ds_read_b128 v[166:169], v222 offset:50176
	ds_read_b128 v[194:197], v222 offset:51200
	ds_read_b128 v[198:201], v222 offset:52224
	ds_read_b128 v[202:205], v222 offset:53248
	ds_read_b128 v[224:227], v222 offset:54272
	ds_read_b128 v[228:231], v222 offset:55296
	ds_read_b128 v[232:235], v222 offset:56320
	global_load_lds_dwordx4 v172, s[88:89]
	s_add_i32 m0, s20, 0x2000
	s_add_u32 s20, s86, 0x40080
	s_addc_u32 s21, s87, 0
	s_add_i32 s12, s8, 0x1c000
	global_load_lds_dwordx4 v192, s[88:89]
	s_mov_b32 m0, s12
	s_nop 0
	global_load_lds_dwordx4 v172, s[20:21]
	s_add_i32 m0, s12, 0x2000
	s_nop 0
	global_load_lds_dwordx4 v192, s[20:21]
	s_mov_b32 m0, s31
	s_nop 0
	global_load_lds_dwordx4 v170, s[100:101]
	s_mov_b32 m0, s34
	s_nop 0
	global_load_lds_dwordx4 v190, s[100:101]
	s_waitcnt vmcnt(8)
	s_waitcnt lgkmcnt(0)
	s_barrier
	s_waitcnt lgkmcnt(0)
	v_mfma_f32_16x16x32_bf16 v[62:65], v[130:133], v[162:165], v[62:65]
	v_mfma_f32_16x16x32_bf16 v[54:57], v[138:141], v[162:165], v[54:57]
	v_mfma_f32_16x16x32_bf16 v[46:49], v[130:133], v[194:197], v[46:49]
	v_mfma_f32_16x16x32_bf16 v[38:41], v[138:141], v[194:197], v[38:41]
	v_mfma_f32_16x16x32_bf16 v[30:33], v[130:133], v[202:205], v[30:33]
	v_mfma_f32_16x16x32_bf16 v[22:25], v[138:141], v[202:205], v[22:25]
	v_mfma_f32_16x16x32_bf16 v[14:17], v[130:133], v[228:231], v[14:17]
	v_mfma_f32_16x16x32_bf16 v[6:9], v[138:141], v[228:231], v[6:9]
	v_mfma_f32_16x16x32_bf16 v[62:65], v[134:137], v[166:169], v[62:65]
	v_mfma_f32_16x16x32_bf16 v[54:57], v[142:145], v[166:169], v[54:57]
	v_mfma_f32_16x16x32_bf16 v[46:49], v[134:137], v[198:201], v[46:49]
	v_mfma_f32_16x16x32_bf16 v[38:41], v[142:145], v[198:201], v[38:41]
	v_mfma_f32_16x16x32_bf16 v[30:33], v[134:137], v[224:227], v[30:33]
	v_mfma_f32_16x16x32_bf16 v[22:25], v[142:145], v[224:227], v[22:25]
	v_mfma_f32_16x16x32_bf16 v[14:17], v[134:137], v[232:235], v[14:17]
	v_mfma_f32_16x16x32_bf16 v[6:9], v[142:145], v[232:235], v[6:9]
	v_mfma_f32_16x16x32_bf16 v[58:61], v[146:149], v[162:165], v[58:61]
	v_mfma_f32_16x16x32_bf16 v[50:53], v[154:157], v[162:165], v[50:53]
	v_mfma_f32_16x16x32_bf16 v[42:45], v[146:149], v[194:197], v[42:45]
	v_mfma_f32_16x16x32_bf16 v[34:37], v[154:157], v[194:197], v[34:37]
	v_mfma_f32_16x16x32_bf16 v[26:29], v[146:149], v[202:205], v[26:29]
	v_mfma_f32_16x16x32_bf16 v[18:21], v[154:157], v[202:205], v[18:21]
	v_mfma_f32_16x16x32_bf16 v[10:13], v[146:149], v[228:231], v[10:13]
	v_mfma_f32_16x16x32_bf16 v[2:5], v[154:157], v[228:231], v[2:5]
	v_mfma_f32_16x16x32_bf16 v[58:61], v[150:153], v[166:169], v[58:61]
	v_mfma_f32_16x16x32_bf16 v[50:53], v[158:161], v[166:169], v[50:53]
	v_mfma_f32_16x16x32_bf16 v[42:45], v[150:153], v[198:201], v[42:45]
	v_mfma_f32_16x16x32_bf16 v[34:37], v[158:161], v[198:201], v[34:37]
	v_mfma_f32_16x16x32_bf16 v[26:29], v[150:153], v[224:227], v[26:29]
	v_mfma_f32_16x16x32_bf16 v[18:21], v[158:161], v[224:227], v[18:21]
	v_mfma_f32_16x16x32_bf16 v[10:13], v[150:153], v[232:235], v[10:13]
	v_mfma_f32_16x16x32_bf16 v[2:5], v[158:161], v[232:235], v[2:5]
	s_barrier
	s_add_i32 s83, s83, 2
	s_add_u32 s18, s18, 0x100
	s_addc_u32 s19, s19, 0
	s_add_u32 s54, s54, 0x100
	s_addc_u32 s81, s81, 0
	s_cmp_gt_u32 s83, 13
.LBB0_232:
	s_add_u32 s20, s18, 0xfffc0080
	s_addc_u32 s21, s19, -1
	s_add_i32 s88, 0, 0x10000
	s_cmp_eq_u32 s83, 12
	s_cselect_b32 s21, s43, s21
	s_cselect_b32 s20, s48, s20
	s_cselect_b32 s87, s49, s81
	s_cselect_b32 s86, s53, s54
	s_add_i32 s90, 0, 0x14000
	s_add_u32 s100, s20, 0x80
	s_addc_u32 s101, s21, 0
	ds_read_b128 v[130:133], v246
	ds_read_b128 v[134:137], v246 offset:1024
	ds_read_b128 v[138:141], v246 offset:2048
	ds_read_b128 v[142:145], v246 offset:3072
	ds_read_b128 v[146:149], v246 offset:16384
	ds_read_b128 v[150:153], v246 offset:17408
	ds_read_b128 v[154:157], v246 offset:18432
	ds_read_b128 v[158:161], v246 offset:19456
	s_add_i32 m0, s9, 0xc000
	ds_read_b128 v[162:165], v222
	ds_read_b128 v[166:169], v222 offset:1024
	ds_read_b128 v[194:197], v222 offset:2048
	ds_read_b128 v[198:201], v222 offset:3072
	ds_read_b128 v[202:205], v222 offset:4096
	ds_read_b128 v[224:227], v222 offset:5120
	ds_read_b128 v[228:231], v222 offset:6144
	ds_read_b128 v[232:235], v222 offset:7168
	global_load_lds_dwordx4 v170, s[18:19]
	s_add_i32 m0, s9, 0xe000
	s_nop 0
	global_load_lds_dwordx4 v190, s[18:19]
	s_waitcnt vmcnt(8)
	s_waitcnt lgkmcnt(0)
	s_barrier
; #define PG8_STAGE(bufoff, gbase, voff) do { _Pragma("unroll") for (int _i = 0; _i < 2; ++_i) \
;         __builtin_amdgcn_global_load_lds((const unsigned*)((const char*)(gbase) + (voff)[_i]), (LAS unsigned*)(lds + (bufoff) + ldsw + _i * 8192), 16, 0, 0); } while (0)
; #define PG8_LDA(dst, b, h) do { _Pragma("unroll") for (int m = 0; m < 4; ++m) _Pragma("unroll") for (int k = 0; k < 2; ++k) dst[m][k] = *(const LAS bf16x8*)(lds + PG8_SA(b, h) + aoff + m * 2048 + k * 1024); } while (0)
; #define PG8_MMA(ai, bj, At, Bt) do { __builtin_amdgcn_s_setprio(1); _Pragma("unroll") for (int m = 0; m < 4; ++m) _Pragma("unroll") for (int n = 0; n < 2; ++n) _Pragma("unroll") for (int k = 0; k < 2; ++k) \
;         acc[ai][bj][m][n] = __builtin_amdgcn_mfma_f32_16x16x32_bf16(Bt[n][k], At[m][k], acc[ai][bj][m][n], 0, 0, 0); __builtin_amdgcn_s_setprio(0); } while (0)
; #define PG8_WAIT_V(n) asm volatile("s_waitcnt vmcnt(" #n ")" ::: "memory")
; #define PG8_WAIT_L(n) asm volatile("s_waitcnt lgkmcnt(" #n ")" ::: "memory")
; #define PG8_BAR __builtin_amdgcn_s_barrier()
; #define PG8_SCHED __builtin_amdgcn_sched_barrier(0)
; template <class Epi, class Sched>
; __device__ __forceinline__ void gemm_phase(LAS unsigned char* lds, const Gemm g, const Sched& S, const Epi& E) {
;     ...
;             PG8_WAIT_V(8); PG8_WAIT_L(0); PG8_BAR; PG8_MMA(0, 0, At, B0); PG8_MMA(0, 1, At, B1); PG8_BAR; PG8_SCHED;
;             PG8_LDA(At, 0, 1); PG8_STAGE(PG8_SB(0, 0), b2, voffB); PG8_STAGE(PG8_SB(0, 1), b2 + hstepB, voffB); PG8_STAGE(PG8_SA(0, 0), a2, voffA);
;             PG8_WAIT_V(8); PG8_WAIT_L(0); PG8_BAR; PG8_MMA(1, 0, At, B0); PG8_MMA(1, 1, At, B1); PG8_BAR; PG8_SCHED;
	s_waitcnt lgkmcnt(0)
	v_mfma_f32_16x16x32_bf16 v[126:129], v[130:133], v[162:165], v[126:129]
	v_mfma_f32_16x16x32_bf16 v[118:121], v[138:141], v[162:165], v[118:121]
	v_mfma_f32_16x16x32_bf16 v[110:113], v[130:133], v[194:197], v[110:113]
	v_mfma_f32_16x16x32_bf16 v[102:105], v[138:141], v[194:197], v[102:105]
	v_mfma_f32_16x16x32_bf16 v[94:97], v[130:133], v[202:205], v[94:97]
	v_mfma_f32_16x16x32_bf16 v[86:89], v[138:141], v[202:205], v[86:89]
	v_mfma_f32_16x16x32_bf16 v[78:81], v[130:133], v[228:231], v[78:81]
	v_mfma_f32_16x16x32_bf16 v[70:73], v[138:141], v[228:231], v[70:73]
	v_mfma_f32_16x16x32_bf16 v[126:129], v[134:137], v[166:169], v[126:129]
	v_mfma_f32_16x16x32_bf16 v[118:121], v[142:145], v[166:169], v[118:121]
	v_mfma_f32_16x16x32_bf16 v[110:113], v[134:137], v[198:201], v[110:113]
	v_mfma_f32_16x16x32_bf16 v[102:105], v[142:145], v[198:201], v[102:105]
	v_mfma_f32_16x16x32_bf16 v[94:97], v[134:137], v[224:227], v[94:97]
	v_mfma_f32_16x16x32_bf16 v[86:89], v[142:145], v[224:227], v[86:89]
	v_mfma_f32_16x16x32_bf16 v[78:81], v[134:137], v[232:235], v[78:81]
	v_mfma_f32_16x16x32_bf16 v[70:73], v[142:145], v[232:235], v[70:73]
	v_mfma_f32_16x16x32_bf16 v[122:125], v[146:149], v[162:165], v[122:125]
	v_mfma_f32_16x16x32_bf16 v[114:117], v[154:157], v[162:165], v[114:117]
	v_mfma_f32_16x16x32_bf16 v[106:109], v[146:149], v[194:197], v[106:109]
	v_mfma_f32_16x16x32_bf16 v[98:101], v[154:157], v[194:197], v[98:101]
	v_mfma_f32_16x16x32_bf16 v[90:93], v[146:149], v[202:205], v[90:93]
	v_mfma_f32_16x16x32_bf16 v[82:85], v[154:157], v[202:205], v[82:85]
	v_mfma_f32_16x16x32_bf16 v[74:77], v[146:149], v[228:231], v[74:77]
	v_mfma_f32_16x16x32_bf16 v[66:69], v[154:157], v[228:231], v[66:69]
	v_mfma_f32_16x16x32_bf16 v[122:125], v[150:153], v[166:169], v[122:125]
	v_mfma_f32_16x16x32_bf16 v[114:117], v[158:161], v[166:169], v[114:117]
	v_mfma_f32_16x16x32_bf16 v[106:109], v[150:153], v[198:201], v[106:109]
	v_mfma_f32_16x16x32_bf16 v[98:101], v[158:161], v[198:201], v[98:101]
	v_mfma_f32_16x16x32_bf16 v[90:93], v[150:153], v[224:227], v[90:93]
	v_mfma_f32_16x16x32_bf16 v[82:85], v[158:161], v[224:227], v[82:85]
	v_mfma_f32_16x16x32_bf16 v[74:77], v[150:153], v[232:235], v[74:77]
	v_mfma_f32_16x16x32_bf16 v[66:69], v[158:161], v[232:235], v[66:69]
	s_barrier
	s_add_i32 s88, s88, s8
	s_mov_b32 m0, s88
	ds_read_b128 v[162:165], v222 offset:16384
	ds_read_b128 v[166:169], v222 offset:17408
	ds_read_b128 v[194:197], v222 offset:18432
	ds_read_b128 v[198:201], v222 offset:19456
	ds_read_b128 v[202:205], v222 offset:20480
	ds_read_b128 v[224:227], v222 offset:21504
	ds_read_b128 v[228:231], v222 offset:22528
	ds_read_b128 v[232:235], v222 offset:23552
	global_load_lds_dwordx4 v172, s[86:87]
	s_add_i32 m0, s88, 0x2000
	s_add_u32 s88, s86, 0x40000
	s_addc_u32 s89, s87, 0
	s_add_i32 s90, s90, s8
	global_load_lds_dwordx4 v192, s[86:87]
	s_mov_b32 m0, s90
	s_nop 0
	global_load_lds_dwordx4 v172, s[88:89]
	s_add_i32 m0, s90, 0x2000
	s_nop 0
	global_load_lds_dwordx4 v192, s[88:89]
	s_mov_b32 m0, s9
	s_nop 0
	global_load_lds_dwordx4 v170, s[20:21]
	s_mov_b32 m0, s28
	s_nop 0
	global_load_lds_dwordx4 v190, s[20:21]
	s_waitcnt vmcnt(8)
	s_waitcnt lgkmcnt(0)
	s_barrier
	s_waitcnt lgkmcnt(0)
	v_mfma_f32_16x16x32_bf16 v[62:65], v[130:133], v[162:165], v[62:65]
	v_mfma_f32_16x16x32_bf16 v[54:57], v[138:141], v[162:165], v[54:57]
	v_mfma_f32_16x16x32_bf16 v[46:49], v[130:133], v[194:197], v[46:49]
	v_mfma_f32_16x16x32_bf16 v[38:41], v[138:141], v[194:197], v[38:41]
	v_mfma_f32_16x16x32_bf16 v[30:33], v[130:133], v[202:205], v[30:33]
	v_mfma_f32_16x16x32_bf16 v[22:25], v[138:141], v[202:205], v[22:25]
	v_mfma_f32_16x16x32_bf16 v[14:17], v[130:133], v[228:231], v[14:17]
	v_mfma_f32_16x16x32_bf16 v[6:9], v[138:141], v[228:231], v[6:9]
	v_mfma_f32_16x16x32_bf16 v[62:65], v[134:137], v[166:169], v[62:65]
	v_mfma_f32_16x16x32_bf16 v[54:57], v[142:145], v[166:169], v[54:57]
	v_mfma_f32_16x16x32_bf16 v[46:49], v[134:137], v[198:201], v[46:49]
	v_mfma_f32_16x16x32_bf16 v[38:41], v[142:145], v[198:201], v[38:41]
	v_mfma_f32_16x16x32_bf16 v[30:33], v[134:137], v[224:227], v[30:33]
	v_mfma_f32_16x16x32_bf16 v[22:25], v[142:145], v[224:227], v[22:25]
	v_mfma_f32_16x16x32_bf16 v[14:17], v[134:137], v[232:235], v[14:17]
	v_mfma_f32_16x16x32_bf16 v[6:9], v[142:145], v[232:235], v[6:9]
	v_mfma_f32_16x16x32_bf16 v[58:61], v[146:149], v[162:165], v[58:61]
	v_mfma_f32_16x16x32_bf16 v[50:53], v[154:157], v[162:165], v[50:53]
	v_mfma_f32_16x16x32_bf16 v[42:45], v[146:149], v[194:197], v[42:45]
	v_mfma_f32_16x16x32_bf16 v[34:37], v[154:157], v[194:197], v[34:37]
	v_mfma_f32_16x16x32_bf16 v[26:29], v[146:149], v[202:205], v[26:29]
	v_mfma_f32_16x16x32_bf16 v[18:21], v[154:157], v[202:205], v[18:21]
	v_mfma_f32_16x16x32_bf16 v[10:13], v[146:149], v[228:231], v[10:13]
	v_mfma_f32_16x16x32_bf16 v[2:5], v[154:157], v[228:231], v[2:5]
	v_mfma_f32_16x16x32_bf16 v[58:61], v[150:153], v[166:169], v[58:61]
	v_mfma_f32_16x16x32_bf16 v[50:53], v[158:161], v[166:169], v[50:53]
	v_mfma_f32_16x16x32_bf16 v[42:45], v[150:153], v[198:201], v[42:45]
	v_mfma_f32_16x16x32_bf16 v[34:37], v[158:161], v[198:201], v[34:37]
	v_mfma_f32_16x16x32_bf16 v[26:29], v[150:153], v[224:227], v[26:29]
	v_mfma_f32_16x16x32_bf16 v[18:21], v[158:161], v[224:227], v[18:21]
	v_mfma_f32_16x16x32_bf16 v[10:13], v[150:153], v[232:235], v[10:13]
	v_mfma_f32_16x16x32_bf16 v[2:5], v[158:161], v[232:235], v[2:5]
	s_barrier
; #define PG8_STAGE(bufoff, gbase, voff) do { _Pragma("unroll") for (int _i = 0; _i < 2; ++_i) \
;         __builtin_amdgcn_global_load_lds((const unsigned*)((const char*)(gbase) + (voff)[_i]), (LAS unsigned*)(lds + (bufoff) + ldsw + _i * 8192), 16, 0, 0); } while (0)
; #define PG8_LDA(dst, b, h) do { _Pragma("unroll") for (int m = 0; m < 4; ++m) _Pragma("unroll") for (int k = 0; k < 2; ++k) dst[m][k] = *(const LAS bf16x8*)(lds + PG8_SA(b, h) + aoff + m * 2048 + k * 1024); } while (0)
; #define PG8_LDB(dst, b, h) do { _Pragma("unroll") for (int n = 0; n < 2; ++n) _Pragma("unroll") for (int k = 0; k < 2; ++k) dst[n][k] = *(const LAS bf16x8*)(lds + PG8_SB(b, h) + boff + n * 2048 + k * 1024); } while (0)
; #define PG8_MMA(ai, bj, At, Bt) do { __builtin_amdgcn_s_setprio(1); _Pragma("unroll") for (int m = 0; m < 4; ++m) _Pragma("unroll") for (int n = 0; n < 2; ++n) _Pragma("unroll") for (int k = 0; k < 2; ++k) \
;         acc[ai][bj][m][n] = __builtin_amdgcn_mfma_f32_16x16x32_bf16(Bt[n][k], At[m][k], acc[ai][bj][m][n], 0, 0, 0); __builtin_amdgcn_s_setprio(0); } while (0)
; #define PG8_WAIT_V(n) asm volatile("s_waitcnt vmcnt(" #n ")" ::: "memory")
; #define PG8_WAIT_L(n) asm volatile("s_waitcnt lgkmcnt(" #n ")" ::: "memory")
; #define PG8_BAR __builtin_amdgcn_s_barrier()
; #define PG8_SCHED __builtin_amdgcn_sched_barrier(0)
; template <class Epi, class Sched>
; __device__ __forceinline__ void gemm_phase(LAS unsigned char* lds, const Gemm g, const Sched& S, const Epi& E) {
;     ...
;             PG8_LDB(B0, 1, 0); PG8_LDB(B1, 1, 1); PG8_SCHED; PG8_LDA(At, 1, 0); PG8_STAGE(PG8_SA(0, 1), a2 + hstepA, voffA);
;             PG8_WAIT_V(8); PG8_WAIT_L(0); PG8_BAR; PG8_MMA(0, 0, At, B0); PG8_MMA(0, 1, At, B1); PG8_BAR; PG8_SCHED;
;             PG8_LDA(At, 1, 1); PG8_STAGE(PG8_SB(1, 0), b3, voffB); PG8_STAGE(PG8_SB(1, 1), b3 + hstepB, voffB); PG8_STAGE(PG8_SA(1, 0), a3, voffA);
;             PG8_WAIT_V(8); PG8_WAIT_L(0); PG8_BAR; PG8_MMA(1, 0, At, B0); PG8_MMA(1, 1, At, B1); PG8_BAR; PG8_SCHED;
;         }
;         if (wr == 0) PG8_BAR;
	s_add_i32 s88, 0, 0x18000
	s_add_i32 s89, 0, 0x1c000
	ds_read_b128 v[130:133], v246 offset:32768
	ds_read_b128 v[134:137], v246 offset:33792
	ds_read_b128 v[138:141], v246 offset:34816
	ds_read_b128 v[142:145], v246 offset:35840
	ds_read_b128 v[146:149], v246 offset:49152
	ds_read_b128 v[150:153], v246 offset:50176
	ds_read_b128 v[154:157], v246 offset:51200
	ds_read_b128 v[158:161], v246 offset:52224
	s_add_u32 s20, s20, 0x40000
	s_addc_u32 s21, s21, 0
	s_mov_b32 m0, s29
	ds_read_b128 v[162:165], v222 offset:32768
	ds_read_b128 v[166:169], v222 offset:33792
	ds_read_b128 v[194:197], v222 offset:34816
	ds_read_b128 v[198:201], v222 offset:35840
	ds_read_b128 v[202:205], v222 offset:36864
	ds_read_b128 v[224:227], v222 offset:37888
	ds_read_b128 v[228:231], v222 offset:38912
	ds_read_b128 v[232:235], v222 offset:39936
	global_load_lds_dwordx4 v170, s[20:21]
	s_mov_b32 m0, s30
	s_nop 0
	global_load_lds_dwordx4 v190, s[20:21]
	s_waitcnt vmcnt(8)
	s_waitcnt lgkmcnt(0)
	s_barrier
	s_waitcnt lgkmcnt(0)
	v_mfma_f32_16x16x32_bf16 v[126:129], v[130:133], v[162:165], v[126:129]
	v_mfma_f32_16x16x32_bf16 v[118:121], v[138:141], v[162:165], v[118:121]
	v_mfma_f32_16x16x32_bf16 v[110:113], v[130:133], v[194:197], v[110:113]
	v_mfma_f32_16x16x32_bf16 v[102:105], v[138:141], v[194:197], v[102:105]
	v_mfma_f32_16x16x32_bf16 v[94:97], v[130:133], v[202:205], v[94:97]
	v_mfma_f32_16x16x32_bf16 v[86:89], v[138:141], v[202:205], v[86:89]
	v_mfma_f32_16x16x32_bf16 v[78:81], v[130:133], v[228:231], v[78:81]
	v_mfma_f32_16x16x32_bf16 v[70:73], v[138:141], v[228:231], v[70:73]
	v_mfma_f32_16x16x32_bf16 v[126:129], v[134:137], v[166:169], v[126:129]
	v_mfma_f32_16x16x32_bf16 v[118:121], v[142:145], v[166:169], v[118:121]
	v_mfma_f32_16x16x32_bf16 v[110:113], v[134:137], v[198:201], v[110:113]
	v_mfma_f32_16x16x32_bf16 v[102:105], v[142:145], v[198:201], v[102:105]
	v_mfma_f32_16x16x32_bf16 v[94:97], v[134:137], v[224:227], v[94:97]
	v_mfma_f32_16x16x32_bf16 v[86:89], v[142:145], v[224:227], v[86:89]
	v_mfma_f32_16x16x32_bf16 v[78:81], v[134:137], v[232:235], v[78:81]
	v_mfma_f32_16x16x32_bf16 v[70:73], v[142:145], v[232:235], v[70:73]
	v_mfma_f32_16x16x32_bf16 v[122:125], v[146:149], v[162:165], v[122:125]
	v_mfma_f32_16x16x32_bf16 v[114:117], v[154:157], v[162:165], v[114:117]
	v_mfma_f32_16x16x32_bf16 v[106:109], v[146:149], v[194:197], v[106:109]
	v_mfma_f32_16x16x32_bf16 v[98:101], v[154:157], v[194:197], v[98:101]
	v_mfma_f32_16x16x32_bf16 v[90:93], v[146:149], v[202:205], v[90:93]
	v_mfma_f32_16x16x32_bf16 v[82:85], v[154:157], v[202:205], v[82:85]
	v_mfma_f32_16x16x32_bf16 v[74:77], v[146:149], v[228:231], v[74:77]
	v_mfma_f32_16x16x32_bf16 v[66:69], v[154:157], v[228:231], v[66:69]
	v_mfma_f32_16x16x32_bf16 v[122:125], v[150:153], v[166:169], v[122:125]
	v_mfma_f32_16x16x32_bf16 v[114:117], v[158:161], v[166:169], v[114:117]
	v_mfma_f32_16x16x32_bf16 v[106:109], v[150:153], v[198:201], v[106:109]
	v_mfma_f32_16x16x32_bf16 v[98:101], v[158:161], v[198:201], v[98:101]
	v_mfma_f32_16x16x32_bf16 v[90:93], v[150:153], v[224:227], v[90:93]
	v_mfma_f32_16x16x32_bf16 v[82:85], v[158:161], v[224:227], v[82:85]
	v_mfma_f32_16x16x32_bf16 v[74:77], v[150:153], v[232:235], v[74:77]
	v_mfma_f32_16x16x32_bf16 v[66:69], v[158:161], v[232:235], v[66:69]
	s_barrier
	s_add_i32 s20, s8, 0x18000
	s_add_u32 s88, s86, 0x80
	s_addc_u32 s89, s87, 0
	s_mov_b32 m0, s20
	ds_read_b128 v[162:165], v222 offset:49152
	ds_read_b128 v[166:169], v222 offset:50176
	ds_read_b128 v[194:197], v222 offset:51200
	ds_read_b128 v[198:201], v222 offset:52224
	ds_read_b128 v[202:205], v222 offset:53248
	ds_read_b128 v[224:227], v222 offset:54272
	ds_read_b128 v[228:231], v222 offset:55296
	ds_read_b128 v[232:235], v222 offset:56320
	global_load_lds_dwordx4 v172, s[88:89]
	s_add_i32 m0, s20, 0x2000
	s_add_u32 s20, s86, 0x40080
	s_addc_u32 s21, s87, 0
	s_add_i32 s12, s8, 0x1c000
	global_load_lds_dwordx4 v192, s[88:89]
	s_mov_b32 m0, s12
	s_nop 0
	global_load_lds_dwordx4 v172, s[20:21]
	s_add_i32 m0, s12, 0x2000
	s_nop 0
	global_load_lds_dwordx4 v192, s[20:21]
	s_mov_b32 m0, s31
	s_nop 0
	global_load_lds_dwordx4 v170, s[100:101]
	s_mov_b32 m0, s34
	s_nop 0
	global_load_lds_dwordx4 v190, s[100:101]
	s_waitcnt vmcnt(8)
	s_waitcnt lgkmcnt(0)
	s_barrier
	s_waitcnt lgkmcnt(0)
	v_mfma_f32_16x16x32_bf16 v[62:65], v[130:133], v[162:165], v[62:65]
	v_mfma_f32_16x16x32_bf16 v[54:57], v[138:141], v[162:165], v[54:57]
	v_mfma_f32_16x16x32_bf16 v[46:49], v[130:133], v[194:197], v[46:49]
	v_mfma_f32_16x16x32_bf16 v[38:41], v[138:141], v[194:197], v[38:41]
	v_mfma_f32_16x16x32_bf16 v[30:33], v[130:133], v[202:205], v[30:33]
	v_mfma_f32_16x16x32_bf16 v[22:25], v[138:141], v[202:205], v[22:25]
	v_mfma_f32_16x16x32_bf16 v[14:17], v[130:133], v[228:231], v[14:17]
	v_mfma_f32_16x16x32_bf16 v[6:9], v[138:141], v[228:231], v[6:9]
	v_mfma_f32_16x16x32_bf16 v[62:65], v[134:137], v[166:169], v[62:65]
	v_mfma_f32_16x16x32_bf16 v[54:57], v[142:145], v[166:169], v[54:57]
	v_mfma_f32_16x16x32_bf16 v[46:49], v[134:137], v[198:201], v[46:49]
	v_mfma_f32_16x16x32_bf16 v[38:41], v[142:145], v[198:201], v[38:41]
	v_mfma_f32_16x16x32_bf16 v[30:33], v[134:137], v[224:227], v[30:33]
	v_mfma_f32_16x16x32_bf16 v[22:25], v[142:145], v[224:227], v[22:25]
	v_mfma_f32_16x16x32_bf16 v[14:17], v[134:137], v[232:235], v[14:17]
	v_mfma_f32_16x16x32_bf16 v[6:9], v[142:145], v[232:235], v[6:9]
	v_mfma_f32_16x16x32_bf16 v[58:61], v[146:149], v[162:165], v[58:61]
	v_mfma_f32_16x16x32_bf16 v[50:53], v[154:157], v[162:165], v[50:53]
	v_mfma_f32_16x16x32_bf16 v[42:45], v[146:149], v[194:197], v[42:45]
	v_mfma_f32_16x16x32_bf16 v[34:37], v[154:157], v[194:197], v[34:37]
	v_mfma_f32_16x16x32_bf16 v[26:29], v[146:149], v[202:205], v[26:29]
	v_mfma_f32_16x16x32_bf16 v[18:21], v[154:157], v[202:205], v[18:21]
	v_mfma_f32_16x16x32_bf16 v[10:13], v[146:149], v[228:231], v[10:13]
	v_mfma_f32_16x16x32_bf16 v[2:5], v[154:157], v[228:231], v[2:5]
	v_mfma_f32_16x16x32_bf16 v[58:61], v[150:153], v[166:169], v[58:61]
	v_mfma_f32_16x16x32_bf16 v[50:53], v[158:161], v[166:169], v[50:53]
	v_mfma_f32_16x16x32_bf16 v[42:45], v[150:153], v[198:201], v[42:45]
	v_mfma_f32_16x16x32_bf16 v[34:37], v[158:161], v[198:201], v[34:37]
	v_mfma_f32_16x16x32_bf16 v[26:29], v[150:153], v[224:227], v[26:29]
	v_mfma_f32_16x16x32_bf16 v[18:21], v[158:161], v[224:227], v[18:21]
	v_mfma_f32_16x16x32_bf16 v[10:13], v[150:153], v[232:235], v[10:13]
	v_mfma_f32_16x16x32_bf16 v[2:5], v[158:161], v[232:235], v[2:5]
	s_barrier
	s_add_i32 s83, s83, 2
	s_add_u32 s18, s18, 0x100
	s_addc_u32 s19, s19, 0
	s_add_u32 s54, s54, 0x100
	s_addc_u32 s81, s81, 0
	s_cmp_gt_u32 s83, 13
	s_cbranch_scc0 .LBB0_232
	s_and_b64 vcc, exec, s[72:73]
	s_cbranch_vccz .LBB0_235
	s_barrier

; #define PG8_STAGE(bufoff, gbase, voff) do { _Pragma("unroll") for (int _i = 0; _i < 2; ++_i) \
;         __builtin_amdgcn_global_load_lds((const unsigned*)((const char*)(gbase) + (voff)[_i]), (LAS unsigned*)(lds + (bufoff) + ldsw + _i * 8192), 16, 0, 0); } while (0)
; #define PG8_LDA(dst, b, h) do { _Pragma("unroll") for (int m = 0; m < 4; ++m) _Pragma("unroll") for (int k = 0; k < 2; ++k) dst[m][k] = *(const LAS bf16x8*)(lds + PG8_SA(b, h) + aoff + m * 2048 + k * 1024); } while (0)
; #define PG8_LDB(dst, b, h) do { _Pragma("unroll") for (int n = 0; n < 2; ++n) _Pragma("unroll") for (int k = 0; k < 2; ++k) dst[n][k] = *(const LAS bf16x8*)(lds + PG8_SB(b, h) + boff + n * 2048 + k * 1024); } while (0)
; #define PG8_MMA(ai, bj, At, Bt) do { __builtin_amdgcn_s_setprio(1); _Pragma("unroll") for (int m = 0; m < 4; ++m) _Pragma("unroll") for (int n = 0; n < 2; ++n) _Pragma("unroll") for (int k = 0; k < 2; ++k) \
;         acc[ai][bj][m][n] = __builtin_amdgcn_mfma_f32_16x16x32_bf16(Bt[n][k], At[m][k], acc[ai][bj][m][n], 0, 0, 0); __builtin_amdgcn_s_setprio(0); } while (0)
; #define PG8_WAIT_V(n) asm volatile("s_waitcnt vmcnt(" #n ")" ::: "memory")
; #define PG8_WAIT_L(n) asm volatile("s_waitcnt lgkmcnt(" #n ")" ::: "memory")
; template <class Epi, class Sched>
; __device__ __forceinline__ void gemm_phase(LAS unsigned char* lds, const Gemm g, const Sched& S, const Epi& E) {
;     ...
;         const bool has_next = S.next(ui + 1, nxt);
;         const char* nA = has_next ? (const char*)g.A + (size_t)nxt.pm * tstepA + (size_t)nxt.pn * g.a_pn_off * 2 : cA; const char* nB = has_next ? (const char*)g.Bt + (size_t)nxt.pn * tstepB : cB;
;         for (int t = 0; t < nt; t += 2) {
;             const bool last = (t == nt - 2);
;             const char* a1 = cA + (size_t)(t + 1) * kstep;
;             const char* a2 = last ? nA : cA + (size_t)(t + 2) * kstep; const char* b2 = last ? nB : cB + (size_t)(t + 2) * kstep;
;             const char* a3 = a2 + kstep; const char* b3 = b2 + kstep;
;             PG8_LDB(B0, 0, 0); PG8_LDB(B1, 0, 1); PG8_SCHED; PG8_LDA(At, 0, 0); PG8_STAGE(PG8_SA(1, 1), a1 + hstepA, voffA);
;             PG8_WAIT_V(8); PG8_WAIT_L(0); PG8_BAR; PG8_MMA(0, 0, At, B0); PG8_MMA(0, 1, At, B1); PG8_BAR; PG8_SCHED;
;             PG8_LDA(At, 0, 1); PG8_STAGE(PG8_SB(0, 0), b2, voffB); PG8_STAGE(PG8_SB(0, 1), b2 + hstepB, voffB); PG8_STAGE(PG8_SA(0, 0), a2, voffA);
.LBB0_348:
	s_ashr_i32 s71, s70, 31
	s_lshl_b64 s[48:49], s[70:71], 19
	s_add_u32 s72, s4, s48
	s_addc_u32 s73, s5, s49
	s_and_b64 s[48:49], s[66:67], exec
	s_cselect_b32 s48, s73, s19
	s_cselect_b32 s49, s72, s18
	s_ashr_i32 s69, s68, 31
	s_lshl_b64 s[74:75], s[68:69], 19
	v_readlane_b32 s12, v248, 13
	s_add_u32 s74, s12, s74
	v_readlane_b32 s12, v248, 14
	s_addc_u32 s75, s12, s75
	s_and_b64 s[76:77], s[66:67], exec
	s_cselect_b32 s53, s75, s21
	s_cselect_b32 s54, s74, s20
	s_add_u32 s18, s18, 0x40080
	s_addc_u32 s19, s19, 0
	s_add_u32 s69, s20, 0x100
	s_addc_u32 s71, s21, 0
	s_mov_b32 s78, -2
	s_waitcnt vmcnt(0)
	v_add_u32_e32 v255, 0x10000, v139
	s_add_u32 s20, s18, 0xfffc0080
	s_addc_u32 s21, s19, -1
	s_add_i32 s79, 0, 0x10000
	s_cmp_eq_u32 s78, 12
	s_cselect_b32 s21, s48, s21
	s_cselect_b32 s20, s49, s20
	s_cselect_b32 s77, s53, s71
	s_cselect_b32 s76, s54, s69
	s_add_u32 s100, s20, 0x80
	s_addc_u32 s101, s21, 0
	s_add_i32 s82, 0, 0x14000
	ds_read_b128 v[150:153], v255
	ds_read_b128 v[154:157], v255 offset:1024
	ds_read_b128 v[158:161], v255 offset:2048
	ds_read_b128 v[162:165], v255 offset:3072
	ds_read_b128 v[166:169], v255 offset:16384
	ds_read_b128 v[170:173], v255 offset:17408
	ds_read_b128 v[190:193], v255 offset:18432
	ds_read_b128 v[194:197], v255 offset:19456
	s_add_i32 m0, s9, 0xc000
	ds_read_b128 v[198:201], v148
	ds_read_b128 v[202:205], v148 offset:1024
	ds_read_b128 v[206:209], v148 offset:2048
	ds_read_b128 v[218:221], v148 offset:3072
	ds_read_b128 v[222:225], v148 offset:4096
	ds_read_b128 v[226:229], v148 offset:5120
	ds_read_b128 v[230:233], v148 offset:6144
	ds_read_b128 v[234:237], v148 offset:7168
	global_load_lds_dwordx4 v130, s[18:19]
	s_add_i32 m0, s9, 0xe000
	s_nop 0
	global_load_lds_dwordx4 v134, s[18:19]
	s_waitcnt vmcnt(8)
	s_waitcnt lgkmcnt(0)
	s_barrier
	s_waitcnt lgkmcnt(0)
	v_mfma_f32_16x16x32_bf16 v[126:129], v[150:153], v[198:201], 0
	v_mfma_f32_16x16x32_bf16 v[122:125], v[158:161], v[198:201], 0
	v_mfma_f32_16x16x32_bf16 v[110:113], v[150:153], v[206:209], 0
	v_mfma_f32_16x16x32_bf16 v[106:109], v[158:161], v[206:209], 0
	v_mfma_f32_16x16x32_bf16 v[94:97], v[150:153], v[222:225], 0
	v_mfma_f32_16x16x32_bf16 v[90:93], v[158:161], v[222:225], 0
	v_mfma_f32_16x16x32_bf16 v[82:85], v[150:153], v[230:233], 0
	v_mfma_f32_16x16x32_bf16 v[74:77], v[158:161], v[230:233], 0
	v_mfma_f32_16x16x32_bf16 v[126:129], v[154:157], v[202:205], v[126:129]
	v_mfma_f32_16x16x32_bf16 v[122:125], v[162:165], v[202:205], v[122:125]
	v_mfma_f32_16x16x32_bf16 v[110:113], v[154:157], v[218:221], v[110:113]
	v_mfma_f32_16x16x32_bf16 v[106:109], v[162:165], v[218:221], v[106:109]
	v_mfma_f32_16x16x32_bf16 v[94:97], v[154:157], v[226:229], v[94:97]
	v_mfma_f32_16x16x32_bf16 v[90:93], v[162:165], v[226:229], v[90:93]
	v_mfma_f32_16x16x32_bf16 v[82:85], v[154:157], v[234:237], v[82:85]
	v_mfma_f32_16x16x32_bf16 v[74:77], v[162:165], v[234:237], v[74:77]
	v_mfma_f32_16x16x32_bf16 v[118:121], v[166:169], v[198:201], 0
	v_mfma_f32_16x16x32_bf16 v[114:117], v[190:193], v[198:201], 0
	v_mfma_f32_16x16x32_bf16 v[102:105], v[166:169], v[206:209], 0
	v_mfma_f32_16x16x32_bf16 v[98:101], v[190:193], v[206:209], 0
	v_mfma_f32_16x16x32_bf16 v[86:89], v[166:169], v[222:225], 0
	v_mfma_f32_16x16x32_bf16 v[78:81], v[190:193], v[222:225], 0
	v_mfma_f32_16x16x32_bf16 v[70:73], v[166:169], v[230:233], 0
	v_mfma_f32_16x16x32_bf16 v[66:69], v[190:193], v[230:233], 0
	v_mfma_f32_16x16x32_bf16 v[118:121], v[170:173], v[202:205], v[118:121]
	v_mfma_f32_16x16x32_bf16 v[114:117], v[194:197], v[202:205], v[114:117]
	v_mfma_f32_16x16x32_bf16 v[102:105], v[170:173], v[218:221], v[102:105]
	v_mfma_f32_16x16x32_bf16 v[98:101], v[194:197], v[218:221], v[98:101]
	v_mfma_f32_16x16x32_bf16 v[86:89], v[170:173], v[226:229], v[86:89]
	v_mfma_f32_16x16x32_bf16 v[78:81], v[194:197], v[226:229], v[78:81]
	v_mfma_f32_16x16x32_bf16 v[70:73], v[170:173], v[234:237], v[70:73]
	v_mfma_f32_16x16x32_bf16 v[66:69], v[194:197], v[234:237], v[66:69]
	s_barrier
	s_add_i32 s79, s79, s8
	s_mov_b32 m0, s79
	ds_read_b128 v[198:201], v148 offset:16384
	ds_read_b128 v[202:205], v148 offset:17408
	ds_read_b128 v[206:209], v148 offset:18432
	ds_read_b128 v[218:221], v148 offset:19456
	ds_read_b128 v[222:225], v148 offset:20480
	ds_read_b128 v[226:229], v148 offset:21504
	ds_read_b128 v[230:233], v148 offset:22528
	ds_read_b128 v[234:237], v148 offset:23552
	global_load_lds_dwordx4 v132, s[76:77]
	s_add_i32 m0, s79, 0x2000
	s_add_u32 s80, s76, 0x40000
	s_addc_u32 s81, s77, 0
	s_add_i32 s79, s82, s8
	global_load_lds_dwordx4 v136, s[76:77]
	s_mov_b32 m0, s79
	s_nop 0
	global_load_lds_dwordx4 v132, s[80:81]
	s_add_i32 m0, s79, 0x2000
	s_nop 0
	global_load_lds_dwordx4 v136, s[80:81]
	s_mov_b32 m0, s9
	s_nop 0
	global_load_lds_dwordx4 v130, s[20:21]
	s_mov_b32 m0, s28
	s_nop 0
	global_load_lds_dwordx4 v134, s[20:21]
	s_waitcnt vmcnt(8)
	s_waitcnt lgkmcnt(0)
	s_barrier
; #define PG8_STAGE(bufoff, gbase, voff) do { _Pragma("unroll") for (int _i = 0; _i < 2; ++_i) \
;         __builtin_amdgcn_global_load_lds((const unsigned*)((const char*)(gbase) + (voff)[_i]), (LAS unsigned*)(lds + (bufoff) + ldsw + _i * 8192), 16, 0, 0); } while (0)
; #define PG8_LDA(dst, b, h) do { _Pragma("unroll") for (int m = 0; m < 4; ++m) _Pragma("unroll") for (int k = 0; k < 2; ++k) dst[m][k] = *(const LAS bf16x8*)(lds + PG8_SA(b, h) + aoff + m * 2048 + k * 1024); } while (0)
; #define PG8_LDB(dst, b, h) do { _Pragma("unroll") for (int n = 0; n < 2; ++n) _Pragma("unroll") for (int k = 0; k < 2; ++k) dst[n][k] = *(const LAS bf16x8*)(lds + PG8_SB(b, h) + boff + n * 2048 + k * 1024); } while (0)
; #define PG8_MMA(ai, bj, At, Bt) do { __builtin_amdgcn_s_setprio(1); _Pragma("unroll") for (int m = 0; m < 4; ++m) _Pragma("unroll") for (int n = 0; n < 2; ++n) _Pragma("unroll") for (int k = 0; k < 2; ++k) \
;         acc[ai][bj][m][n] = __builtin_amdgcn_mfma_f32_16x16x32_bf16(Bt[n][k], At[m][k], acc[ai][bj][m][n], 0, 0, 0); __builtin_amdgcn_s_setprio(0); } while (0)
; #define PG8_WAIT_V(n) asm volatile("s_waitcnt vmcnt(" #n ")" ::: "memory")
; #define PG8_WAIT_L(n) asm volatile("s_waitcnt lgkmcnt(" #n ")" ::: "memory")
; #define PG8_BAR __builtin_amdgcn_s_barrier()
; #define PG8_SCHED __builtin_amdgcn_sched_barrier(0)
; template <class Epi, class Sched>
; __device__ __forceinline__ void gemm_phase(LAS unsigned char* lds, const Gemm g, const Sched& S, const Epi& E) {
;     ...
;             PG8_WAIT_V(8); PG8_WAIT_L(0); PG8_BAR; PG8_MMA(1, 0, At, B0); PG8_MMA(1, 1, At, B1); PG8_BAR; PG8_SCHED;
;             PG8_LDB(B0, 1, 0); PG8_LDB(B1, 1, 1); PG8_SCHED; PG8_LDA(At, 1, 0); PG8_STAGE(PG8_SA(0, 1), a2 + hstepA, voffA);
;             PG8_WAIT_V(8); PG8_WAIT_L(0); PG8_BAR; PG8_MMA(0, 0, At, B0); PG8_MMA(0, 1, At, B1); PG8_BAR; PG8_SCHED;
	s_waitcnt lgkmcnt(0)
	v_mfma_f32_16x16x32_bf16 v[62:65], v[150:153], v[198:201], 0
	v_mfma_f32_16x16x32_bf16 v[58:61], v[158:161], v[198:201], 0
	v_mfma_f32_16x16x32_bf16 v[50:53], v[150:153], v[206:209], 0
	v_mfma_f32_16x16x32_bf16 v[42:45], v[158:161], v[206:209], 0
	v_mfma_f32_16x16x32_bf16 v[30:33], v[150:153], v[222:225], 0
	v_mfma_f32_16x16x32_bf16 v[26:29], v[158:161], v[222:225], 0
	v_mfma_f32_16x16x32_bf16 v[18:21], v[150:153], v[230:233], 0
	v_mfma_f32_16x16x32_bf16 v[10:13], v[158:161], v[230:233], 0
	v_mfma_f32_16x16x32_bf16 v[62:65], v[154:157], v[202:205], v[62:65]
	v_mfma_f32_16x16x32_bf16 v[58:61], v[162:165], v[202:205], v[58:61]
	v_mfma_f32_16x16x32_bf16 v[50:53], v[154:157], v[218:221], v[50:53]
	v_mfma_f32_16x16x32_bf16 v[42:45], v[162:165], v[218:221], v[42:45]
	v_mfma_f32_16x16x32_bf16 v[30:33], v[154:157], v[226:229], v[30:33]
	v_mfma_f32_16x16x32_bf16 v[26:29], v[162:165], v[226:229], v[26:29]
	v_mfma_f32_16x16x32_bf16 v[18:21], v[154:157], v[234:237], v[18:21]
	v_mfma_f32_16x16x32_bf16 v[10:13], v[162:165], v[234:237], v[10:13]
	v_mfma_f32_16x16x32_bf16 v[54:57], v[166:169], v[198:201], 0
	v_mfma_f32_16x16x32_bf16 v[46:49], v[190:193], v[198:201], 0
	v_mfma_f32_16x16x32_bf16 v[38:41], v[166:169], v[206:209], 0
	v_mfma_f32_16x16x32_bf16 v[34:37], v[190:193], v[206:209], 0
	v_mfma_f32_16x16x32_bf16 v[22:25], v[166:169], v[222:225], 0
	v_mfma_f32_16x16x32_bf16 v[14:17], v[190:193], v[222:225], 0
	v_mfma_f32_16x16x32_bf16 v[6:9], v[166:169], v[230:233], 0
	v_mfma_f32_16x16x32_bf16 v[2:5], v[190:193], v[230:233], 0
	v_mfma_f32_16x16x32_bf16 v[54:57], v[170:173], v[202:205], v[54:57]
	v_mfma_f32_16x16x32_bf16 v[46:49], v[194:197], v[202:205], v[46:49]
	v_mfma_f32_16x16x32_bf16 v[38:41], v[170:173], v[218:221], v[38:41]
	v_mfma_f32_16x16x32_bf16 v[34:37], v[194:197], v[218:221], v[34:37]
	v_mfma_f32_16x16x32_bf16 v[22:25], v[170:173], v[226:229], v[22:25]
	v_mfma_f32_16x16x32_bf16 v[14:17], v[194:197], v[226:229], v[14:17]
	v_mfma_f32_16x16x32_bf16 v[6:9], v[170:173], v[234:237], v[6:9]
	v_mfma_f32_16x16x32_bf16 v[2:5], v[194:197], v[234:237], v[2:5]
	s_barrier
	s_add_i32 s79, 0, 0x18000
	s_add_i32 s80, 0, 0x1c000
	ds_read_b128 v[150:153], v255 offset:32768
	ds_read_b128 v[154:157], v255 offset:33792
	ds_read_b128 v[158:161], v255 offset:34816
	ds_read_b128 v[162:165], v255 offset:35840
	ds_read_b128 v[166:169], v255 offset:49152
	ds_read_b128 v[170:173], v255 offset:50176
	ds_read_b128 v[190:193], v255 offset:51200
	ds_read_b128 v[194:197], v255 offset:52224
	s_add_u32 s20, s20, 0x40000
	s_addc_u32 s21, s21, 0
	s_mov_b32 m0, s29
	ds_read_b128 v[198:201], v148 offset:32768
	ds_read_b128 v[202:205], v148 offset:33792
	ds_read_b128 v[206:209], v148 offset:34816
	ds_read_b128 v[218:221], v148 offset:35840
	ds_read_b128 v[222:225], v148 offset:36864
	ds_read_b128 v[226:229], v148 offset:37888
	ds_read_b128 v[230:233], v148 offset:38912
	ds_read_b128 v[234:237], v148 offset:39936
	global_load_lds_dwordx4 v130, s[20:21]
	s_mov_b32 m0, s30
	s_nop 0
	global_load_lds_dwordx4 v134, s[20:21]
	s_waitcnt vmcnt(8)
	s_waitcnt lgkmcnt(0)
	s_barrier
	s_waitcnt lgkmcnt(0)
	v_mfma_f32_16x16x32_bf16 v[126:129], v[150:153], v[198:201], v[126:129]
	v_mfma_f32_16x16x32_bf16 v[122:125], v[158:161], v[198:201], v[122:125]
	v_mfma_f32_16x16x32_bf16 v[110:113], v[150:153], v[206:209], v[110:113]
	v_mfma_f32_16x16x32_bf16 v[106:109], v[158:161], v[206:209], v[106:109]
	v_mfma_f32_16x16x32_bf16 v[94:97], v[150:153], v[222:225], v[94:97]
	v_mfma_f32_16x16x32_bf16 v[90:93], v[158:161], v[222:225], v[90:93]
	v_mfma_f32_16x16x32_bf16 v[82:85], v[150:153], v[230:233], v[82:85]
	v_mfma_f32_16x16x32_bf16 v[74:77], v[158:161], v[230:233], v[74:77]
	v_mfma_f32_16x16x32_bf16 v[126:129], v[154:157], v[202:205], v[126:129]
	v_mfma_f32_16x16x32_bf16 v[122:125], v[162:165], v[202:205], v[122:125]
	v_mfma_f32_16x16x32_bf16 v[110:113], v[154:157], v[218:221], v[110:113]
	v_mfma_f32_16x16x32_bf16 v[106:109], v[162:165], v[218:221], v[106:109]
	v_mfma_f32_16x16x32_bf16 v[94:97], v[154:157], v[226:229], v[94:97]
	v_mfma_f32_16x16x32_bf16 v[90:93], v[162:165], v[226:229], v[90:93]
	v_mfma_f32_16x16x32_bf16 v[82:85], v[154:157], v[234:237], v[82:85]
	v_mfma_f32_16x16x32_bf16 v[74:77], v[162:165], v[234:237], v[74:77]
	v_mfma_f32_16x16x32_bf16 v[118:121], v[166:169], v[198:201], v[118:121]
	v_mfma_f32_16x16x32_bf16 v[114:117], v[190:193], v[198:201], v[114:117]
	v_mfma_f32_16x16x32_bf16 v[102:105], v[166:169], v[206:209], v[102:105]
	v_mfma_f32_16x16x32_bf16 v[98:101], v[190:193], v[206:209], v[98:101]
	v_mfma_f32_16x16x32_bf16 v[86:89], v[166:169], v[222:225], v[86:89]
	v_mfma_f32_16x16x32_bf16 v[78:81], v[190:193], v[222:225], v[78:81]
	v_mfma_f32_16x16x32_bf16 v[70:73], v[166:169], v[230:233], v[70:73]
	v_mfma_f32_16x16x32_bf16 v[66:69], v[190:193], v[230:233], v[66:69]
	v_mfma_f32_16x16x32_bf16 v[118:121], v[170:173], v[202:205], v[118:121]
	v_mfma_f32_16x16x32_bf16 v[114:117], v[194:197], v[202:205], v[114:117]
	v_mfma_f32_16x16x32_bf16 v[102:105], v[170:173], v[218:221], v[102:105]
	v_mfma_f32_16x16x32_bf16 v[98:101], v[194:197], v[218:221], v[98:101]
	v_mfma_f32_16x16x32_bf16 v[86:89], v[170:173], v[226:229], v[86:89]
	v_mfma_f32_16x16x32_bf16 v[78:81], v[194:197], v[226:229], v[78:81]
	v_mfma_f32_16x16x32_bf16 v[70:73], v[170:173], v[234:237], v[70:73]
	v_mfma_f32_16x16x32_bf16 v[66:69], v[194:197], v[234:237], v[66:69]
	s_barrier
; #define PG8_STAGE(bufoff, gbase, voff) do { _Pragma("unroll") for (int _i = 0; _i < 2; ++_i) \
;         __builtin_amdgcn_global_load_lds((const unsigned*)((const char*)(gbase) + (voff)[_i]), (LAS unsigned*)(lds + (bufoff) + ldsw + _i * 8192), 16, 0, 0); } while (0)
; #define PG8_LDA(dst, b, h) do { _Pragma("unroll") for (int m = 0; m < 4; ++m) _Pragma("unroll") for (int k = 0; k < 2; ++k) dst[m][k] = *(const LAS bf16x8*)(lds + PG8_SA(b, h) + aoff + m * 2048 + k * 1024); } while (0)
; #define PG8_LDB(dst, b, h) do { _Pragma("unroll") for (int n = 0; n < 2; ++n) _Pragma("unroll") for (int k = 0; k < 2; ++k) dst[n][k] = *(const LAS bf16x8*)(lds + PG8_SB(b, h) + boff + n * 2048 + k * 1024); } while (0)
; #define PG8_WAIT_V(n) asm volatile("s_waitcnt vmcnt(" #n ")" ::: "memory")
; #define PG8_WAIT_L(n) asm volatile("s_waitcnt lgkmcnt(" #n ")" ::: "memory")
; template <class Epi, class Sched>
; __device__ __forceinline__ void gemm_phase(LAS unsigned char* lds, const Gemm g, const Sched& S, const Epi& E) {
;     ...
;             const bool last = (t == nt - 2);
;             const char* a1 = cA + (size_t)(t + 1) * kstep;
;             const char* a2 = last ? nA : cA + (size_t)(t + 2) * kstep; const char* b2 = last ? nB : cB + (size_t)(t + 2) * kstep;
;             const char* a3 = a2 + kstep; const char* b3 = b2 + kstep;
;             PG8_LDB(B0, 0, 0); PG8_LDB(B1, 0, 1); PG8_SCHED; PG8_LDA(At, 0, 0); PG8_STAGE(PG8_SA(1, 1), a1 + hstepA, voffA);
;             PG8_WAIT_V(8); PG8_WAIT_L(0); PG8_BAR; PG8_MMA(0, 0, At, B0); PG8_MMA(0, 1, At, B1); PG8_BAR; PG8_SCHED;
;             PG8_LDA(At, 0, 1); PG8_STAGE(PG8_SB(0, 0), b2, voffB); PG8_STAGE(PG8_SB(0, 1), b2 + hstepB, voffB); PG8_STAGE(PG8_SA(0, 0), a2, voffA);
;             PG8_WAIT_V(8); PG8_WAIT_L(0); PG8_BAR; PG8_MMA(1, 0, At, B0); PG8_MMA(1, 1, At, B1); PG8_BAR; PG8_SCHED;
;             PG8_LDB(B0, 1, 0); PG8_LDB(B1, 1, 1); PG8_SCHED; PG8_LDA(At, 1, 0); PG8_STAGE(PG8_SA(0, 1), a2 + hstepA, voffA);
;             PG8_WAIT_V(8); PG8_WAIT_L(0); PG8_BAR; PG8_MMA(0, 0, At, B0); PG8_MMA(0, 1, At, B1); PG8_BAR; PG8_SCHED;
;             PG8_LDA(At, 1, 1); PG8_STAGE(PG8_SB(1, 0), b3, voffB); PG8_STAGE(PG8_SB(1, 1), b3 + hstepB, voffB); PG8_STAGE(PG8_SA(1, 0), a3, voffA);
;             PG8_WAIT_V(8); PG8_WAIT_L(0); PG8_BAR; PG8_MMA(1, 0, At, B0); PG8_MMA(1, 1, At, B1); PG8_BAR; PG8_SCHED;
;         }
	s_add_i32 s20, s8, 0x18000
	s_add_u32 s80, s76, 0x80
	s_addc_u32 s81, s77, 0
	s_mov_b32 m0, s20
	ds_read_b128 v[198:201], v148 offset:49152
	ds_read_b128 v[202:205], v148 offset:50176
	ds_read_b128 v[206:209], v148 offset:51200
	ds_read_b128 v[218:221], v148 offset:52224
	ds_read_b128 v[222:225], v148 offset:53248
	ds_read_b128 v[226:229], v148 offset:54272
	ds_read_b128 v[230:233], v148 offset:55296
	ds_read_b128 v[234:237], v148 offset:56320
	global_load_lds_dwordx4 v132, s[80:81]
	s_add_i32 m0, s20, 0x2000
	s_add_u32 s20, s76, 0x40080
	s_addc_u32 s21, s77, 0
	s_add_i32 s12, s8, 0x1c000
	global_load_lds_dwordx4 v136, s[80:81]
	s_mov_b32 m0, s12
	s_nop 0
	global_load_lds_dwordx4 v132, s[20:21]
	s_add_i32 m0, s12, 0x2000
	s_nop 0
	global_load_lds_dwordx4 v136, s[20:21]
	s_mov_b32 m0, s31
	s_nop 0
	global_load_lds_dwordx4 v130, s[100:101]
	s_mov_b32 m0, s34
	s_nop 0
	global_load_lds_dwordx4 v134, s[100:101]
	s_waitcnt vmcnt(8)
	s_waitcnt lgkmcnt(0)
	s_barrier
	s_waitcnt lgkmcnt(0)
	v_mfma_f32_16x16x32_bf16 v[62:65], v[150:153], v[198:201], v[62:65]
	v_mfma_f32_16x16x32_bf16 v[58:61], v[158:161], v[198:201], v[58:61]
	v_mfma_f32_16x16x32_bf16 v[50:53], v[150:153], v[206:209], v[50:53]
	v_mfma_f32_16x16x32_bf16 v[42:45], v[158:161], v[206:209], v[42:45]
	v_mfma_f32_16x16x32_bf16 v[30:33], v[150:153], v[222:225], v[30:33]
	v_mfma_f32_16x16x32_bf16 v[26:29], v[158:161], v[222:225], v[26:29]
	v_mfma_f32_16x16x32_bf16 v[18:21], v[150:153], v[230:233], v[18:21]
	v_mfma_f32_16x16x32_bf16 v[10:13], v[158:161], v[230:233], v[10:13]
	v_mfma_f32_16x16x32_bf16 v[62:65], v[154:157], v[202:205], v[62:65]
	v_mfma_f32_16x16x32_bf16 v[58:61], v[162:165], v[202:205], v[58:61]
	v_mfma_f32_16x16x32_bf16 v[50:53], v[154:157], v[218:221], v[50:53]
	v_mfma_f32_16x16x32_bf16 v[42:45], v[162:165], v[218:221], v[42:45]
	v_mfma_f32_16x16x32_bf16 v[30:33], v[154:157], v[226:229], v[30:33]
	v_mfma_f32_16x16x32_bf16 v[26:29], v[162:165], v[226:229], v[26:29]
	v_mfma_f32_16x16x32_bf16 v[18:21], v[154:157], v[234:237], v[18:21]
	v_mfma_f32_16x16x32_bf16 v[10:13], v[162:165], v[234:237], v[10:13]
	v_mfma_f32_16x16x32_bf16 v[54:57], v[166:169], v[198:201], v[54:57]
	v_mfma_f32_16x16x32_bf16 v[46:49], v[190:193], v[198:201], v[46:49]
	v_mfma_f32_16x16x32_bf16 v[38:41], v[166:169], v[206:209], v[38:41]
	v_mfma_f32_16x16x32_bf16 v[34:37], v[190:193], v[206:209], v[34:37]
	v_mfma_f32_16x16x32_bf16 v[22:25], v[166:169], v[222:225], v[22:25]
	v_mfma_f32_16x16x32_bf16 v[14:17], v[190:193], v[222:225], v[14:17]
	v_mfma_f32_16x16x32_bf16 v[6:9], v[166:169], v[230:233], v[6:9]
	v_mfma_f32_16x16x32_bf16 v[2:5], v[190:193], v[230:233], v[2:5]
	v_mfma_f32_16x16x32_bf16 v[54:57], v[170:173], v[202:205], v[54:57]
	v_mfma_f32_16x16x32_bf16 v[46:49], v[194:197], v[202:205], v[46:49]
	v_mfma_f32_16x16x32_bf16 v[38:41], v[170:173], v[218:221], v[38:41]
	v_mfma_f32_16x16x32_bf16 v[34:37], v[194:197], v[218:221], v[34:37]
	v_mfma_f32_16x16x32_bf16 v[22:25], v[170:173], v[226:229], v[22:25]
	v_mfma_f32_16x16x32_bf16 v[14:17], v[194:197], v[226:229], v[14:17]
	v_mfma_f32_16x16x32_bf16 v[6:9], v[170:173], v[234:237], v[6:9]
	v_mfma_f32_16x16x32_bf16 v[2:5], v[194:197], v[234:237], v[2:5]
	s_barrier
	s_add_i32 s78, s78, 2
	s_add_u32 s18, s18, 0x100
	s_addc_u32 s19, s19, 0
	s_add_u32 s69, s69, 0x100
	s_addc_u32 s71, s71, 0
	s_cmp_gt_u32 s78, 13
.LBB0_349:
	s_add_u32 s20, s18, 0xfffc0080
	s_addc_u32 s21, s19, -1
	s_add_i32 s79, 0, 0x10000
	s_cmp_eq_u32 s78, 12
	s_cselect_b32 s21, s48, s21
	s_cselect_b32 s20, s49, s20
	s_cselect_b32 s77, s53, s71
	s_cselect_b32 s76, s54, s69
	s_add_u32 s100, s20, 0x80
	s_addc_u32 s101, s21, 0
	s_add_i32 s82, 0, 0x14000
	ds_read_b128 v[150:153], v255
	ds_read_b128 v[154:157], v255 offset:1024
	ds_read_b128 v[158:161], v255 offset:2048
	ds_read_b128 v[162:165], v255 offset:3072
	ds_read_b128 v[166:169], v255 offset:16384
	ds_read_b128 v[170:173], v255 offset:17408
	ds_read_b128 v[190:193], v255 offset:18432
	ds_read_b128 v[194:197], v255 offset:19456
	s_add_i32 m0, s9, 0xc000
	ds_read_b128 v[198:201], v148
	ds_read_b128 v[202:205], v148 offset:1024
	ds_read_b128 v[206:209], v148 offset:2048
	ds_read_b128 v[218:221], v148 offset:3072
	ds_read_b128 v[222:225], v148 offset:4096
	ds_read_b128 v[226:229], v148 offset:5120
	ds_read_b128 v[230:233], v148 offset:6144
	ds_read_b128 v[234:237], v148 offset:7168
	global_load_lds_dwordx4 v130, s[18:19]
	s_add_i32 m0, s9, 0xe000
	s_nop 0
	global_load_lds_dwordx4 v134, s[18:19]
	s_waitcnt vmcnt(8)
	s_waitcnt lgkmcnt(0)
	s_barrier
; #define PG8_STAGE(bufoff, gbase, voff) do { _Pragma("unroll") for (int _i = 0; _i < 2; ++_i) \
;         __builtin_amdgcn_global_load_lds((const unsigned*)((const char*)(gbase) + (voff)[_i]), (LAS unsigned*)(lds + (bufoff) + ldsw + _i * 8192), 16, 0, 0); } while (0)
; #define PG8_LDA(dst, b, h) do { _Pragma("unroll") for (int m = 0; m < 4; ++m) _Pragma("unroll") for (int k = 0; k < 2; ++k) dst[m][k] = *(const LAS bf16x8*)(lds + PG8_SA(b, h) + aoff + m * 2048 + k * 1024); } while (0)
; #define PG8_MMA(ai, bj, At, Bt) do { __builtin_amdgcn_s_setprio(1); _Pragma("unroll") for (int m = 0; m < 4; ++m) _Pragma("unroll") for (int n = 0; n < 2; ++n) _Pragma("unroll") for (int k = 0; k < 2; ++k) \
;         acc[ai][bj][m][n] = __builtin_amdgcn_mfma_f32_16x16x32_bf16(Bt[n][k], At[m][k], acc[ai][bj][m][n], 0, 0, 0); __builtin_amdgcn_s_setprio(0); } while (0)
; #define PG8_WAIT_V(n) asm volatile("s_waitcnt vmcnt(" #n ")" ::: "memory")
; #define PG8_WAIT_L(n) asm volatile("s_waitcnt lgkmcnt(" #n ")" ::: "memory")
; #define PG8_BAR __builtin_amdgcn_s_barrier()
; #define PG8_SCHED __builtin_amdgcn_sched_barrier(0)
; template <class Epi, class Sched>
; __device__ __forceinline__ void gemm_phase(LAS unsigned char* lds, const Gemm g, const Sched& S, const Epi& E) {
;     ...
;             PG8_WAIT_V(8); PG8_WAIT_L(0); PG8_BAR; PG8_MMA(0, 0, At, B0); PG8_MMA(0, 1, At, B1); PG8_BAR; PG8_SCHED;
;             PG8_LDA(At, 0, 1); PG8_STAGE(PG8_SB(0, 0), b2, voffB); PG8_STAGE(PG8_SB(0, 1), b2 + hstepB, voffB); PG8_STAGE(PG8_SA(0, 0), a2, voffA);
;             PG8_WAIT_V(8); PG8_WAIT_L(0); PG8_BAR; PG8_MMA(1, 0, At, B0); PG8_MMA(1, 1, At, B1); PG8_BAR; PG8_SCHED;
	s_waitcnt lgkmcnt(0)
	v_mfma_f32_16x16x32_bf16 v[126:129], v[150:153], v[198:201], v[126:129]
	v_mfma_f32_16x16x32_bf16 v[122:125], v[158:161], v[198:201], v[122:125]
	v_mfma_f32_16x16x32_bf16 v[110:113], v[150:153], v[206:209], v[110:113]
	v_mfma_f32_16x16x32_bf16 v[106:109], v[158:161], v[206:209], v[106:109]
	v_mfma_f32_16x16x32_bf16 v[94:97], v[150:153], v[222:225], v[94:97]
	v_mfma_f32_16x16x32_bf16 v[90:93], v[158:161], v[222:225], v[90:93]
	v_mfma_f32_16x16x32_bf16 v[82:85], v[150:153], v[230:233], v[82:85]
	v_mfma_f32_16x16x32_bf16 v[74:77], v[158:161], v[230:233], v[74:77]
	v_mfma_f32_16x16x32_bf16 v[126:129], v[154:157], v[202:205], v[126:129]
	v_mfma_f32_16x16x32_bf16 v[122:125], v[162:165], v[202:205], v[122:125]
	v_mfma_f32_16x16x32_bf16 v[110:113], v[154:157], v[218:221], v[110:113]
	v_mfma_f32_16x16x32_bf16 v[106:109], v[162:165], v[218:221], v[106:109]
	v_mfma_f32_16x16x32_bf16 v[94:97], v[154:157], v[226:229], v[94:97]
	v_mfma_f32_16x16x32_bf16 v[90:93], v[162:165], v[226:229], v[90:93]
	v_mfma_f32_16x16x32_bf16 v[82:85], v[154:157], v[234:237], v[82:85]
	v_mfma_f32_16x16x32_bf16 v[74:77], v[162:165], v[234:237], v[74:77]
	v_mfma_f32_16x16x32_bf16 v[118:121], v[166:169], v[198:201], v[118:121]
	v_mfma_f32_16x16x32_bf16 v[114:117], v[190:193], v[198:201], v[114:117]
	v_mfma_f32_16x16x32_bf16 v[102:105], v[166:169], v[206:209], v[102:105]
	v_mfma_f32_16x16x32_bf16 v[98:101], v[190:193], v[206:209], v[98:101]
	v_mfma_f32_16x16x32_bf16 v[86:89], v[166:169], v[222:225], v[86:89]
	v_mfma_f32_16x16x32_bf16 v[78:81], v[190:193], v[222:225], v[78:81]
	v_mfma_f32_16x16x32_bf16 v[70:73], v[166:169], v[230:233], v[70:73]
	v_mfma_f32_16x16x32_bf16 v[66:69], v[190:193], v[230:233], v[66:69]
	v_mfma_f32_16x16x32_bf16 v[118:121], v[170:173], v[202:205], v[118:121]
	v_mfma_f32_16x16x32_bf16 v[114:117], v[194:197], v[202:205], v[114:117]
	v_mfma_f32_16x16x32_bf16 v[102:105], v[170:173], v[218:221], v[102:105]
	v_mfma_f32_16x16x32_bf16 v[98:101], v[194:197], v[218:221], v[98:101]
	v_mfma_f32_16x16x32_bf16 v[86:89], v[170:173], v[226:229], v[86:89]
	v_mfma_f32_16x16x32_bf16 v[78:81], v[194:197], v[226:229], v[78:81]
	v_mfma_f32_16x16x32_bf16 v[70:73], v[170:173], v[234:237], v[70:73]
	v_mfma_f32_16x16x32_bf16 v[66:69], v[194:197], v[234:237], v[66:69]
	s_barrier
	s_add_i32 s79, s79, s8
	s_mov_b32 m0, s79
	ds_read_b128 v[198:201], v148 offset:16384
	ds_read_b128 v[202:205], v148 offset:17408
	ds_read_b128 v[206:209], v148 offset:18432
	ds_read_b128 v[218:221], v148 offset:19456
	ds_read_b128 v[222:225], v148 offset:20480
	ds_read_b128 v[226:229], v148 offset:21504
	ds_read_b128 v[230:233], v148 offset:22528
	ds_read_b128 v[234:237], v148 offset:23552
	global_load_lds_dwordx4 v132, s[76:77]
	s_add_i32 m0, s79, 0x2000
	s_add_u32 s80, s76, 0x40000
	s_addc_u32 s81, s77, 0
	s_add_i32 s79, s82, s8
	global_load_lds_dwordx4 v136, s[76:77]
	s_mov_b32 m0, s79
	s_nop 0
	global_load_lds_dwordx4 v132, s[80:81]
	s_add_i32 m0, s79, 0x2000
	s_nop 0
	global_load_lds_dwordx4 v136, s[80:81]
	s_mov_b32 m0, s9
	s_nop 0
	global_load_lds_dwordx4 v130, s[20:21]
	s_mov_b32 m0, s28
	s_nop 0
	global_load_lds_dwordx4 v134, s[20:21]
	s_waitcnt vmcnt(8)
	s_waitcnt lgkmcnt(0)
	s_barrier
	s_waitcnt lgkmcnt(0)
	v_mfma_f32_16x16x32_bf16 v[62:65], v[150:153], v[198:201], v[62:65]
	v_mfma_f32_16x16x32_bf16 v[58:61], v[158:161], v[198:201], v[58:61]
	v_mfma_f32_16x16x32_bf16 v[50:53], v[150:153], v[206:209], v[50:53]
	v_mfma_f32_16x16x32_bf16 v[42:45], v[158:161], v[206:209], v[42:45]
	v_mfma_f32_16x16x32_bf16 v[30:33], v[150:153], v[222:225], v[30:33]
	v_mfma_f32_16x16x32_bf16 v[26:29], v[158:161], v[222:225], v[26:29]
	v_mfma_f32_16x16x32_bf16 v[18:21], v[150:153], v[230:233], v[18:21]
	v_mfma_f32_16x16x32_bf16 v[10:13], v[158:161], v[230:233], v[10:13]
	v_mfma_f32_16x16x32_bf16 v[62:65], v[154:157], v[202:205], v[62:65]
	v_mfma_f32_16x16x32_bf16 v[58:61], v[162:165], v[202:205], v[58:61]
	v_mfma_f32_16x16x32_bf16 v[50:53], v[154:157], v[218:221], v[50:53]
	v_mfma_f32_16x16x32_bf16 v[42:45], v[162:165], v[218:221], v[42:45]
	v_mfma_f32_16x16x32_bf16 v[30:33], v[154:157], v[226:229], v[30:33]
	v_mfma_f32_16x16x32_bf16 v[26:29], v[162:165], v[226:229], v[26:29]
	v_mfma_f32_16x16x32_bf16 v[18:21], v[154:157], v[234:237], v[18:21]
	v_mfma_f32_16x16x32_bf16 v[10:13], v[162:165], v[234:237], v[10:13]
	v_mfma_f32_16x16x32_bf16 v[54:57], v[166:169], v[198:201], v[54:57]
	v_mfma_f32_16x16x32_bf16 v[46:49], v[190:193], v[198:201], v[46:49]
	v_mfma_f32_16x16x32_bf16 v[38:41], v[166:169], v[206:209], v[38:41]
	v_mfma_f32_16x16x32_bf16 v[34:37], v[190:193], v[206:209], v[34:37]
	v_mfma_f32_16x16x32_bf16 v[22:25], v[166:169], v[222:225], v[22:25]
	v_mfma_f32_16x16x32_bf16 v[14:17], v[190:193], v[222:225], v[14:17]
	v_mfma_f32_16x16x32_bf16 v[6:9], v[166:169], v[230:233], v[6:9]
	v_mfma_f32_16x16x32_bf16 v[2:5], v[190:193], v[230:233], v[2:5]
	v_mfma_f32_16x16x32_bf16 v[54:57], v[170:173], v[202:205], v[54:57]
	v_mfma_f32_16x16x32_bf16 v[46:49], v[194:197], v[202:205], v[46:49]
	v_mfma_f32_16x16x32_bf16 v[38:41], v[170:173], v[218:221], v[38:41]
	v_mfma_f32_16x16x32_bf16 v[34:37], v[194:197], v[218:221], v[34:37]
	v_mfma_f32_16x16x32_bf16 v[22:25], v[170:173], v[226:229], v[22:25]
	v_mfma_f32_16x16x32_bf16 v[14:17], v[194:197], v[226:229], v[14:17]
	v_mfma_f32_16x16x32_bf16 v[6:9], v[170:173], v[234:237], v[6:9]
	v_mfma_f32_16x16x32_bf16 v[2:5], v[194:197], v[234:237], v[2:5]
	s_barrier
; #define PG8_STAGE(bufoff, gbase, voff) do { _Pragma("unroll") for (int _i = 0; _i < 2; ++_i) \
;         __builtin_amdgcn_global_load_lds((const unsigned*)((const char*)(gbase) + (voff)[_i]), (LAS unsigned*)(lds + (bufoff) + ldsw + _i * 8192), 16, 0, 0); } while (0)
; #define PG8_LDA(dst, b, h) do { _Pragma("unroll") for (int m = 0; m < 4; ++m) _Pragma("unroll") for (int k = 0; k < 2; ++k) dst[m][k] = *(const LAS bf16x8*)(lds + PG8_SA(b, h) + aoff + m * 2048 + k * 1024); } while (0)
; #define PG8_LDB(dst, b, h) do { _Pragma("unroll") for (int n = 0; n < 2; ++n) _Pragma("unroll") for (int k = 0; k < 2; ++k) dst[n][k] = *(const LAS bf16x8*)(lds + PG8_SB(b, h) + boff + n * 2048 + k * 1024); } while (0)
; #define PG8_MMA(ai, bj, At, Bt) do { __builtin_amdgcn_s_setprio(1); _Pragma("unroll") for (int m = 0; m < 4; ++m) _Pragma("unroll") for (int n = 0; n < 2; ++n) _Pragma("unroll") for (int k = 0; k < 2; ++k) \
;         acc[ai][bj][m][n] = __builtin_amdgcn_mfma_f32_16x16x32_bf16(Bt[n][k], At[m][k], acc[ai][bj][m][n], 0, 0, 0); __builtin_amdgcn_s_setprio(0); } while (0)
; #define PG8_WAIT_V(n) asm volatile("s_waitcnt vmcnt(" #n ")" ::: "memory")
; #define PG8_WAIT_L(n) asm volatile("s_waitcnt lgkmcnt(" #n ")" ::: "memory")
; #define PG8_BAR __builtin_amdgcn_s_barrier()
; #define PG8_SCHED __builtin_amdgcn_sched_barrier(0)
; template <class Epi, class Sched>
; __device__ __forceinline__ void gemm_phase(LAS unsigned char* lds, const Gemm g, const Sched& S, const Epi& E) {
;     ...
;             PG8_LDB(B0, 1, 0); PG8_LDB(B1, 1, 1); PG8_SCHED; PG8_LDA(At, 1, 0); PG8_STAGE(PG8_SA(0, 1), a2 + hstepA, voffA);
;             PG8_WAIT_V(8); PG8_WAIT_L(0); PG8_BAR; PG8_MMA(0, 0, At, B0); PG8_MMA(0, 1, At, B1); PG8_BAR; PG8_SCHED;
;             PG8_LDA(At, 1, 1); PG8_STAGE(PG8_SB(1, 0), b3, voffB); PG8_STAGE(PG8_SB(1, 1), b3 + hstepB, voffB); PG8_STAGE(PG8_SA(1, 0), a3, voffA);
;             PG8_WAIT_V(8); PG8_WAIT_L(0); PG8_BAR; PG8_MMA(1, 0, At, B0); PG8_MMA(1, 1, At, B1); PG8_BAR; PG8_SCHED;
;         }
;         if (wr == 0) PG8_BAR;
	s_add_i32 s79, 0, 0x18000
	s_add_i32 s80, 0, 0x1c000
	ds_read_b128 v[150:153], v255 offset:32768
	ds_read_b128 v[154:157], v255 offset:33792
	ds_read_b128 v[158:161], v255 offset:34816
	ds_read_b128 v[162:165], v255 offset:35840
	ds_read_b128 v[166:169], v255 offset:49152
	ds_read_b128 v[170:173], v255 offset:50176
	ds_read_b128 v[190:193], v255 offset:51200
	ds_read_b128 v[194:197], v255 offset:52224
	s_add_u32 s20, s20, 0x40000
	s_addc_u32 s21, s21, 0
	s_mov_b32 m0, s29
	ds_read_b128 v[198:201], v148 offset:32768
	ds_read_b128 v[202:205], v148 offset:33792
	ds_read_b128 v[206:209], v148 offset:34816
	ds_read_b128 v[218:221], v148 offset:35840
	ds_read_b128 v[222:225], v148 offset:36864
	ds_read_b128 v[226:229], v148 offset:37888
	ds_read_b128 v[230:233], v148 offset:38912
	ds_read_b128 v[234:237], v148 offset:39936
	global_load_lds_dwordx4 v130, s[20:21]
	s_mov_b32 m0, s30
	s_nop 0
	global_load_lds_dwordx4 v134, s[20:21]
	s_waitcnt vmcnt(8)
	s_waitcnt lgkmcnt(0)
	s_barrier
	s_waitcnt lgkmcnt(0)
	v_mfma_f32_16x16x32_bf16 v[126:129], v[150:153], v[198:201], v[126:129]
	v_mfma_f32_16x16x32_bf16 v[122:125], v[158:161], v[198:201], v[122:125]
	v_mfma_f32_16x16x32_bf16 v[110:113], v[150:153], v[206:209], v[110:113]
	v_mfma_f32_16x16x32_bf16 v[106:109], v[158:161], v[206:209], v[106:109]
	v_mfma_f32_16x16x32_bf16 v[94:97], v[150:153], v[222:225], v[94:97]
	v_mfma_f32_16x16x32_bf16 v[90:93], v[158:161], v[222:225], v[90:93]
	v_mfma_f32_16x16x32_bf16 v[82:85], v[150:153], v[230:233], v[82:85]
	v_mfma_f32_16x16x32_bf16 v[74:77], v[158:161], v[230:233], v[74:77]
	v_mfma_f32_16x16x32_bf16 v[126:129], v[154:157], v[202:205], v[126:129]
	v_mfma_f32_16x16x32_bf16 v[122:125], v[162:165], v[202:205], v[122:125]
	v_mfma_f32_16x16x32_bf16 v[110:113], v[154:157], v[218:221], v[110:113]
	v_mfma_f32_16x16x32_bf16 v[106:109], v[162:165], v[218:221], v[106:109]
	v_mfma_f32_16x16x32_bf16 v[94:97], v[154:157], v[226:229], v[94:97]
	v_mfma_f32_16x16x32_bf16 v[90:93], v[162:165], v[226:229], v[90:93]
	v_mfma_f32_16x16x32_bf16 v[82:85], v[154:157], v[234:237], v[82:85]
	v_mfma_f32_16x16x32_bf16 v[74:77], v[162:165], v[234:237], v[74:77]
	v_mfma_f32_16x16x32_bf16 v[118:121], v[166:169], v[198:201], v[118:121]
	v_mfma_f32_16x16x32_bf16 v[114:117], v[190:193], v[198:201], v[114:117]
	v_mfma_f32_16x16x32_bf16 v[102:105], v[166:169], v[206:209], v[102:105]
	v_mfma_f32_16x16x32_bf16 v[98:101], v[190:193], v[206:209], v[98:101]
	v_mfma_f32_16x16x32_bf16 v[86:89], v[166:169], v[222:225], v[86:89]
	v_mfma_f32_16x16x32_bf16 v[78:81], v[190:193], v[222:225], v[78:81]
	v_mfma_f32_16x16x32_bf16 v[70:73], v[166:169], v[230:233], v[70:73]
	v_mfma_f32_16x16x32_bf16 v[66:69], v[190:193], v[230:233], v[66:69]
	v_mfma_f32_16x16x32_bf16 v[118:121], v[170:173], v[202:205], v[118:121]
	v_mfma_f32_16x16x32_bf16 v[114:117], v[194:197], v[202:205], v[114:117]
	v_mfma_f32_16x16x32_bf16 v[102:105], v[170:173], v[218:221], v[102:105]
	v_mfma_f32_16x16x32_bf16 v[98:101], v[194:197], v[218:221], v[98:101]
	v_mfma_f32_16x16x32_bf16 v[86:89], v[170:173], v[226:229], v[86:89]
	v_mfma_f32_16x16x32_bf16 v[78:81], v[194:197], v[226:229], v[78:81]
	v_mfma_f32_16x16x32_bf16 v[70:73], v[170:173], v[234:237], v[70:73]
	v_mfma_f32_16x16x32_bf16 v[66:69], v[194:197], v[234:237], v[66:69]
	s_barrier
	s_add_i32 s20, s8, 0x18000
	s_add_u32 s80, s76, 0x80
	s_addc_u32 s81, s77, 0
	s_mov_b32 m0, s20
	ds_read_b128 v[198:201], v148 offset:49152
	ds_read_b128 v[202:205], v148 offset:50176
	ds_read_b128 v[206:209], v148 offset:51200
	ds_read_b128 v[218:221], v148 offset:52224
	ds_read_b128 v[222:225], v148 offset:53248
	ds_read_b128 v[226:229], v148 offset:54272
	ds_read_b128 v[230:233], v148 offset:55296
	ds_read_b128 v[234:237], v148 offset:56320
	global_load_lds_dwordx4 v132, s[80:81]
	s_add_i32 m0, s20, 0x2000
	s_add_u32 s20, s76, 0x40080
	s_addc_u32 s21, s77, 0
	s_add_i32 s12, s8, 0x1c000
	global_load_lds_dwordx4 v136, s[80:81]
	s_mov_b32 m0, s12
	s_nop 0
	global_load_lds_dwordx4 v132, s[20:21]
	s_add_i32 m0, s12, 0x2000
	s_nop 0
	global_load_lds_dwordx4 v136, s[20:21]
	s_mov_b32 m0, s31
	s_nop 0
	global_load_lds_dwordx4 v130, s[100:101]
	s_mov_b32 m0, s34
	s_nop 0
	global_load_lds_dwordx4 v134, s[100:101]
	s_waitcnt vmcnt(8)
	s_waitcnt lgkmcnt(0)
	s_barrier
	s_waitcnt lgkmcnt(0)
	v_mfma_f32_16x16x32_bf16 v[62:65], v[150:153], v[198:201], v[62:65]
	v_mfma_f32_16x16x32_bf16 v[58:61], v[158:161], v[198:201], v[58:61]
	v_mfma_f32_16x16x32_bf16 v[50:53], v[150:153], v[206:209], v[50:53]
	v_mfma_f32_16x16x32_bf16 v[42:45], v[158:161], v[206:209], v[42:45]
	v_mfma_f32_16x16x32_bf16 v[30:33], v[150:153], v[222:225], v[30:33]
	v_mfma_f32_16x16x32_bf16 v[26:29], v[158:161], v[222:225], v[26:29]
	v_mfma_f32_16x16x32_bf16 v[18:21], v[150:153], v[230:233], v[18:21]
	v_mfma_f32_16x16x32_bf16 v[10:13], v[158:161], v[230:233], v[10:13]
	v_mfma_f32_16x16x32_bf16 v[62:65], v[154:157], v[202:205], v[62:65]
	v_mfma_f32_16x16x32_bf16 v[58:61], v[162:165], v[202:205], v[58:61]
	v_mfma_f32_16x16x32_bf16 v[50:53], v[154:157], v[218:221], v[50:53]
	v_mfma_f32_16x16x32_bf16 v[42:45], v[162:165], v[218:221], v[42:45]
	v_mfma_f32_16x16x32_bf16 v[30:33], v[154:157], v[226:229], v[30:33]
	v_mfma_f32_16x16x32_bf16 v[26:29], v[162:165], v[226:229], v[26:29]
	v_mfma_f32_16x16x32_bf16 v[18:21], v[154:157], v[234:237], v[18:21]
	v_mfma_f32_16x16x32_bf16 v[10:13], v[162:165], v[234:237], v[10:13]
	v_mfma_f32_16x16x32_bf16 v[54:57], v[166:169], v[198:201], v[54:57]
	v_mfma_f32_16x16x32_bf16 v[46:49], v[190:193], v[198:201], v[46:49]
	v_mfma_f32_16x16x32_bf16 v[38:41], v[166:169], v[206:209], v[38:41]
	v_mfma_f32_16x16x32_bf16 v[34:37], v[190:193], v[206:209], v[34:37]
	v_mfma_f32_16x16x32_bf16 v[22:25], v[166:169], v[222:225], v[22:25]
	v_mfma_f32_16x16x32_bf16 v[14:17], v[190:193], v[222:225], v[14:17]
	v_mfma_f32_16x16x32_bf16 v[6:9], v[166:169], v[230:233], v[6:9]
	v_mfma_f32_16x16x32_bf16 v[2:5], v[190:193], v[230:233], v[2:5]
	v_mfma_f32_16x16x32_bf16 v[54:57], v[170:173], v[202:205], v[54:57]
	v_mfma_f32_16x16x32_bf16 v[46:49], v[194:197], v[202:205], v[46:49]
	v_mfma_f32_16x16x32_bf16 v[38:41], v[170:173], v[218:221], v[38:41]
	v_mfma_f32_16x16x32_bf16 v[34:37], v[194:197], v[218:221], v[34:37]
	v_mfma_f32_16x16x32_bf16 v[22:25], v[170:173], v[226:229], v[22:25]
	v_mfma_f32_16x16x32_bf16 v[14:17], v[194:197], v[226:229], v[14:17]
	v_mfma_f32_16x16x32_bf16 v[6:9], v[170:173], v[234:237], v[6:9]
	v_mfma_f32_16x16x32_bf16 v[2:5], v[194:197], v[234:237], v[2:5]
	s_barrier
	s_add_i32 s78, s78, 2
	s_add_u32 s18, s18, 0x100
	s_addc_u32 s19, s19, 0
	s_add_u32 s69, s69, 0x100
	s_addc_u32 s71, s71, 0
	s_cmp_gt_u32 s78, 13
	s_cbranch_scc0 .LBB0_349
	s_and_b64 vcc, exec, s[36:37]
	s_cbranch_vccz .LBB0_352
	s_barrier

; #define PG8_STAGE(bufoff, gbase, voff) do { _Pragma("unroll") for (int _i = 0; _i < 2; ++_i) \
;         __builtin_amdgcn_global_load_lds((const unsigned*)((const char*)(gbase) + (voff)[_i]), (LAS unsigned*)(lds + (bufoff) + ldsw + _i * 8192), 16, 0, 0); } while (0)
; #define PG8_LDA(dst, b, h) do { _Pragma("unroll") for (int m = 0; m < 4; ++m) _Pragma("unroll") for (int k = 0; k < 2; ++k) dst[m][k] = *(const LAS bf16x8*)(lds + PG8_SA(b, h) + aoff + m * 2048 + k * 1024); } while (0)
; #define PG8_LDB(dst, b, h) do { _Pragma("unroll") for (int n = 0; n < 2; ++n) _Pragma("unroll") for (int k = 0; k < 2; ++k) dst[n][k] = *(const LAS bf16x8*)(lds + PG8_SB(b, h) + boff + n * 2048 + k * 1024); } while (0)
; #define PG8_MMA(ai, bj, At, Bt) do { __builtin_amdgcn_s_setprio(1); _Pragma("unroll") for (int m = 0; m < 4; ++m) _Pragma("unroll") for (int n = 0; n < 2; ++n) _Pragma("unroll") for (int k = 0; k < 2; ++k) \
;         acc[ai][bj][m][n] = __builtin_amdgcn_mfma_f32_16x16x32_bf16(Bt[n][k], At[m][k], acc[ai][bj][m][n], 0, 0, 0); __builtin_amdgcn_s_setprio(0); } while (0)
; #define PG8_WAIT_V(n) asm volatile("s_waitcnt vmcnt(" #n ")" ::: "memory")
; #define PG8_WAIT_L(n) asm volatile("s_waitcnt lgkmcnt(" #n ")" ::: "memory")
; template <class Epi, class Sched>
; __device__ __forceinline__ void gemm_phase(LAS unsigned char* lds, const Gemm g, const Sched& S, const Epi& E) {
;     ...
;         const bool has_next = S.next(ui + 1, nxt);
;         const char* nA = has_next ? (const char*)g.A + (size_t)nxt.pm * tstepA + (size_t)nxt.pn * g.a_pn_off * 2 : cA; const char* nB = has_next ? (const char*)g.Bt + (size_t)nxt.pn * tstepB : cB;
;         for (int t = 0; t < nt; t += 2) {
;             const bool last = (t == nt - 2);
;             const char* a1 = cA + (size_t)(t + 1) * kstep;
;             const char* a2 = last ? nA : cA + (size_t)(t + 2) * kstep; const char* b2 = last ? nB : cB + (size_t)(t + 2) * kstep;
;             const char* a3 = a2 + kstep; const char* b3 = b2 + kstep;
;             PG8_LDB(B0, 0, 0); PG8_LDB(B1, 0, 1); PG8_SCHED; PG8_LDA(At, 0, 0); PG8_STAGE(PG8_SA(1, 1), a1 + hstepA, voffA);
;             PG8_WAIT_V(8); PG8_WAIT_L(0); PG8_BAR; PG8_MMA(0, 0, At, B0); PG8_MMA(0, 1, At, B1); PG8_BAR; PG8_SCHED;
;             PG8_LDA(At, 0, 1); PG8_STAGE(PG8_SB(0, 0), b2, voffB); PG8_STAGE(PG8_SB(0, 1), b2 + hstepB, voffB); PG8_STAGE(PG8_SA(0, 0), a2, voffA);
.LBB0_377:
	s_ashr_i32 s71, s70, 31
	s_lshl_b64 s[48:49], s[70:71], 19
	v_readlane_b32 s12, v248, 21
	s_add_u32 s72, s12, s48
	v_readlane_b32 s12, v248, 22
	s_addc_u32 s73, s12, s49
	s_and_b64 s[48:49], s[66:67], exec
	s_cselect_b32 s43, s73, s19
	s_cselect_b32 s48, s72, s18
	s_ashr_i32 s69, s68, 31
	s_lshl_b64 s[74:75], s[68:69], 19
	s_add_u32 s74, s4, s74
	s_addc_u32 s75, s5, s75
	s_and_b64 s[76:77], s[66:67], exec
	s_cselect_b32 s49, s75, s21
	s_cselect_b32 s53, s74, s20
	s_add_u32 s18, s18, 0x40080
	s_addc_u32 s19, s19, 0
	s_add_u32 s69, s20, 0x100
	s_addc_u32 s71, s21, 0
	s_mov_b32 s78, -2
	v_add_u32_e32 v255, 0x10000, v158
	s_add_u32 s20, s18, 0xfffc0080
	s_addc_u32 s21, s19, -1
	s_add_i32 s79, 0, 0x10000
	s_cmp_eq_u32 s78, 12
	s_cselect_b32 s21, s43, s21
	s_cselect_b32 s20, s48, s20
	s_cselect_b32 s77, s49, s71
	s_cselect_b32 s76, s53, s69
	s_add_u32 s100, s20, 0x80
	s_addc_u32 s101, s21, 0
	s_add_i32 s82, 0, 0x14000
	ds_read_b128 v[130:133], v255
	ds_read_b128 v[134:137], v255 offset:1024
	ds_read_b128 v[138:141], v255 offset:2048
	ds_read_b128 v[142:145], v255 offset:3072
	ds_read_b128 v[162:165], v255 offset:16384
	ds_read_b128 v[166:169], v255 offset:17408
	ds_read_b128 v[170:173], v255 offset:18432
	ds_read_b128 v[190:193], v255 offset:19456
	s_add_i32 m0, s9, 0xc000
	ds_read_b128 v[194:197], v160
	ds_read_b128 v[198:201], v160 offset:1024
	ds_read_b128 v[202:205], v160 offset:2048
	ds_read_b128 v[206:209], v160 offset:3072
	ds_read_b128 v[218:221], v160 offset:4096
	ds_read_b128 v[222:225], v160 offset:5120
	ds_read_b128 v[226:229], v160 offset:6144
	ds_read_b128 v[230:233], v160 offset:7168
	global_load_lds_dwordx4 v146, s[18:19]
	s_add_i32 m0, s9, 0xe000
	s_nop 0
	global_load_lds_dwordx4 v150, s[18:19]
	s_waitcnt vmcnt(8)
	s_waitcnt lgkmcnt(0)
	s_barrier
	s_waitcnt lgkmcnt(0)
	v_mfma_f32_16x16x32_bf16 v[126:129], v[130:133], v[194:197], 0
	v_mfma_f32_16x16x32_bf16 v[122:125], v[138:141], v[194:197], 0
	v_mfma_f32_16x16x32_bf16 v[118:121], v[130:133], v[202:205], 0
	v_mfma_f32_16x16x32_bf16 v[110:113], v[138:141], v[202:205], 0
	v_mfma_f32_16x16x32_bf16 v[102:105], v[130:133], v[218:221], 0
	v_mfma_f32_16x16x32_bf16 v[94:97], v[138:141], v[218:221], 0
	v_mfma_f32_16x16x32_bf16 v[86:89], v[130:133], v[226:229], 0
	v_mfma_f32_16x16x32_bf16 v[78:81], v[138:141], v[226:229], 0
	v_mfma_f32_16x16x32_bf16 v[126:129], v[134:137], v[198:201], v[126:129]
	v_mfma_f32_16x16x32_bf16 v[122:125], v[142:145], v[198:201], v[122:125]
	v_mfma_f32_16x16x32_bf16 v[118:121], v[134:137], v[206:209], v[118:121]
	v_mfma_f32_16x16x32_bf16 v[110:113], v[142:145], v[206:209], v[110:113]
	v_mfma_f32_16x16x32_bf16 v[102:105], v[134:137], v[222:225], v[102:105]
	v_mfma_f32_16x16x32_bf16 v[94:97], v[142:145], v[222:225], v[94:97]
	v_mfma_f32_16x16x32_bf16 v[86:89], v[134:137], v[230:233], v[86:89]
	v_mfma_f32_16x16x32_bf16 v[78:81], v[142:145], v[230:233], v[78:81]
	v_mfma_f32_16x16x32_bf16 v[114:117], v[162:165], v[194:197], 0
	v_mfma_f32_16x16x32_bf16 v[106:109], v[170:173], v[194:197], 0
	v_mfma_f32_16x16x32_bf16 v[98:101], v[162:165], v[202:205], 0
	v_mfma_f32_16x16x32_bf16 v[90:93], v[170:173], v[202:205], 0
	v_mfma_f32_16x16x32_bf16 v[82:85], v[162:165], v[218:221], 0
	v_mfma_f32_16x16x32_bf16 v[74:77], v[170:173], v[218:221], 0
	v_mfma_f32_16x16x32_bf16 v[70:73], v[162:165], v[226:229], 0
	v_mfma_f32_16x16x32_bf16 v[66:69], v[170:173], v[226:229], 0
	v_mfma_f32_16x16x32_bf16 v[114:117], v[166:169], v[198:201], v[114:117]
	v_mfma_f32_16x16x32_bf16 v[106:109], v[190:193], v[198:201], v[106:109]
	v_mfma_f32_16x16x32_bf16 v[98:101], v[166:169], v[206:209], v[98:101]
	v_mfma_f32_16x16x32_bf16 v[90:93], v[190:193], v[206:209], v[90:93]
	v_mfma_f32_16x16x32_bf16 v[82:85], v[166:169], v[222:225], v[82:85]
	v_mfma_f32_16x16x32_bf16 v[74:77], v[190:193], v[222:225], v[74:77]
	v_mfma_f32_16x16x32_bf16 v[70:73], v[166:169], v[230:233], v[70:73]
	v_mfma_f32_16x16x32_bf16 v[66:69], v[190:193], v[230:233], v[66:69]
	s_barrier
	s_add_i32 s79, s79, s8
	s_mov_b32 m0, s79
	ds_read_b128 v[194:197], v160 offset:16384
	ds_read_b128 v[198:201], v160 offset:17408
	ds_read_b128 v[202:205], v160 offset:18432
	ds_read_b128 v[206:209], v160 offset:19456
	ds_read_b128 v[218:221], v160 offset:20480
	ds_read_b128 v[222:225], v160 offset:21504
	ds_read_b128 v[226:229], v160 offset:22528
	ds_read_b128 v[230:233], v160 offset:23552
	global_load_lds_dwordx4 v148, s[76:77]
	s_add_i32 m0, s79, 0x2000
	s_add_u32 s80, s76, 0x40000
	s_addc_u32 s81, s77, 0
	s_add_i32 s79, s82, s8
	global_load_lds_dwordx4 v152, s[76:77]
	s_mov_b32 m0, s79
	s_nop 0
	global_load_lds_dwordx4 v148, s[80:81]
	s_add_i32 m0, s79, 0x2000
	s_nop 0
	global_load_lds_dwordx4 v152, s[80:81]
	s_mov_b32 m0, s9
	s_nop 0
	global_load_lds_dwordx4 v146, s[20:21]
	s_mov_b32 m0, s28
	s_nop 0
	global_load_lds_dwordx4 v150, s[20:21]
	s_waitcnt vmcnt(8)
	s_waitcnt lgkmcnt(0)
	s_barrier
; #define PG8_STAGE(bufoff, gbase, voff) do { _Pragma("unroll") for (int _i = 0; _i < 2; ++_i) \
;         __builtin_amdgcn_global_load_lds((const unsigned*)((const char*)(gbase) + (voff)[_i]), (LAS unsigned*)(lds + (bufoff) + ldsw + _i * 8192), 16, 0, 0); } while (0)
; #define PG8_LDA(dst, b, h) do { _Pragma("unroll") for (int m = 0; m < 4; ++m) _Pragma("unroll") for (int k = 0; k < 2; ++k) dst[m][k] = *(const LAS bf16x8*)(lds + PG8_SA(b, h) + aoff + m * 2048 + k * 1024); } while (0)
; #define PG8_LDB(dst, b, h) do { _Pragma("unroll") for (int n = 0; n < 2; ++n) _Pragma("unroll") for (int k = 0; k < 2; ++k) dst[n][k] = *(const LAS bf16x8*)(lds + PG8_SB(b, h) + boff + n * 2048 + k * 1024); } while (0)
; #define PG8_MMA(ai, bj, At, Bt) do { __builtin_amdgcn_s_setprio(1); _Pragma("unroll") for (int m = 0; m < 4; ++m) _Pragma("unroll") for (int n = 0; n < 2; ++n) _Pragma("unroll") for (int k = 0; k < 2; ++k) \
;         acc[ai][bj][m][n] = __builtin_amdgcn_mfma_f32_16x16x32_bf16(Bt[n][k], At[m][k], acc[ai][bj][m][n], 0, 0, 0); __builtin_amdgcn_s_setprio(0); } while (0)
; #define PG8_WAIT_V(n) asm volatile("s_waitcnt vmcnt(" #n ")" ::: "memory")
; #define PG8_WAIT_L(n) asm volatile("s_waitcnt lgkmcnt(" #n ")" ::: "memory")
; #define PG8_BAR __builtin_amdgcn_s_barrier()
; #define PG8_SCHED __builtin_amdgcn_sched_barrier(0)
; template <class Epi, class Sched>
; __device__ __forceinline__ void gemm_phase(LAS unsigned char* lds, const Gemm g, const Sched& S, const Epi& E) {
;     ...
;             PG8_WAIT_V(8); PG8_WAIT_L(0); PG8_BAR; PG8_MMA(1, 0, At, B0); PG8_MMA(1, 1, At, B1); PG8_BAR; PG8_SCHED;
;             PG8_LDB(B0, 1, 0); PG8_LDB(B1, 1, 1); PG8_SCHED; PG8_LDA(At, 1, 0); PG8_STAGE(PG8_SA(0, 1), a2 + hstepA, voffA);
;             PG8_WAIT_V(8); PG8_WAIT_L(0); PG8_BAR; PG8_MMA(0, 0, At, B0); PG8_MMA(0, 1, At, B1); PG8_BAR; PG8_SCHED;
	s_waitcnt lgkmcnt(0)
	v_mfma_f32_16x16x32_bf16 v[62:65], v[130:133], v[194:197], 0
	v_mfma_f32_16x16x32_bf16 v[58:61], v[138:141], v[194:197], 0
	v_mfma_f32_16x16x32_bf16 v[54:57], v[130:133], v[202:205], 0
	v_mfma_f32_16x16x32_bf16 v[46:49], v[138:141], v[202:205], 0
	v_mfma_f32_16x16x32_bf16 v[38:41], v[130:133], v[218:221], 0
	v_mfma_f32_16x16x32_bf16 v[30:33], v[138:141], v[218:221], 0
	v_mfma_f32_16x16x32_bf16 v[22:25], v[130:133], v[226:229], 0
	v_mfma_f32_16x16x32_bf16 v[14:17], v[138:141], v[226:229], 0
	v_mfma_f32_16x16x32_bf16 v[62:65], v[134:137], v[198:201], v[62:65]
	v_mfma_f32_16x16x32_bf16 v[58:61], v[142:145], v[198:201], v[58:61]
	v_mfma_f32_16x16x32_bf16 v[54:57], v[134:137], v[206:209], v[54:57]
	v_mfma_f32_16x16x32_bf16 v[46:49], v[142:145], v[206:209], v[46:49]
	v_mfma_f32_16x16x32_bf16 v[38:41], v[134:137], v[222:225], v[38:41]
	v_mfma_f32_16x16x32_bf16 v[30:33], v[142:145], v[222:225], v[30:33]
	v_mfma_f32_16x16x32_bf16 v[22:25], v[134:137], v[230:233], v[22:25]
	v_mfma_f32_16x16x32_bf16 v[14:17], v[142:145], v[230:233], v[14:17]
	v_mfma_f32_16x16x32_bf16 v[50:53], v[162:165], v[194:197], 0
	v_mfma_f32_16x16x32_bf16 v[42:45], v[170:173], v[194:197], 0
	v_mfma_f32_16x16x32_bf16 v[34:37], v[162:165], v[202:205], 0
	v_mfma_f32_16x16x32_bf16 v[26:29], v[170:173], v[202:205], 0
	v_mfma_f32_16x16x32_bf16 v[18:21], v[162:165], v[218:221], 0
	v_mfma_f32_16x16x32_bf16 v[10:13], v[170:173], v[218:221], 0
	v_mfma_f32_16x16x32_bf16 v[6:9], v[162:165], v[226:229], 0
	v_mfma_f32_16x16x32_bf16 v[2:5], v[170:173], v[226:229], 0
	v_mfma_f32_16x16x32_bf16 v[50:53], v[166:169], v[198:201], v[50:53]
	v_mfma_f32_16x16x32_bf16 v[42:45], v[190:193], v[198:201], v[42:45]
	v_mfma_f32_16x16x32_bf16 v[34:37], v[166:169], v[206:209], v[34:37]
	v_mfma_f32_16x16x32_bf16 v[26:29], v[190:193], v[206:209], v[26:29]
	v_mfma_f32_16x16x32_bf16 v[18:21], v[166:169], v[222:225], v[18:21]
	v_mfma_f32_16x16x32_bf16 v[10:13], v[190:193], v[222:225], v[10:13]
	v_mfma_f32_16x16x32_bf16 v[6:9], v[166:169], v[230:233], v[6:9]
	v_mfma_f32_16x16x32_bf16 v[2:5], v[190:193], v[230:233], v[2:5]
	s_barrier
	s_add_i32 s79, 0, 0x18000
	s_add_i32 s80, 0, 0x1c000
	ds_read_b128 v[130:133], v255 offset:32768
	ds_read_b128 v[134:137], v255 offset:33792
	ds_read_b128 v[138:141], v255 offset:34816
	ds_read_b128 v[142:145], v255 offset:35840
	ds_read_b128 v[162:165], v255 offset:49152
	ds_read_b128 v[166:169], v255 offset:50176
	ds_read_b128 v[170:173], v255 offset:51200
	ds_read_b128 v[190:193], v255 offset:52224
	s_add_u32 s20, s20, 0x40000
	s_addc_u32 s21, s21, 0
	s_mov_b32 m0, s29
	ds_read_b128 v[194:197], v160 offset:32768
	ds_read_b128 v[198:201], v160 offset:33792
	ds_read_b128 v[202:205], v160 offset:34816
	ds_read_b128 v[206:209], v160 offset:35840
	ds_read_b128 v[218:221], v160 offset:36864
	ds_read_b128 v[222:225], v160 offset:37888
	ds_read_b128 v[226:229], v160 offset:38912
	ds_read_b128 v[230:233], v160 offset:39936
	global_load_lds_dwordx4 v146, s[20:21]
	s_mov_b32 m0, s30
	s_nop 0
	global_load_lds_dwordx4 v150, s[20:21]
	s_waitcnt vmcnt(8)
	s_waitcnt lgkmcnt(0)
	s_barrier
	s_waitcnt lgkmcnt(0)
	v_mfma_f32_16x16x32_bf16 v[126:129], v[130:133], v[194:197], v[126:129]
	v_mfma_f32_16x16x32_bf16 v[122:125], v[138:141], v[194:197], v[122:125]
	v_mfma_f32_16x16x32_bf16 v[118:121], v[130:133], v[202:205], v[118:121]
	v_mfma_f32_16x16x32_bf16 v[110:113], v[138:141], v[202:205], v[110:113]
	v_mfma_f32_16x16x32_bf16 v[102:105], v[130:133], v[218:221], v[102:105]
	v_mfma_f32_16x16x32_bf16 v[94:97], v[138:141], v[218:221], v[94:97]
	v_mfma_f32_16x16x32_bf16 v[86:89], v[130:133], v[226:229], v[86:89]
	v_mfma_f32_16x16x32_bf16 v[78:81], v[138:141], v[226:229], v[78:81]
	v_mfma_f32_16x16x32_bf16 v[126:129], v[134:137], v[198:201], v[126:129]
	v_mfma_f32_16x16x32_bf16 v[122:125], v[142:145], v[198:201], v[122:125]
	v_mfma_f32_16x16x32_bf16 v[118:121], v[134:137], v[206:209], v[118:121]
	v_mfma_f32_16x16x32_bf16 v[110:113], v[142:145], v[206:209], v[110:113]
	v_mfma_f32_16x16x32_bf16 v[102:105], v[134:137], v[222:225], v[102:105]
	v_mfma_f32_16x16x32_bf16 v[94:97], v[142:145], v[222:225], v[94:97]
	v_mfma_f32_16x16x32_bf16 v[86:89], v[134:137], v[230:233], v[86:89]
	v_mfma_f32_16x16x32_bf16 v[78:81], v[142:145], v[230:233], v[78:81]
	v_mfma_f32_16x16x32_bf16 v[114:117], v[162:165], v[194:197], v[114:117]
	v_mfma_f32_16x16x32_bf16 v[106:109], v[170:173], v[194:197], v[106:109]
	v_mfma_f32_16x16x32_bf16 v[98:101], v[162:165], v[202:205], v[98:101]
	v_mfma_f32_16x16x32_bf16 v[90:93], v[170:173], v[202:205], v[90:93]
	v_mfma_f32_16x16x32_bf16 v[82:85], v[162:165], v[218:221], v[82:85]
	v_mfma_f32_16x16x32_bf16 v[74:77], v[170:173], v[218:221], v[74:77]
	v_mfma_f32_16x16x32_bf16 v[70:73], v[162:165], v[226:229], v[70:73]
	v_mfma_f32_16x16x32_bf16 v[66:69], v[170:173], v[226:229], v[66:69]
	v_mfma_f32_16x16x32_bf16 v[114:117], v[166:169], v[198:201], v[114:117]
	v_mfma_f32_16x16x32_bf16 v[106:109], v[190:193], v[198:201], v[106:109]
	v_mfma_f32_16x16x32_bf16 v[98:101], v[166:169], v[206:209], v[98:101]
	v_mfma_f32_16x16x32_bf16 v[90:93], v[190:193], v[206:209], v[90:93]
	v_mfma_f32_16x16x32_bf16 v[82:85], v[166:169], v[222:225], v[82:85]
	v_mfma_f32_16x16x32_bf16 v[74:77], v[190:193], v[222:225], v[74:77]
	v_mfma_f32_16x16x32_bf16 v[70:73], v[166:169], v[230:233], v[70:73]
	v_mfma_f32_16x16x32_bf16 v[66:69], v[190:193], v[230:233], v[66:69]
	s_barrier
; #define PG8_STAGE(bufoff, gbase, voff) do { _Pragma("unroll") for (int _i = 0; _i < 2; ++_i) \
;         __builtin_amdgcn_global_load_lds((const unsigned*)((const char*)(gbase) + (voff)[_i]), (LAS unsigned*)(lds + (bufoff) + ldsw + _i * 8192), 16, 0, 0); } while (0)
; #define PG8_LDA(dst, b, h) do { _Pragma("unroll") for (int m = 0; m < 4; ++m) _Pragma("unroll") for (int k = 0; k < 2; ++k) dst[m][k] = *(const LAS bf16x8*)(lds + PG8_SA(b, h) + aoff + m * 2048 + k * 1024); } while (0)
; #define PG8_LDB(dst, b, h) do { _Pragma("unroll") for (int n = 0; n < 2; ++n) _Pragma("unroll") for (int k = 0; k < 2; ++k) dst[n][k] = *(const LAS bf16x8*)(lds + PG8_SB(b, h) + boff + n * 2048 + k * 1024); } while (0)
; #define PG8_WAIT_V(n) asm volatile("s_waitcnt vmcnt(" #n ")" ::: "memory")
; #define PG8_WAIT_L(n) asm volatile("s_waitcnt lgkmcnt(" #n ")" ::: "memory")
; template <class Epi, class Sched>
; __device__ __forceinline__ void gemm_phase(LAS unsigned char* lds, const Gemm g, const Sched& S, const Epi& E) {
;     ...
;             const bool last = (t == nt - 2);
;             const char* a1 = cA + (size_t)(t + 1) * kstep;
;             const char* a2 = last ? nA : cA + (size_t)(t + 2) * kstep; const char* b2 = last ? nB : cB + (size_t)(t + 2) * kstep;
;             const char* a3 = a2 + kstep; const char* b3 = b2 + kstep;
;             PG8_LDB(B0, 0, 0); PG8_LDB(B1, 0, 1); PG8_SCHED; PG8_LDA(At, 0, 0); PG8_STAGE(PG8_SA(1, 1), a1 + hstepA, voffA);
;             PG8_WAIT_V(8); PG8_WAIT_L(0); PG8_BAR; PG8_MMA(0, 0, At, B0); PG8_MMA(0, 1, At, B1); PG8_BAR; PG8_SCHED;
;             PG8_LDA(At, 0, 1); PG8_STAGE(PG8_SB(0, 0), b2, voffB); PG8_STAGE(PG8_SB(0, 1), b2 + hstepB, voffB); PG8_STAGE(PG8_SA(0, 0), a2, voffA);
;             PG8_WAIT_V(8); PG8_WAIT_L(0); PG8_BAR; PG8_MMA(1, 0, At, B0); PG8_MMA(1, 1, At, B1); PG8_BAR; PG8_SCHED;
;             PG8_LDB(B0, 1, 0); PG8_LDB(B1, 1, 1); PG8_SCHED; PG8_LDA(At, 1, 0); PG8_STAGE(PG8_SA(0, 1), a2 + hstepA, voffA);
;             PG8_WAIT_V(8); PG8_WAIT_L(0); PG8_BAR; PG8_MMA(0, 0, At, B0); PG8_MMA(0, 1, At, B1); PG8_BAR; PG8_SCHED;
;             PG8_LDA(At, 1, 1); PG8_STAGE(PG8_SB(1, 0), b3, voffB); PG8_STAGE(PG8_SB(1, 1), b3 + hstepB, voffB); PG8_STAGE(PG8_SA(1, 0), a3, voffA);
;             PG8_WAIT_V(8); PG8_WAIT_L(0); PG8_BAR; PG8_MMA(1, 0, At, B0); PG8_MMA(1, 1, At, B1); PG8_BAR; PG8_SCHED;
;         }
	s_add_i32 s20, s8, 0x18000
	s_add_u32 s80, s76, 0x80
	s_addc_u32 s81, s77, 0
	s_mov_b32 m0, s20
	ds_read_b128 v[194:197], v160 offset:49152
	ds_read_b128 v[198:201], v160 offset:50176
	ds_read_b128 v[202:205], v160 offset:51200
	ds_read_b128 v[206:209], v160 offset:52224
	ds_read_b128 v[218:221], v160 offset:53248
	ds_read_b128 v[222:225], v160 offset:54272
	ds_read_b128 v[226:229], v160 offset:55296
	ds_read_b128 v[230:233], v160 offset:56320
	global_load_lds_dwordx4 v148, s[80:81]
	s_add_i32 m0, s20, 0x2000
	s_add_u32 s20, s76, 0x40080
	s_addc_u32 s21, s77, 0
	s_add_i32 s12, s8, 0x1c000
	global_load_lds_dwordx4 v152, s[80:81]
	s_mov_b32 m0, s12
	s_nop 0
	global_load_lds_dwordx4 v148, s[20:21]
	s_add_i32 m0, s12, 0x2000
	s_nop 0
	global_load_lds_dwordx4 v152, s[20:21]
	s_mov_b32 m0, s31
	s_nop 0
	global_load_lds_dwordx4 v146, s[100:101]
	s_mov_b32 m0, s34
	s_nop 0
	global_load_lds_dwordx4 v150, s[100:101]
	s_waitcnt vmcnt(8)
	s_waitcnt lgkmcnt(0)
	s_barrier
	s_waitcnt lgkmcnt(0)
	v_mfma_f32_16x16x32_bf16 v[62:65], v[130:133], v[194:197], v[62:65]
	v_mfma_f32_16x16x32_bf16 v[58:61], v[138:141], v[194:197], v[58:61]
	v_mfma_f32_16x16x32_bf16 v[54:57], v[130:133], v[202:205], v[54:57]
	v_mfma_f32_16x16x32_bf16 v[46:49], v[138:141], v[202:205], v[46:49]
	v_mfma_f32_16x16x32_bf16 v[38:41], v[130:133], v[218:221], v[38:41]
	v_mfma_f32_16x16x32_bf16 v[30:33], v[138:141], v[218:221], v[30:33]
	v_mfma_f32_16x16x32_bf16 v[22:25], v[130:133], v[226:229], v[22:25]
	v_mfma_f32_16x16x32_bf16 v[14:17], v[138:141], v[226:229], v[14:17]
	v_mfma_f32_16x16x32_bf16 v[62:65], v[134:137], v[198:201], v[62:65]
	v_mfma_f32_16x16x32_bf16 v[58:61], v[142:145], v[198:201], v[58:61]
	v_mfma_f32_16x16x32_bf16 v[54:57], v[134:137], v[206:209], v[54:57]
	v_mfma_f32_16x16x32_bf16 v[46:49], v[142:145], v[206:209], v[46:49]
	v_mfma_f32_16x16x32_bf16 v[38:41], v[134:137], v[222:225], v[38:41]
	v_mfma_f32_16x16x32_bf16 v[30:33], v[142:145], v[222:225], v[30:33]
	v_mfma_f32_16x16x32_bf16 v[22:25], v[134:137], v[230:233], v[22:25]
	v_mfma_f32_16x16x32_bf16 v[14:17], v[142:145], v[230:233], v[14:17]
	v_mfma_f32_16x16x32_bf16 v[50:53], v[162:165], v[194:197], v[50:53]
	v_mfma_f32_16x16x32_bf16 v[42:45], v[170:173], v[194:197], v[42:45]
	v_mfma_f32_16x16x32_bf16 v[34:37], v[162:165], v[202:205], v[34:37]
	v_mfma_f32_16x16x32_bf16 v[26:29], v[170:173], v[202:205], v[26:29]
	v_mfma_f32_16x16x32_bf16 v[18:21], v[162:165], v[218:221], v[18:21]
	v_mfma_f32_16x16x32_bf16 v[10:13], v[170:173], v[218:221], v[10:13]
	v_mfma_f32_16x16x32_bf16 v[6:9], v[162:165], v[226:229], v[6:9]
	v_mfma_f32_16x16x32_bf16 v[2:5], v[170:173], v[226:229], v[2:5]
	v_mfma_f32_16x16x32_bf16 v[50:53], v[166:169], v[198:201], v[50:53]
	v_mfma_f32_16x16x32_bf16 v[42:45], v[190:193], v[198:201], v[42:45]
	v_mfma_f32_16x16x32_bf16 v[34:37], v[166:169], v[206:209], v[34:37]
	v_mfma_f32_16x16x32_bf16 v[26:29], v[190:193], v[206:209], v[26:29]
	v_mfma_f32_16x16x32_bf16 v[18:21], v[166:169], v[222:225], v[18:21]
	v_mfma_f32_16x16x32_bf16 v[10:13], v[190:193], v[222:225], v[10:13]
	v_mfma_f32_16x16x32_bf16 v[6:9], v[166:169], v[230:233], v[6:9]
	v_mfma_f32_16x16x32_bf16 v[2:5], v[190:193], v[230:233], v[2:5]
	s_barrier
	s_add_i32 s78, s78, 2
	s_add_u32 s18, s18, 0x100
	s_addc_u32 s19, s19, 0
	s_add_u32 s69, s69, 0x100
	s_addc_u32 s71, s71, 0
	s_cmp_gt_u32 s78, 13
.LBB0_378:
	s_add_u32 s20, s18, 0xfffc0080
	s_addc_u32 s21, s19, -1
	s_add_i32 s79, 0, 0x10000
	s_cmp_eq_u32 s78, 12
	s_cselect_b32 s21, s43, s21
	s_cselect_b32 s20, s48, s20
	s_cselect_b32 s77, s49, s71
	s_cselect_b32 s76, s53, s69
	s_add_u32 s100, s20, 0x80
	s_addc_u32 s101, s21, 0
	s_add_i32 s82, 0, 0x14000
	ds_read_b128 v[130:133], v255
	ds_read_b128 v[134:137], v255 offset:1024
	ds_read_b128 v[138:141], v255 offset:2048
	ds_read_b128 v[142:145], v255 offset:3072
	ds_read_b128 v[162:165], v255 offset:16384
	ds_read_b128 v[166:169], v255 offset:17408
	ds_read_b128 v[170:173], v255 offset:18432
	ds_read_b128 v[190:193], v255 offset:19456
	s_add_i32 m0, s9, 0xc000
	ds_read_b128 v[194:197], v160
	ds_read_b128 v[198:201], v160 offset:1024
	ds_read_b128 v[202:205], v160 offset:2048
	ds_read_b128 v[206:209], v160 offset:3072
	ds_read_b128 v[218:221], v160 offset:4096
	ds_read_b128 v[222:225], v160 offset:5120
	ds_read_b128 v[226:229], v160 offset:6144
	ds_read_b128 v[230:233], v160 offset:7168
	global_load_lds_dwordx4 v146, s[18:19]
	s_add_i32 m0, s9, 0xe000
	s_nop 0
	global_load_lds_dwordx4 v150, s[18:19]
	s_waitcnt vmcnt(8)
	s_waitcnt lgkmcnt(0)
	s_barrier
; #define PG8_STAGE(bufoff, gbase, voff) do { _Pragma("unroll") for (int _i = 0; _i < 2; ++_i) \
;         __builtin_amdgcn_global_load_lds((const unsigned*)((const char*)(gbase) + (voff)[_i]), (LAS unsigned*)(lds + (bufoff) + ldsw + _i * 8192), 16, 0, 0); } while (0)
; #define PG8_LDA(dst, b, h) do { _Pragma("unroll") for (int m = 0; m < 4; ++m) _Pragma("unroll") for (int k = 0; k < 2; ++k) dst[m][k] = *(const LAS bf16x8*)(lds + PG8_SA(b, h) + aoff + m * 2048 + k * 1024); } while (0)
; #define PG8_MMA(ai, bj, At, Bt) do { __builtin_amdgcn_s_setprio(1); _Pragma("unroll") for (int m = 0; m < 4; ++m) _Pragma("unroll") for (int n = 0; n < 2; ++n) _Pragma("unroll") for (int k = 0; k < 2; ++k) \
;         acc[ai][bj][m][n] = __builtin_amdgcn_mfma_f32_16x16x32_bf16(Bt[n][k], At[m][k], acc[ai][bj][m][n], 0, 0, 0); __builtin_amdgcn_s_setprio(0); } while (0)
; #define PG8_WAIT_V(n) asm volatile("s_waitcnt vmcnt(" #n ")" ::: "memory")
; #define PG8_WAIT_L(n) asm volatile("s_waitcnt lgkmcnt(" #n ")" ::: "memory")
; #define PG8_BAR __builtin_amdgcn_s_barrier()
; #define PG8_SCHED __builtin_amdgcn_sched_barrier(0)
; template <class Epi, class Sched>
; __device__ __forceinline__ void gemm_phase(LAS unsigned char* lds, const Gemm g, const Sched& S, const Epi& E) {
;     ...
;             PG8_WAIT_V(8); PG8_WAIT_L(0); PG8_BAR; PG8_MMA(0, 0, At, B0); PG8_MMA(0, 1, At, B1); PG8_BAR; PG8_SCHED;
;             PG8_LDA(At, 0, 1); PG8_STAGE(PG8_SB(0, 0), b2, voffB); PG8_STAGE(PG8_SB(0, 1), b2 + hstepB, voffB); PG8_STAGE(PG8_SA(0, 0), a2, voffA);
;             PG8_WAIT_V(8); PG8_WAIT_L(0); PG8_BAR; PG8_MMA(1, 0, At, B0); PG8_MMA(1, 1, At, B1); PG8_BAR; PG8_SCHED;
	s_waitcnt lgkmcnt(0)
	v_mfma_f32_16x16x32_bf16 v[126:129], v[130:133], v[194:197], v[126:129]
	v_mfma_f32_16x16x32_bf16 v[122:125], v[138:141], v[194:197], v[122:125]
	v_mfma_f32_16x16x32_bf16 v[118:121], v[130:133], v[202:205], v[118:121]
	v_mfma_f32_16x16x32_bf16 v[110:113], v[138:141], v[202:205], v[110:113]
	v_mfma_f32_16x16x32_bf16 v[102:105], v[130:133], v[218:221], v[102:105]
	v_mfma_f32_16x16x32_bf16 v[94:97], v[138:141], v[218:221], v[94:97]
	v_mfma_f32_16x16x32_bf16 v[86:89], v[130:133], v[226:229], v[86:89]
	v_mfma_f32_16x16x32_bf16 v[78:81], v[138:141], v[226:229], v[78:81]
	v_mfma_f32_16x16x32_bf16 v[126:129], v[134:137], v[198:201], v[126:129]
	v_mfma_f32_16x16x32_bf16 v[122:125], v[142:145], v[198:201], v[122:125]
	v_mfma_f32_16x16x32_bf16 v[118:121], v[134:137], v[206:209], v[118:121]
	v_mfma_f32_16x16x32_bf16 v[110:113], v[142:145], v[206:209], v[110:113]
	v_mfma_f32_16x16x32_bf16 v[102:105], v[134:137], v[222:225], v[102:105]
	v_mfma_f32_16x16x32_bf16 v[94:97], v[142:145], v[222:225], v[94:97]
	v_mfma_f32_16x16x32_bf16 v[86:89], v[134:137], v[230:233], v[86:89]
	v_mfma_f32_16x16x32_bf16 v[78:81], v[142:145], v[230:233], v[78:81]
	v_mfma_f32_16x16x32_bf16 v[114:117], v[162:165], v[194:197], v[114:117]
	v_mfma_f32_16x16x32_bf16 v[106:109], v[170:173], v[194:197], v[106:109]
	v_mfma_f32_16x16x32_bf16 v[98:101], v[162:165], v[202:205], v[98:101]
	v_mfma_f32_16x16x32_bf16 v[90:93], v[170:173], v[202:205], v[90:93]
	v_mfma_f32_16x16x32_bf16 v[82:85], v[162:165], v[218:221], v[82:85]
	v_mfma_f32_16x16x32_bf16 v[74:77], v[170:173], v[218:221], v[74:77]
	v_mfma_f32_16x16x32_bf16 v[70:73], v[162:165], v[226:229], v[70:73]
	v_mfma_f32_16x16x32_bf16 v[66:69], v[170:173], v[226:229], v[66:69]
	v_mfma_f32_16x16x32_bf16 v[114:117], v[166:169], v[198:201], v[114:117]
	v_mfma_f32_16x16x32_bf16 v[106:109], v[190:193], v[198:201], v[106:109]
	v_mfma_f32_16x16x32_bf16 v[98:101], v[166:169], v[206:209], v[98:101]
	v_mfma_f32_16x16x32_bf16 v[90:93], v[190:193], v[206:209], v[90:93]
	v_mfma_f32_16x16x32_bf16 v[82:85], v[166:169], v[222:225], v[82:85]
	v_mfma_f32_16x16x32_bf16 v[74:77], v[190:193], v[222:225], v[74:77]
	v_mfma_f32_16x16x32_bf16 v[70:73], v[166:169], v[230:233], v[70:73]
	v_mfma_f32_16x16x32_bf16 v[66:69], v[190:193], v[230:233], v[66:69]
	s_barrier
	s_add_i32 s79, s79, s8
	s_mov_b32 m0, s79
	ds_read_b128 v[194:197], v160 offset:16384
	ds_read_b128 v[198:201], v160 offset:17408
	ds_read_b128 v[202:205], v160 offset:18432
	ds_read_b128 v[206:209], v160 offset:19456
	ds_read_b128 v[218:221], v160 offset:20480
	ds_read_b128 v[222:225], v160 offset:21504
	ds_read_b128 v[226:229], v160 offset:22528
	ds_read_b128 v[230:233], v160 offset:23552
	global_load_lds_dwordx4 v148, s[76:77]
	s_add_i32 m0, s79, 0x2000
	s_add_u32 s80, s76, 0x40000
	s_addc_u32 s81, s77, 0
	s_add_i32 s79, s82, s8
	global_load_lds_dwordx4 v152, s[76:77]
	s_mov_b32 m0, s79
	s_nop 0
	global_load_lds_dwordx4 v148, s[80:81]
	s_add_i32 m0, s79, 0x2000
	s_nop 0
	global_load_lds_dwordx4 v152, s[80:81]
	s_mov_b32 m0, s9
	s_nop 0
	global_load_lds_dwordx4 v146, s[20:21]
	s_mov_b32 m0, s28
	s_nop 0
	global_load_lds_dwordx4 v150, s[20:21]
	s_waitcnt vmcnt(8)
	s_waitcnt lgkmcnt(0)
	s_barrier
	s_waitcnt lgkmcnt(0)
	v_mfma_f32_16x16x32_bf16 v[62:65], v[130:133], v[194:197], v[62:65]
	v_mfma_f32_16x16x32_bf16 v[58:61], v[138:141], v[194:197], v[58:61]
	v_mfma_f32_16x16x32_bf16 v[54:57], v[130:133], v[202:205], v[54:57]
	v_mfma_f32_16x16x32_bf16 v[46:49], v[138:141], v[202:205], v[46:49]
	v_mfma_f32_16x16x32_bf16 v[38:41], v[130:133], v[218:221], v[38:41]
	v_mfma_f32_16x16x32_bf16 v[30:33], v[138:141], v[218:221], v[30:33]
	v_mfma_f32_16x16x32_bf16 v[22:25], v[130:133], v[226:229], v[22:25]
	v_mfma_f32_16x16x32_bf16 v[14:17], v[138:141], v[226:229], v[14:17]
	v_mfma_f32_16x16x32_bf16 v[62:65], v[134:137], v[198:201], v[62:65]
	v_mfma_f32_16x16x32_bf16 v[58:61], v[142:145], v[198:201], v[58:61]
	v_mfma_f32_16x16x32_bf16 v[54:57], v[134:137], v[206:209], v[54:57]
	v_mfma_f32_16x16x32_bf16 v[46:49], v[142:145], v[206:209], v[46:49]
	v_mfma_f32_16x16x32_bf16 v[38:41], v[134:137], v[222:225], v[38:41]
	v_mfma_f32_16x16x32_bf16 v[30:33], v[142:145], v[222:225], v[30:33]
	v_mfma_f32_16x16x32_bf16 v[22:25], v[134:137], v[230:233], v[22:25]
	v_mfma_f32_16x16x32_bf16 v[14:17], v[142:145], v[230:233], v[14:17]
	v_mfma_f32_16x16x32_bf16 v[50:53], v[162:165], v[194:197], v[50:53]
	v_mfma_f32_16x16x32_bf16 v[42:45], v[170:173], v[194:197], v[42:45]
	v_mfma_f32_16x16x32_bf16 v[34:37], v[162:165], v[202:205], v[34:37]
	v_mfma_f32_16x16x32_bf16 v[26:29], v[170:173], v[202:205], v[26:29]
	v_mfma_f32_16x16x32_bf16 v[18:21], v[162:165], v[218:221], v[18:21]
	v_mfma_f32_16x16x32_bf16 v[10:13], v[170:173], v[218:221], v[10:13]
	v_mfma_f32_16x16x32_bf16 v[6:9], v[162:165], v[226:229], v[6:9]
	v_mfma_f32_16x16x32_bf16 v[2:5], v[170:173], v[226:229], v[2:5]
	v_mfma_f32_16x16x32_bf16 v[50:53], v[166:169], v[198:201], v[50:53]
	v_mfma_f32_16x16x32_bf16 v[42:45], v[190:193], v[198:201], v[42:45]
	v_mfma_f32_16x16x32_bf16 v[34:37], v[166:169], v[206:209], v[34:37]
	v_mfma_f32_16x16x32_bf16 v[26:29], v[190:193], v[206:209], v[26:29]
	v_mfma_f32_16x16x32_bf16 v[18:21], v[166:169], v[222:225], v[18:21]
	v_mfma_f32_16x16x32_bf16 v[10:13], v[190:193], v[222:225], v[10:13]
	v_mfma_f32_16x16x32_bf16 v[6:9], v[166:169], v[230:233], v[6:9]
	v_mfma_f32_16x16x32_bf16 v[2:5], v[190:193], v[230:233], v[2:5]
	s_barrier
; #define PG8_STAGE(bufoff, gbase, voff) do { _Pragma("unroll") for (int _i = 0; _i < 2; ++_i) \
;         __builtin_amdgcn_global_load_lds((const unsigned*)((const char*)(gbase) + (voff)[_i]), (LAS unsigned*)(lds + (bufoff) + ldsw + _i * 8192), 16, 0, 0); } while (0)
; #define PG8_LDA(dst, b, h) do { _Pragma("unroll") for (int m = 0; m < 4; ++m) _Pragma("unroll") for (int k = 0; k < 2; ++k) dst[m][k] = *(const LAS bf16x8*)(lds + PG8_SA(b, h) + aoff + m * 2048 + k * 1024); } while (0)
; #define PG8_LDB(dst, b, h) do { _Pragma("unroll") for (int n = 0; n < 2; ++n) _Pragma("unroll") for (int k = 0; k < 2; ++k) dst[n][k] = *(const LAS bf16x8*)(lds + PG8_SB(b, h) + boff + n * 2048 + k * 1024); } while (0)
; #define PG8_MMA(ai, bj, At, Bt) do { __builtin_amdgcn_s_setprio(1); _Pragma("unroll") for (int m = 0; m < 4; ++m) _Pragma("unroll") for (int n = 0; n < 2; ++n) _Pragma("unroll") for (int k = 0; k < 2; ++k) \
;         acc[ai][bj][m][n] = __builtin_amdgcn_mfma_f32_16x16x32_bf16(Bt[n][k], At[m][k], acc[ai][bj][m][n], 0, 0, 0); __builtin_amdgcn_s_setprio(0); } while (0)
; #define PG8_WAIT_V(n) asm volatile("s_waitcnt vmcnt(" #n ")" ::: "memory")
; #define PG8_WAIT_L(n) asm volatile("s_waitcnt lgkmcnt(" #n ")" ::: "memory")
; #define PG8_BAR __builtin_amdgcn_s_barrier()
; #define PG8_SCHED __builtin_amdgcn_sched_barrier(0)
; template <class Epi, class Sched>
; __device__ __forceinline__ void gemm_phase(LAS unsigned char* lds, const Gemm g, const Sched& S, const Epi& E) {
;     ...
;             PG8_LDB(B0, 1, 0); PG8_LDB(B1, 1, 1); PG8_SCHED; PG8_LDA(At, 1, 0); PG8_STAGE(PG8_SA(0, 1), a2 + hstepA, voffA);
;             PG8_WAIT_V(8); PG8_WAIT_L(0); PG8_BAR; PG8_MMA(0, 0, At, B0); PG8_MMA(0, 1, At, B1); PG8_BAR; PG8_SCHED;
;             PG8_LDA(At, 1, 1); PG8_STAGE(PG8_SB(1, 0), b3, voffB); PG8_STAGE(PG8_SB(1, 1), b3 + hstepB, voffB); PG8_STAGE(PG8_SA(1, 0), a3, voffA);
;             PG8_WAIT_V(8); PG8_WAIT_L(0); PG8_BAR; PG8_MMA(1, 0, At, B0); PG8_MMA(1, 1, At, B1); PG8_BAR; PG8_SCHED;
;         }
;         if (wr == 0) PG8_BAR;
	s_add_i32 s79, 0, 0x18000
	s_add_i32 s80, 0, 0x1c000
	ds_read_b128 v[130:133], v255 offset:32768
	ds_read_b128 v[134:137], v255 offset:33792
	ds_read_b128 v[138:141], v255 offset:34816
	ds_read_b128 v[142:145], v255 offset:35840
	ds_read_b128 v[162:165], v255 offset:49152
	ds_read_b128 v[166:169], v255 offset:50176
	ds_read_b128 v[170:173], v255 offset:51200
	ds_read_b128 v[190:193], v255 offset:52224
	s_add_u32 s20, s20, 0x40000
	s_addc_u32 s21, s21, 0
	s_mov_b32 m0, s29
	ds_read_b128 v[194:197], v160 offset:32768
	ds_read_b128 v[198:201], v160 offset:33792
	ds_read_b128 v[202:205], v160 offset:34816
	ds_read_b128 v[206:209], v160 offset:35840
	ds_read_b128 v[218:221], v160 offset:36864
	ds_read_b128 v[222:225], v160 offset:37888
	ds_read_b128 v[226:229], v160 offset:38912
	ds_read_b128 v[230:233], v160 offset:39936
	global_load_lds_dwordx4 v146, s[20:21]
	s_mov_b32 m0, s30
	s_nop 0
	global_load_lds_dwordx4 v150, s[20:21]
	s_waitcnt vmcnt(8)
	s_waitcnt lgkmcnt(0)
	s_barrier
	s_waitcnt lgkmcnt(0)
	v_mfma_f32_16x16x32_bf16 v[126:129], v[130:133], v[194:197], v[126:129]
	v_mfma_f32_16x16x32_bf16 v[122:125], v[138:141], v[194:197], v[122:125]
	v_mfma_f32_16x16x32_bf16 v[118:121], v[130:133], v[202:205], v[118:121]
	v_mfma_f32_16x16x32_bf16 v[110:113], v[138:141], v[202:205], v[110:113]
	v_mfma_f32_16x16x32_bf16 v[102:105], v[130:133], v[218:221], v[102:105]
	v_mfma_f32_16x16x32_bf16 v[94:97], v[138:141], v[218:221], v[94:97]
	v_mfma_f32_16x16x32_bf16 v[86:89], v[130:133], v[226:229], v[86:89]
	v_mfma_f32_16x16x32_bf16 v[78:81], v[138:141], v[226:229], v[78:81]
	v_mfma_f32_16x16x32_bf16 v[126:129], v[134:137], v[198:201], v[126:129]
	v_mfma_f32_16x16x32_bf16 v[122:125], v[142:145], v[198:201], v[122:125]
	v_mfma_f32_16x16x32_bf16 v[118:121], v[134:137], v[206:209], v[118:121]
	v_mfma_f32_16x16x32_bf16 v[110:113], v[142:145], v[206:209], v[110:113]
	v_mfma_f32_16x16x32_bf16 v[102:105], v[134:137], v[222:225], v[102:105]
	v_mfma_f32_16x16x32_bf16 v[94:97], v[142:145], v[222:225], v[94:97]
	v_mfma_f32_16x16x32_bf16 v[86:89], v[134:137], v[230:233], v[86:89]
	v_mfma_f32_16x16x32_bf16 v[78:81], v[142:145], v[230:233], v[78:81]
	v_mfma_f32_16x16x32_bf16 v[114:117], v[162:165], v[194:197], v[114:117]
	v_mfma_f32_16x16x32_bf16 v[106:109], v[170:173], v[194:197], v[106:109]
	v_mfma_f32_16x16x32_bf16 v[98:101], v[162:165], v[202:205], v[98:101]
	v_mfma_f32_16x16x32_bf16 v[90:93], v[170:173], v[202:205], v[90:93]
	v_mfma_f32_16x16x32_bf16 v[82:85], v[162:165], v[218:221], v[82:85]
	v_mfma_f32_16x16x32_bf16 v[74:77], v[170:173], v[218:221], v[74:77]
	v_mfma_f32_16x16x32_bf16 v[70:73], v[162:165], v[226:229], v[70:73]
	v_mfma_f32_16x16x32_bf16 v[66:69], v[170:173], v[226:229], v[66:69]
	v_mfma_f32_16x16x32_bf16 v[114:117], v[166:169], v[198:201], v[114:117]
	v_mfma_f32_16x16x32_bf16 v[106:109], v[190:193], v[198:201], v[106:109]
	v_mfma_f32_16x16x32_bf16 v[98:101], v[166:169], v[206:209], v[98:101]
	v_mfma_f32_16x16x32_bf16 v[90:93], v[190:193], v[206:209], v[90:93]
	v_mfma_f32_16x16x32_bf16 v[82:85], v[166:169], v[222:225], v[82:85]
	v_mfma_f32_16x16x32_bf16 v[74:77], v[190:193], v[222:225], v[74:77]
	v_mfma_f32_16x16x32_bf16 v[70:73], v[166:169], v[230:233], v[70:73]
	v_mfma_f32_16x16x32_bf16 v[66:69], v[190:193], v[230:233], v[66:69]
	s_barrier
	s_add_i32 s20, s8, 0x18000
	s_add_u32 s80, s76, 0x80
	s_addc_u32 s81, s77, 0
	s_mov_b32 m0, s20
	ds_read_b128 v[194:197], v160 offset:49152
	ds_read_b128 v[198:201], v160 offset:50176
	ds_read_b128 v[202:205], v160 offset:51200
	ds_read_b128 v[206:209], v160 offset:52224
	ds_read_b128 v[218:221], v160 offset:53248
	ds_read_b128 v[222:225], v160 offset:54272
	ds_read_b128 v[226:229], v160 offset:55296
	ds_read_b128 v[230:233], v160 offset:56320
	global_load_lds_dwordx4 v148, s[80:81]
	s_add_i32 m0, s20, 0x2000
	s_add_u32 s20, s76, 0x40080
	s_addc_u32 s21, s77, 0
	s_add_i32 s12, s8, 0x1c000
	global_load_lds_dwordx4 v152, s[80:81]
	s_mov_b32 m0, s12
	s_nop 0
	global_load_lds_dwordx4 v148, s[20:21]
	s_add_i32 m0, s12, 0x2000
	s_nop 0
	global_load_lds_dwordx4 v152, s[20:21]
	s_mov_b32 m0, s31
	s_nop 0
	global_load_lds_dwordx4 v146, s[100:101]
	s_mov_b32 m0, s34
	s_nop 0
	global_load_lds_dwordx4 v150, s[100:101]
	s_waitcnt vmcnt(8)
	s_waitcnt lgkmcnt(0)
	s_barrier
	s_waitcnt lgkmcnt(0)
	v_mfma_f32_16x16x32_bf16 v[62:65], v[130:133], v[194:197], v[62:65]
	v_mfma_f32_16x16x32_bf16 v[58:61], v[138:141], v[194:197], v[58:61]
	v_mfma_f32_16x16x32_bf16 v[54:57], v[130:133], v[202:205], v[54:57]
	v_mfma_f32_16x16x32_bf16 v[46:49], v[138:141], v[202:205], v[46:49]
	v_mfma_f32_16x16x32_bf16 v[38:41], v[130:133], v[218:221], v[38:41]
	v_mfma_f32_16x16x32_bf16 v[30:33], v[138:141], v[218:221], v[30:33]
	v_mfma_f32_16x16x32_bf16 v[22:25], v[130:133], v[226:229], v[22:25]
	v_mfma_f32_16x16x32_bf16 v[14:17], v[138:141], v[226:229], v[14:17]
	v_mfma_f32_16x16x32_bf16 v[62:65], v[134:137], v[198:201], v[62:65]
	v_mfma_f32_16x16x32_bf16 v[58:61], v[142:145], v[198:201], v[58:61]
	v_mfma_f32_16x16x32_bf16 v[54:57], v[134:137], v[206:209], v[54:57]
	v_mfma_f32_16x16x32_bf16 v[46:49], v[142:145], v[206:209], v[46:49]
	v_mfma_f32_16x16x32_bf16 v[38:41], v[134:137], v[222:225], v[38:41]
	v_mfma_f32_16x16x32_bf16 v[30:33], v[142:145], v[222:225], v[30:33]
	v_mfma_f32_16x16x32_bf16 v[22:25], v[134:137], v[230:233], v[22:25]
	v_mfma_f32_16x16x32_bf16 v[14:17], v[142:145], v[230:233], v[14:17]
	v_mfma_f32_16x16x32_bf16 v[50:53], v[162:165], v[194:197], v[50:53]
	v_mfma_f32_16x16x32_bf16 v[42:45], v[170:173], v[194:197], v[42:45]
	v_mfma_f32_16x16x32_bf16 v[34:37], v[162:165], v[202:205], v[34:37]
	v_mfma_f32_16x16x32_bf16 v[26:29], v[170:173], v[202:205], v[26:29]
	v_mfma_f32_16x16x32_bf16 v[18:21], v[162:165], v[218:221], v[18:21]
	v_mfma_f32_16x16x32_bf16 v[10:13], v[170:173], v[218:221], v[10:13]
	v_mfma_f32_16x16x32_bf16 v[6:9], v[162:165], v[226:229], v[6:9]
	v_mfma_f32_16x16x32_bf16 v[2:5], v[170:173], v[226:229], v[2:5]
	v_mfma_f32_16x16x32_bf16 v[50:53], v[166:169], v[198:201], v[50:53]
	v_mfma_f32_16x16x32_bf16 v[42:45], v[190:193], v[198:201], v[42:45]
	v_mfma_f32_16x16x32_bf16 v[34:37], v[166:169], v[206:209], v[34:37]
	v_mfma_f32_16x16x32_bf16 v[26:29], v[190:193], v[206:209], v[26:29]
	v_mfma_f32_16x16x32_bf16 v[18:21], v[166:169], v[222:225], v[18:21]
	v_mfma_f32_16x16x32_bf16 v[10:13], v[190:193], v[222:225], v[10:13]
	v_mfma_f32_16x16x32_bf16 v[6:9], v[166:169], v[230:233], v[6:9]
	v_mfma_f32_16x16x32_bf16 v[2:5], v[190:193], v[230:233], v[2:5]
	s_barrier
	s_add_i32 s78, s78, 2
	s_add_u32 s18, s18, 0x100
	s_addc_u32 s19, s19, 0
	s_add_u32 s69, s69, 0x100
	s_addc_u32 s71, s71, 0
	s_cmp_gt_u32 s78, 13
	s_cbranch_scc0 .LBB0_378
	s_and_b64 vcc, exec, s[36:37]
	s_cbranch_vccz .LBB0_381
	s_barrier

; #define PG8_STAGE(bufoff, gbase, voff) do { _Pragma("unroll") for (int _i = 0; _i < 2; ++_i) \
;         __builtin_amdgcn_global_load_lds((const unsigned*)((const char*)(gbase) + (voff)[_i]), (LAS unsigned*)(lds + (bufoff) + ldsw + _i * 8192), 16, 0, 0); } while (0)
; #define PG8_LDA(dst, b, h) do { _Pragma("unroll") for (int m = 0; m < 4; ++m) _Pragma("unroll") for (int k = 0; k < 2; ++k) dst[m][k] = *(const LAS bf16x8*)(lds + PG8_SA(b, h) + aoff + m * 2048 + k * 1024); } while (0)
; #define PG8_LDB(dst, b, h) do { _Pragma("unroll") for (int n = 0; n < 2; ++n) _Pragma("unroll") for (int k = 0; k < 2; ++k) dst[n][k] = *(const LAS bf16x8*)(lds + PG8_SB(b, h) + boff + n * 2048 + k * 1024); } while (0)
; #define PG8_MMA(ai, bj, At, Bt) do { __builtin_amdgcn_s_setprio(1); _Pragma("unroll") for (int m = 0; m < 4; ++m) _Pragma("unroll") for (int n = 0; n < 2; ++n) _Pragma("unroll") for (int k = 0; k < 2; ++k) \
;         acc[ai][bj][m][n] = __builtin_amdgcn_mfma_f32_16x16x32_bf16(Bt[n][k], At[m][k], acc[ai][bj][m][n], 0, 0, 0); __builtin_amdgcn_s_setprio(0); } while (0)
; #define PG8_WAIT_V(n) asm volatile("s_waitcnt vmcnt(" #n ")" ::: "memory")
; #define PG8_WAIT_L(n) asm volatile("s_waitcnt lgkmcnt(" #n ")" ::: "memory")
; #define PG8_BAR __builtin_amdgcn_s_barrier()
; #define PG8_SCHED __builtin_amdgcn_sched_barrier(0)
; template <class Epi, class Sched>
; __device__ __forceinline__ void gemm_phase(LAS unsigned char* lds, const Gemm g, const Sched& S, const Epi& E) {
;     ...
;             const bool last = (t == nt - 2);
;             const char* a1 = cA + (size_t)(t + 1) * kstep;
;             const char* a2 = last ? nA : cA + (size_t)(t + 2) * kstep; const char* b2 = last ? nB : cB + (size_t)(t + 2) * kstep;
;             const char* a3 = a2 + kstep; const char* b3 = b2 + kstep;
;             PG8_LDB(B0, 0, 0); PG8_LDB(B1, 0, 1); PG8_SCHED; PG8_LDA(At, 0, 0); PG8_STAGE(PG8_SA(1, 1), a1 + hstepA, voffA);
;             PG8_WAIT_V(8); PG8_WAIT_L(0); PG8_BAR; PG8_MMA(0, 0, At, B0); PG8_MMA(0, 1, At, B1); PG8_BAR; PG8_SCHED;
;             PG8_LDA(At, 0, 1); PG8_STAGE(PG8_SB(0, 0), b2, voffB); PG8_STAGE(PG8_SB(0, 1), b2 + hstepB, voffB); PG8_STAGE(PG8_SA(0, 0), a2, voffA);
;             PG8_WAIT_V(8); PG8_WAIT_L(0); PG8_BAR; PG8_MMA(1, 0, At, B0); PG8_MMA(1, 1, At, B1); PG8_BAR; PG8_SCHED;
.LBB0_598:
	s_add_i32 vcc_lo, s20, 2
	s_add_u32 s90, s18, 0x80
	s_addc_u32 s21, s19, 0
	s_add_i32 s92, 0, 0x10000
	s_cmp_eq_u32 s43, s20
	s_cselect_b32 s21, s37, s21
	s_cselect_b32 s20, s36, s90
	s_cselect_b32 s91, s71, s87
	s_cselect_b32 s90, s70, s86
	s_add_i32 s93, 0, 0x14000
	ds_read_b128 v[142:145], v255
	ds_read_b128 v[150:153], v255 offset:1024
	ds_read_b128 v[154:157], v255 offset:2048
	ds_read_b128 v[158:161], v255 offset:3072
	ds_read_b128 v[162:165], v255 offset:16384
	ds_read_b128 v[166:169], v255 offset:17408
	ds_read_b128 v[170:173], v255 offset:18432
	ds_read_b128 v[190:193], v255 offset:19456
	s_add_i32 m0, s35, 0xc000
	ds_read_b128 v[194:197], v148
	ds_read_b128 v[198:201], v148 offset:1024
	ds_read_b128 v[202:205], v148 offset:2048
	ds_read_b128 v[206:209], v148 offset:3072
	ds_read_b128 v[218:221], v148 offset:4096
	ds_read_b128 v[222:225], v148 offset:5120
	ds_read_b128 v[226:229], v148 offset:6144
	ds_read_b128 v[230:233], v148 offset:7168
	global_load_lds_dwordx4 v138, s[18:19]
	s_add_i32 m0, s35, 0xe000
	s_nop 0
	global_load_lds_dwordx4 v140, s[18:19]
	s_waitcnt vmcnt(8)
	s_waitcnt lgkmcnt(0)
	s_barrier
	s_waitcnt lgkmcnt(0)
	v_mfma_f32_16x16x32_bf16 v[114:117], v[142:145], v[194:197], v[114:117]
	v_mfma_f32_16x16x32_bf16 v[118:121], v[154:157], v[194:197], v[118:121]
	v_mfma_f32_16x16x32_bf16 v[94:97], v[142:145], v[202:205], v[94:97]
	v_mfma_f32_16x16x32_bf16 v[98:101], v[154:157], v[202:205], v[98:101]
	v_mfma_f32_16x16x32_bf16 v[62:65], v[142:145], v[218:221], v[62:65]
	v_mfma_f32_16x16x32_bf16 v[66:69], v[154:157], v[218:221], v[66:69]
	v_mfma_f32_16x16x32_bf16 v[22:25], v[142:145], v[226:229], v[22:25]
	v_mfma_f32_16x16x32_bf16 v[34:37], v[154:157], v[226:229], v[34:37]
	v_mfma_f32_16x16x32_bf16 v[114:117], v[150:153], v[198:201], v[114:117]
	v_mfma_f32_16x16x32_bf16 v[118:121], v[158:161], v[198:201], v[118:121]
	v_mfma_f32_16x16x32_bf16 v[94:97], v[150:153], v[206:209], v[94:97]
	v_mfma_f32_16x16x32_bf16 v[98:101], v[158:161], v[206:209], v[98:101]
	v_mfma_f32_16x16x32_bf16 v[62:65], v[150:153], v[222:225], v[62:65]
	v_mfma_f32_16x16x32_bf16 v[66:69], v[158:161], v[222:225], v[66:69]
	v_mfma_f32_16x16x32_bf16 v[22:25], v[150:153], v[230:233], v[22:25]
	v_mfma_f32_16x16x32_bf16 v[34:37], v[158:161], v[230:233], v[34:37]
	v_mfma_f32_16x16x32_bf16 v[122:125], v[162:165], v[194:197], v[122:125]
	v_mfma_f32_16x16x32_bf16 v[126:129], v[170:173], v[194:197], v[126:129]
	v_mfma_f32_16x16x32_bf16 v[102:105], v[162:165], v[202:205], v[102:105]
	v_mfma_f32_16x16x32_bf16 v[106:109], v[170:173], v[202:205], v[106:109]
	v_mfma_f32_16x16x32_bf16 v[70:73], v[162:165], v[218:221], v[70:73]
	v_mfma_f32_16x16x32_bf16 v[78:81], v[170:173], v[218:221], v[78:81]
	v_mfma_f32_16x16x32_bf16 v[38:41], v[162:165], v[226:229], v[38:41]
	v_mfma_f32_16x16x32_bf16 v[46:49], v[170:173], v[226:229], v[46:49]
	v_mfma_f32_16x16x32_bf16 v[122:125], v[166:169], v[198:201], v[122:125]
	v_mfma_f32_16x16x32_bf16 v[126:129], v[190:193], v[198:201], v[126:129]
	v_mfma_f32_16x16x32_bf16 v[102:105], v[166:169], v[206:209], v[102:105]
	v_mfma_f32_16x16x32_bf16 v[106:109], v[190:193], v[206:209], v[106:109]
	v_mfma_f32_16x16x32_bf16 v[70:73], v[166:169], v[222:225], v[70:73]
	v_mfma_f32_16x16x32_bf16 v[78:81], v[190:193], v[222:225], v[78:81]
	v_mfma_f32_16x16x32_bf16 v[38:41], v[166:169], v[230:233], v[38:41]
	v_mfma_f32_16x16x32_bf16 v[46:49], v[190:193], v[230:233], v[46:49]
	s_barrier
	s_add_i32 s92, s92, s34
	s_add_u32 s98, s90, 0x80
	s_addc_u32 s99, s91, 0
	s_add_u32 s100, s20, 0x80
	s_addc_u32 s101, s21, 0
	s_mov_b32 m0, s92
	ds_read_b128 v[194:197], v148 offset:16384
	ds_read_b128 v[198:201], v148 offset:17408
	ds_read_b128 v[202:205], v148 offset:18432
	ds_read_b128 v[206:209], v148 offset:19456
	ds_read_b128 v[218:221], v148 offset:20480
	ds_read_b128 v[222:225], v148 offset:21504
	ds_read_b128 v[226:229], v148 offset:22528
	ds_read_b128 v[230:233], v148 offset:23552
	global_load_lds_dwordx4 v132, s[90:91]
	s_add_i32 m0, s92, 0x2000
	s_add_i32 s92, s93, s34
	global_load_lds_dwordx4 v136, s[90:91]
	s_add_u32 s90, s90, s29
	s_addc_u32 s91, s91, 0
	s_mov_b32 m0, s92
	s_nop 0
	global_load_lds_dwordx4 v132, s[90:91]
	s_add_i32 m0, s92, 0x2000
	s_nop 0
	global_load_lds_dwordx4 v136, s[90:91]
	s_mov_b32 m0, s35
	s_nop 0
	global_load_lds_dwordx4 v130, s[20:21]
	s_mov_b32 m0, s8
	s_nop 0
	global_load_lds_dwordx4 v134, s[20:21]
	s_waitcnt vmcnt(8)
	s_waitcnt lgkmcnt(0)
	s_barrier
	s_waitcnt lgkmcnt(0)
	v_mfma_f32_16x16x32_bf16 v[14:17], v[142:145], v[194:197], v[14:17]
	v_mfma_f32_16x16x32_bf16 v[26:29], v[154:157], v[194:197], v[26:29]
	v_mfma_f32_16x16x32_bf16 v[74:77], v[142:145], v[202:205], v[74:77]
	v_mfma_f32_16x16x32_bf16 v[82:85], v[154:157], v[202:205], v[82:85]
	v_mfma_f32_16x16x32_bf16 v[42:45], v[142:145], v[218:221], v[42:45]
	v_mfma_f32_16x16x32_bf16 v[50:53], v[154:157], v[218:221], v[50:53]
	v_mfma_f32_16x16x32_bf16 v[2:5], v[142:145], v[226:229], v[2:5]
	v_mfma_f32_16x16x32_bf16 v[6:9], v[154:157], v[226:229], v[6:9]
	v_mfma_f32_16x16x32_bf16 v[14:17], v[150:153], v[198:201], v[14:17]
	v_mfma_f32_16x16x32_bf16 v[26:29], v[158:161], v[198:201], v[26:29]
	v_mfma_f32_16x16x32_bf16 v[74:77], v[150:153], v[206:209], v[74:77]
	v_mfma_f32_16x16x32_bf16 v[82:85], v[158:161], v[206:209], v[82:85]
	v_mfma_f32_16x16x32_bf16 v[42:45], v[150:153], v[222:225], v[42:45]
	v_mfma_f32_16x16x32_bf16 v[50:53], v[158:161], v[222:225], v[50:53]
	v_mfma_f32_16x16x32_bf16 v[2:5], v[150:153], v[230:233], v[2:5]
	v_mfma_f32_16x16x32_bf16 v[6:9], v[158:161], v[230:233], v[6:9]
	v_mfma_f32_16x16x32_bf16 v[30:33], v[162:165], v[194:197], v[30:33]
	v_mfma_f32_16x16x32_bf16 v[110:113], v[170:173], v[194:197], v[110:113]
	v_mfma_f32_16x16x32_bf16 v[86:89], v[162:165], v[202:205], v[86:89]
	v_mfma_f32_16x16x32_bf16 v[90:93], v[170:173], v[202:205], v[90:93]
	v_mfma_f32_16x16x32_bf16 v[54:57], v[162:165], v[218:221], v[54:57]
	v_mfma_f32_16x16x32_bf16 v[58:61], v[170:173], v[218:221], v[58:61]
	v_mfma_f32_16x16x32_bf16 v[10:13], v[162:165], v[226:229], v[10:13]
	v_mfma_f32_16x16x32_bf16 v[18:21], v[170:173], v[226:229], v[18:21]
	v_mfma_f32_16x16x32_bf16 v[30:33], v[166:169], v[198:201], v[30:33]
	v_mfma_f32_16x16x32_bf16 v[110:113], v[190:193], v[198:201], v[110:113]
	v_mfma_f32_16x16x32_bf16 v[86:89], v[166:169], v[206:209], v[86:89]
	v_mfma_f32_16x16x32_bf16 v[90:93], v[190:193], v[206:209], v[90:93]
	v_mfma_f32_16x16x32_bf16 v[54:57], v[166:169], v[222:225], v[54:57]
	v_mfma_f32_16x16x32_bf16 v[58:61], v[190:193], v[222:225], v[58:61]
	v_mfma_f32_16x16x32_bf16 v[10:13], v[166:169], v[230:233], v[10:13]
	v_mfma_f32_16x16x32_bf16 v[18:21], v[190:193], v[230:233], v[18:21]
	s_barrier
; #define PG8_STAGE(bufoff, gbase, voff) do { _Pragma("unroll") for (int _i = 0; _i < 2; ++_i) \
;         __builtin_amdgcn_global_load_lds((const unsigned*)((const char*)(gbase) + (voff)[_i]), (LAS unsigned*)(lds + (bufoff) + ldsw + _i * 8192), 16, 0, 0); } while (0)
; #define PG8_LDA(dst, b, h) do { _Pragma("unroll") for (int m = 0; m < 4; ++m) _Pragma("unroll") for (int k = 0; k < 2; ++k) dst[m][k] = *(const LAS bf16x8*)(lds + PG8_SA(b, h) + aoff + m * 2048 + k * 1024); } while (0)
; #define PG8_LDB(dst, b, h) do { _Pragma("unroll") for (int n = 0; n < 2; ++n) _Pragma("unroll") for (int k = 0; k < 2; ++k) dst[n][k] = *(const LAS bf16x8*)(lds + PG8_SB(b, h) + boff + n * 2048 + k * 1024); } while (0)
; #define PG8_MMA(ai, bj, At, Bt) do { __builtin_amdgcn_s_setprio(1); _Pragma("unroll") for (int m = 0; m < 4; ++m) _Pragma("unroll") for (int n = 0; n < 2; ++n) _Pragma("unroll") for (int k = 0; k < 2; ++k) \
;         acc[ai][bj][m][n] = __builtin_amdgcn_mfma_f32_16x16x32_bf16(Bt[n][k], At[m][k], acc[ai][bj][m][n], 0, 0, 0); __builtin_amdgcn_s_setprio(0); } while (0)
; #define PG8_WAIT_V(n) asm volatile("s_waitcnt vmcnt(" #n ")" ::: "memory")
; #define PG8_WAIT_L(n) asm volatile("s_waitcnt lgkmcnt(" #n ")" ::: "memory")
; #define PG8_BAR __builtin_amdgcn_s_barrier()
; #define PG8_SCHED __builtin_amdgcn_sched_barrier(0)
; template <class Epi, class Sched>
; __device__ __forceinline__ void gemm_phase(LAS unsigned char* lds, const Gemm g, const Sched& S, const Epi& E) {
;     ...
;             PG8_LDB(B0, 1, 0); PG8_LDB(B1, 1, 1); PG8_SCHED; PG8_LDA(At, 1, 0); PG8_STAGE(PG8_SA(0, 1), a2 + hstepA, voffA);
;             PG8_WAIT_V(8); PG8_WAIT_L(0); PG8_BAR; PG8_MMA(0, 0, At, B0); PG8_MMA(0, 1, At, B1); PG8_BAR; PG8_SCHED;
;             PG8_LDA(At, 1, 1); PG8_STAGE(PG8_SB(1, 0), b3, voffB); PG8_STAGE(PG8_SB(1, 1), b3 + hstepB, voffB); PG8_STAGE(PG8_SA(1, 0), a3, voffA);
;             PG8_WAIT_V(8); PG8_WAIT_L(0); PG8_BAR; PG8_MMA(1, 0, At, B0); PG8_MMA(1, 1, At, B1); PG8_BAR; PG8_SCHED;
;         }
;         if (wr == 0) PG8_BAR;
	ds_read_b128 v[142:145], v255 offset:32768
	ds_read_b128 v[150:153], v255 offset:33792
	ds_read_b128 v[154:157], v255 offset:34816
	ds_read_b128 v[158:161], v255 offset:35840
	ds_read_b128 v[162:165], v255 offset:49152
	ds_read_b128 v[166:169], v255 offset:50176
	ds_read_b128 v[170:173], v255 offset:51200
	ds_read_b128 v[190:193], v255 offset:52224
	s_add_u32 s20, s20, s80
	s_addc_u32 s21, s21, 0
	s_mov_b32 m0, s9
	ds_read_b128 v[194:197], v148 offset:32768
	ds_read_b128 v[198:201], v148 offset:33792
	ds_read_b128 v[202:205], v148 offset:34816
	ds_read_b128 v[206:209], v148 offset:35840
	ds_read_b128 v[218:221], v148 offset:36864
	ds_read_b128 v[222:225], v148 offset:37888
	ds_read_b128 v[226:229], v148 offset:38912
	ds_read_b128 v[230:233], v148 offset:39936
	global_load_lds_dwordx4 v130, s[20:21]
	s_mov_b32 m0, s40
	s_nop 0
	global_load_lds_dwordx4 v134, s[20:21]
	s_waitcnt vmcnt(8)
	s_waitcnt lgkmcnt(0)
	s_barrier
	s_waitcnt lgkmcnt(0)
	v_mfma_f32_16x16x32_bf16 v[114:117], v[142:145], v[194:197], v[114:117]
	v_mfma_f32_16x16x32_bf16 v[118:121], v[154:157], v[194:197], v[118:121]
	v_mfma_f32_16x16x32_bf16 v[94:97], v[142:145], v[202:205], v[94:97]
	v_mfma_f32_16x16x32_bf16 v[98:101], v[154:157], v[202:205], v[98:101]
	v_mfma_f32_16x16x32_bf16 v[62:65], v[142:145], v[218:221], v[62:65]
	v_mfma_f32_16x16x32_bf16 v[66:69], v[154:157], v[218:221], v[66:69]
	v_mfma_f32_16x16x32_bf16 v[22:25], v[142:145], v[226:229], v[22:25]
	v_mfma_f32_16x16x32_bf16 v[34:37], v[154:157], v[226:229], v[34:37]
	v_mfma_f32_16x16x32_bf16 v[114:117], v[150:153], v[198:201], v[114:117]
	v_mfma_f32_16x16x32_bf16 v[118:121], v[158:161], v[198:201], v[118:121]
	v_mfma_f32_16x16x32_bf16 v[94:97], v[150:153], v[206:209], v[94:97]
	v_mfma_f32_16x16x32_bf16 v[98:101], v[158:161], v[206:209], v[98:101]
	v_mfma_f32_16x16x32_bf16 v[62:65], v[150:153], v[222:225], v[62:65]
	v_mfma_f32_16x16x32_bf16 v[66:69], v[158:161], v[222:225], v[66:69]
	v_mfma_f32_16x16x32_bf16 v[22:25], v[150:153], v[230:233], v[22:25]
	v_mfma_f32_16x16x32_bf16 v[34:37], v[158:161], v[230:233], v[34:37]
	v_mfma_f32_16x16x32_bf16 v[122:125], v[162:165], v[194:197], v[122:125]
	v_mfma_f32_16x16x32_bf16 v[126:129], v[170:173], v[194:197], v[126:129]
	v_mfma_f32_16x16x32_bf16 v[102:105], v[162:165], v[202:205], v[102:105]
	v_mfma_f32_16x16x32_bf16 v[106:109], v[170:173], v[202:205], v[106:109]
	v_mfma_f32_16x16x32_bf16 v[70:73], v[162:165], v[218:221], v[70:73]
	v_mfma_f32_16x16x32_bf16 v[78:81], v[170:173], v[218:221], v[78:81]
	v_mfma_f32_16x16x32_bf16 v[38:41], v[162:165], v[226:229], v[38:41]
	v_mfma_f32_16x16x32_bf16 v[46:49], v[170:173], v[226:229], v[46:49]
	v_mfma_f32_16x16x32_bf16 v[122:125], v[166:169], v[198:201], v[122:125]
	v_mfma_f32_16x16x32_bf16 v[126:129], v[190:193], v[198:201], v[126:129]
	v_mfma_f32_16x16x32_bf16 v[102:105], v[166:169], v[206:209], v[102:105]
	v_mfma_f32_16x16x32_bf16 v[106:109], v[190:193], v[206:209], v[106:109]
	v_mfma_f32_16x16x32_bf16 v[70:73], v[166:169], v[222:225], v[70:73]
	v_mfma_f32_16x16x32_bf16 v[78:81], v[190:193], v[222:225], v[78:81]
	v_mfma_f32_16x16x32_bf16 v[38:41], v[166:169], v[230:233], v[38:41]
	v_mfma_f32_16x16x32_bf16 v[46:49], v[190:193], v[230:233], v[46:49]
	s_barrier
	s_add_i32 s20, s34, 0x18000
	s_mov_b32 m0, s20
	ds_read_b128 v[194:197], v148 offset:49152
	ds_read_b128 v[198:201], v148 offset:50176
	ds_read_b128 v[202:205], v148 offset:51200
	ds_read_b128 v[206:209], v148 offset:52224
	ds_read_b128 v[218:221], v148 offset:53248
	ds_read_b128 v[222:225], v148 offset:54272
	ds_read_b128 v[226:229], v148 offset:55296
	ds_read_b128 v[230:233], v148 offset:56320
	global_load_lds_dwordx4 v132, s[98:99]
	s_add_i32 m0, s20, 0x2000
	s_add_i32 s20, s34, 0x1c000
	global_load_lds_dwordx4 v136, s[98:99]
	s_add_u32 s98, s98, s29
	s_addc_u32 s99, s99, 0
	s_mov_b32 m0, s20
	s_nop 0
	global_load_lds_dwordx4 v132, s[98:99]
	s_add_i32 m0, s20, 0x2000
	s_nop 0
	global_load_lds_dwordx4 v136, s[98:99]
	s_mov_b32 m0, s41
	s_nop 0
	global_load_lds_dwordx4 v130, s[100:101]
	s_mov_b32 m0, s42
	s_nop 0
	global_load_lds_dwordx4 v134, s[100:101]
	s_waitcnt vmcnt(8)
	s_waitcnt lgkmcnt(0)
	s_barrier
	s_waitcnt lgkmcnt(0)
	v_mfma_f32_16x16x32_bf16 v[14:17], v[142:145], v[194:197], v[14:17]
	v_mfma_f32_16x16x32_bf16 v[26:29], v[154:157], v[194:197], v[26:29]
	v_mfma_f32_16x16x32_bf16 v[74:77], v[142:145], v[202:205], v[74:77]
	v_mfma_f32_16x16x32_bf16 v[82:85], v[154:157], v[202:205], v[82:85]
	v_mfma_f32_16x16x32_bf16 v[42:45], v[142:145], v[218:221], v[42:45]
	v_mfma_f32_16x16x32_bf16 v[50:53], v[154:157], v[218:221], v[50:53]
	v_mfma_f32_16x16x32_bf16 v[2:5], v[142:145], v[226:229], v[2:5]
	v_mfma_f32_16x16x32_bf16 v[6:9], v[154:157], v[226:229], v[6:9]
	v_mfma_f32_16x16x32_bf16 v[14:17], v[150:153], v[198:201], v[14:17]
	v_mfma_f32_16x16x32_bf16 v[26:29], v[158:161], v[198:201], v[26:29]
	v_mfma_f32_16x16x32_bf16 v[74:77], v[150:153], v[206:209], v[74:77]
	v_mfma_f32_16x16x32_bf16 v[82:85], v[158:161], v[206:209], v[82:85]
	v_mfma_f32_16x16x32_bf16 v[42:45], v[150:153], v[222:225], v[42:45]
	v_mfma_f32_16x16x32_bf16 v[50:53], v[158:161], v[222:225], v[50:53]
	v_mfma_f32_16x16x32_bf16 v[2:5], v[150:153], v[230:233], v[2:5]
	v_mfma_f32_16x16x32_bf16 v[6:9], v[158:161], v[230:233], v[6:9]
	v_mfma_f32_16x16x32_bf16 v[30:33], v[162:165], v[194:197], v[30:33]
	v_mfma_f32_16x16x32_bf16 v[110:113], v[170:173], v[194:197], v[110:113]
	v_mfma_f32_16x16x32_bf16 v[86:89], v[162:165], v[202:205], v[86:89]
	v_mfma_f32_16x16x32_bf16 v[90:93], v[170:173], v[202:205], v[90:93]
	v_mfma_f32_16x16x32_bf16 v[54:57], v[162:165], v[218:221], v[54:57]
	v_mfma_f32_16x16x32_bf16 v[58:61], v[170:173], v[218:221], v[58:61]
	v_mfma_f32_16x16x32_bf16 v[10:13], v[162:165], v[226:229], v[10:13]
	v_mfma_f32_16x16x32_bf16 v[18:21], v[170:173], v[226:229], v[18:21]
	v_mfma_f32_16x16x32_bf16 v[30:33], v[166:169], v[198:201], v[30:33]
	v_mfma_f32_16x16x32_bf16 v[110:113], v[190:193], v[198:201], v[110:113]
	v_mfma_f32_16x16x32_bf16 v[86:89], v[166:169], v[206:209], v[86:89]
	v_mfma_f32_16x16x32_bf16 v[90:93], v[190:193], v[206:209], v[90:93]
	v_mfma_f32_16x16x32_bf16 v[54:57], v[166:169], v[222:225], v[54:57]
	v_mfma_f32_16x16x32_bf16 v[58:61], v[190:193], v[222:225], v[58:61]
	v_mfma_f32_16x16x32_bf16 v[10:13], v[166:169], v[230:233], v[10:13]
	v_mfma_f32_16x16x32_bf16 v[18:21], v[190:193], v[230:233], v[18:21]
	s_barrier
	s_add_u32 s18, s18, 0x100
	s_addc_u32 s19, s19, 0
	s_add_u32 s86, s86, 0x100
	s_addc_u32 s87, s87, 0
	s_cmp_ge_u32 vcc_lo, s48
	s_mov_b32 s20, vcc_lo
	s_cbranch_scc0 .LBB0_598
	s_and_b64 vcc, exec, s[84:85]
	s_cbranch_vccz .LBB0_601
	s_barrier

; #define PG8_STAGE(bufoff, gbase, voff) do { _Pragma("unroll") for (int _i = 0; _i < 2; ++_i) \
;         __builtin_amdgcn_global_load_lds((const unsigned*)((const char*)(gbase) + (voff)[_i]), (LAS unsigned*)(lds + (bufoff) + ldsw + _i * 8192), 16, 0, 0); } while (0)
; #define PG8_LDA(dst, b, h) do { _Pragma("unroll") for (int m = 0; m < 4; ++m) _Pragma("unroll") for (int k = 0; k < 2; ++k) dst[m][k] = *(const LAS bf16x8*)(lds + PG8_SA(b, h) + aoff + m * 2048 + k * 1024); } while (0)
; #define PG8_LDB(dst, b, h) do { _Pragma("unroll") for (int n = 0; n < 2; ++n) _Pragma("unroll") for (int k = 0; k < 2; ++k) dst[n][k] = *(const LAS bf16x8*)(lds + PG8_SB(b, h) + boff + n * 2048 + k * 1024); } while (0)
; #define PG8_MMA(ai, bj, At, Bt) do { __builtin_amdgcn_s_setprio(1); _Pragma("unroll") for (int m = 0; m < 4; ++m) _Pragma("unroll") for (int n = 0; n < 2; ++n) _Pragma("unroll") for (int k = 0; k < 2; ++k) \
;         acc[ai][bj][m][n] = __builtin_amdgcn_mfma_f32_16x16x32_bf16(Bt[n][k], At[m][k], acc[ai][bj][m][n], 0, 0, 0); __builtin_amdgcn_s_setprio(0); } while (0)
; #define PG8_WAIT_V(n) asm volatile("s_waitcnt vmcnt(" #n ")" ::: "memory")
; #define PG8_WAIT_L(n) asm volatile("s_waitcnt lgkmcnt(" #n ")" ::: "memory")
; #define PG8_BAR __builtin_amdgcn_s_barrier()
; #define PG8_SCHED __builtin_amdgcn_sched_barrier(0)
; template <class Epi, class Sched>
; __device__ __forceinline__ void gemm_phase(LAS unsigned char* lds, const Gemm g, const Sched& S, const Epi& E) {
;     ...
;             const bool last = (t == nt - 2);
;             const char* a1 = cA + (size_t)(t + 1) * kstep;
;             const char* a2 = last ? nA : cA + (size_t)(t + 2) * kstep; const char* b2 = last ? nB : cB + (size_t)(t + 2) * kstep;
;             const char* a3 = a2 + kstep; const char* b3 = b2 + kstep;
;             PG8_LDB(B0, 0, 0); PG8_LDB(B1, 0, 1); PG8_SCHED; PG8_LDA(At, 0, 0); PG8_STAGE(PG8_SA(1, 1), a1 + hstepA, voffA);
;             PG8_WAIT_V(8); PG8_WAIT_L(0); PG8_BAR; PG8_MMA(0, 0, At, B0); PG8_MMA(0, 1, At, B1); PG8_BAR; PG8_SCHED;
;             PG8_LDA(At, 0, 1); PG8_STAGE(PG8_SB(0, 0), b2, voffB); PG8_STAGE(PG8_SB(0, 1), b2 + hstepB, voffB); PG8_STAGE(PG8_SA(0, 0), a2, voffA);
;             PG8_WAIT_V(8); PG8_WAIT_L(0); PG8_BAR; PG8_MMA(1, 0, At, B0); PG8_MMA(1, 1, At, B1); PG8_BAR; PG8_SCHED;
.LBB0_640:
	s_add_i32 s87, s20, 2
	s_add_u32 s88, s18, 0x80
	s_addc_u32 s21, s19, 0
	s_add_i32 s90, 0, 0x10000
	s_cmp_eq_u32 s43, s20
	s_cselect_b32 s21, s69, s21
	s_cselect_b32 s20, s68, s88
	s_cselect_b32 s89, s81, s83
	s_cselect_b32 s88, s80, s82
	s_add_i32 s91, 0, 0x14000
	ds_read_b128 v[146:149], v255
	ds_read_b128 v[150:153], v255 offset:1024
	ds_read_b128 v[154:157], v255 offset:2048
	ds_read_b128 v[158:161], v255 offset:3072
	ds_read_b128 v[162:165], v255 offset:16384
	ds_read_b128 v[166:169], v255 offset:17408
	ds_read_b128 v[170:173], v255 offset:18432
	ds_read_b128 v[190:193], v255 offset:19456
	s_add_i32 m0, s30, 0xc000
	ds_read_b128 v[194:197], v144
	ds_read_b128 v[198:201], v144 offset:1024
	ds_read_b128 v[202:205], v144 offset:2048
	ds_read_b128 v[206:209], v144 offset:3072
	ds_read_b128 v[218:221], v144 offset:4096
	ds_read_b128 v[222:225], v144 offset:5120
	ds_read_b128 v[226:229], v144 offset:6144
	ds_read_b128 v[230:233], v144 offset:7168
	global_load_lds_dwordx4 v138, s[18:19]
	s_add_i32 m0, s30, 0xe000
	s_nop 0
	global_load_lds_dwordx4 v140, s[18:19]
	s_waitcnt vmcnt(8)
	s_waitcnt lgkmcnt(0)
	s_barrier
	s_waitcnt lgkmcnt(0)
	v_mfma_f32_16x16x32_bf16 v[2:5], v[146:149], v[194:197], v[2:5]
	v_mfma_f32_16x16x32_bf16 v[6:9], v[154:157], v[194:197], v[6:9]
	v_mfma_f32_16x16x32_bf16 v[10:13], v[146:149], v[202:205], v[10:13]
	v_mfma_f32_16x16x32_bf16 v[14:17], v[154:157], v[202:205], v[14:17]
	v_mfma_f32_16x16x32_bf16 v[26:29], v[146:149], v[218:221], v[26:29]
	v_mfma_f32_16x16x32_bf16 v[30:33], v[154:157], v[218:221], v[30:33]
	v_mfma_f32_16x16x32_bf16 v[42:45], v[146:149], v[226:229], v[42:45]
	v_mfma_f32_16x16x32_bf16 v[46:49], v[154:157], v[226:229], v[46:49]
	v_mfma_f32_16x16x32_bf16 v[2:5], v[150:153], v[198:201], v[2:5]
	v_mfma_f32_16x16x32_bf16 v[6:9], v[158:161], v[198:201], v[6:9]
	v_mfma_f32_16x16x32_bf16 v[10:13], v[150:153], v[206:209], v[10:13]
	v_mfma_f32_16x16x32_bf16 v[14:17], v[158:161], v[206:209], v[14:17]
	v_mfma_f32_16x16x32_bf16 v[26:29], v[150:153], v[222:225], v[26:29]
	v_mfma_f32_16x16x32_bf16 v[30:33], v[158:161], v[222:225], v[30:33]
	v_mfma_f32_16x16x32_bf16 v[42:45], v[150:153], v[230:233], v[42:45]
	v_mfma_f32_16x16x32_bf16 v[46:49], v[158:161], v[230:233], v[46:49]
	v_mfma_f32_16x16x32_bf16 v[18:21], v[162:165], v[194:197], v[18:21]
	v_mfma_f32_16x16x32_bf16 v[22:25], v[170:173], v[194:197], v[22:25]
	v_mfma_f32_16x16x32_bf16 v[34:37], v[162:165], v[202:205], v[34:37]
	v_mfma_f32_16x16x32_bf16 v[38:41], v[170:173], v[202:205], v[38:41]
	v_mfma_f32_16x16x32_bf16 v[50:53], v[162:165], v[218:221], v[50:53]
	v_mfma_f32_16x16x32_bf16 v[54:57], v[170:173], v[218:221], v[54:57]
	v_mfma_f32_16x16x32_bf16 v[58:61], v[162:165], v[226:229], v[58:61]
	v_mfma_f32_16x16x32_bf16 v[66:69], v[170:173], v[226:229], v[66:69]
	v_mfma_f32_16x16x32_bf16 v[18:21], v[166:169], v[198:201], v[18:21]
	v_mfma_f32_16x16x32_bf16 v[22:25], v[190:193], v[198:201], v[22:25]
	v_mfma_f32_16x16x32_bf16 v[34:37], v[166:169], v[206:209], v[34:37]
	v_mfma_f32_16x16x32_bf16 v[38:41], v[190:193], v[206:209], v[38:41]
	v_mfma_f32_16x16x32_bf16 v[50:53], v[166:169], v[222:225], v[50:53]
	v_mfma_f32_16x16x32_bf16 v[54:57], v[190:193], v[222:225], v[54:57]
	v_mfma_f32_16x16x32_bf16 v[58:61], v[166:169], v[230:233], v[58:61]
	v_mfma_f32_16x16x32_bf16 v[66:69], v[190:193], v[230:233], v[66:69]
	s_barrier
	s_add_i32 s90, s90, s29
	s_add_u32 s98, s88, 0x80
	s_addc_u32 s99, s89, 0
	s_add_u32 s100, s20, 0x80
	s_addc_u32 s101, s21, 0
	s_mov_b32 m0, s90
	ds_read_b128 v[194:197], v144 offset:16384
	ds_read_b128 v[198:201], v144 offset:17408
	ds_read_b128 v[202:205], v144 offset:18432
	ds_read_b128 v[206:209], v144 offset:19456
	ds_read_b128 v[218:221], v144 offset:20480
	ds_read_b128 v[222:225], v144 offset:21504
	ds_read_b128 v[226:229], v144 offset:22528
	ds_read_b128 v[230:233], v144 offset:23552
	global_load_lds_dwordx4 v132, s[88:89]
	s_add_i32 m0, s90, 0x2000
	s_add_i32 s90, s91, s29
	global_load_lds_dwordx4 v136, s[88:89]
	s_add_u32 s88, s88, s8
	s_addc_u32 s89, s89, 0
	s_mov_b32 m0, s90
	s_nop 0
	global_load_lds_dwordx4 v132, s[88:89]
	s_add_i32 m0, s90, 0x2000
	s_nop 0
	global_load_lds_dwordx4 v136, s[88:89]
	s_mov_b32 m0, s30
	s_nop 0
	global_load_lds_dwordx4 v130, s[20:21]
	s_mov_b32 m0, s31
	s_nop 0
	global_load_lds_dwordx4 v134, s[20:21]
	s_waitcnt vmcnt(8)
	s_waitcnt lgkmcnt(0)
	s_barrier
	s_waitcnt lgkmcnt(0)
	v_mfma_f32_16x16x32_bf16 v[62:65], v[146:149], v[194:197], v[62:65]
	v_mfma_f32_16x16x32_bf16 v[70:73], v[154:157], v[194:197], v[70:73]
	v_mfma_f32_16x16x32_bf16 v[78:81], v[146:149], v[202:205], v[78:81]
	v_mfma_f32_16x16x32_bf16 v[82:85], v[154:157], v[202:205], v[82:85]
	v_mfma_f32_16x16x32_bf16 v[90:93], v[146:149], v[218:221], v[90:93]
	v_mfma_f32_16x16x32_bf16 v[94:97], v[154:157], v[218:221], v[94:97]
	v_mfma_f32_16x16x32_bf16 v[106:109], v[146:149], v[226:229], v[106:109]
	v_mfma_f32_16x16x32_bf16 v[110:113], v[154:157], v[226:229], v[110:113]
	v_mfma_f32_16x16x32_bf16 v[62:65], v[150:153], v[198:201], v[62:65]
	v_mfma_f32_16x16x32_bf16 v[70:73], v[158:161], v[198:201], v[70:73]
	v_mfma_f32_16x16x32_bf16 v[78:81], v[150:153], v[206:209], v[78:81]
	v_mfma_f32_16x16x32_bf16 v[82:85], v[158:161], v[206:209], v[82:85]
	v_mfma_f32_16x16x32_bf16 v[90:93], v[150:153], v[222:225], v[90:93]
	v_mfma_f32_16x16x32_bf16 v[94:97], v[158:161], v[222:225], v[94:97]
	v_mfma_f32_16x16x32_bf16 v[106:109], v[150:153], v[230:233], v[106:109]
	v_mfma_f32_16x16x32_bf16 v[110:113], v[158:161], v[230:233], v[110:113]
	v_mfma_f32_16x16x32_bf16 v[74:77], v[162:165], v[194:197], v[74:77]
	v_mfma_f32_16x16x32_bf16 v[86:89], v[170:173], v[194:197], v[86:89]
	v_mfma_f32_16x16x32_bf16 v[98:101], v[162:165], v[202:205], v[98:101]
	v_mfma_f32_16x16x32_bf16 v[102:105], v[170:173], v[202:205], v[102:105]
	v_mfma_f32_16x16x32_bf16 v[114:117], v[162:165], v[218:221], v[114:117]
	v_mfma_f32_16x16x32_bf16 v[118:121], v[170:173], v[218:221], v[118:121]
	v_mfma_f32_16x16x32_bf16 v[122:125], v[162:165], v[226:229], v[122:125]
	v_mfma_f32_16x16x32_bf16 v[126:129], v[170:173], v[226:229], v[126:129]
	v_mfma_f32_16x16x32_bf16 v[74:77], v[166:169], v[198:201], v[74:77]
	v_mfma_f32_16x16x32_bf16 v[86:89], v[190:193], v[198:201], v[86:89]
	v_mfma_f32_16x16x32_bf16 v[98:101], v[166:169], v[206:209], v[98:101]
	v_mfma_f32_16x16x32_bf16 v[102:105], v[190:193], v[206:209], v[102:105]
	v_mfma_f32_16x16x32_bf16 v[114:117], v[166:169], v[222:225], v[114:117]
	v_mfma_f32_16x16x32_bf16 v[118:121], v[190:193], v[222:225], v[118:121]
	v_mfma_f32_16x16x32_bf16 v[122:125], v[166:169], v[230:233], v[122:125]
	v_mfma_f32_16x16x32_bf16 v[126:129], v[190:193], v[230:233], v[126:129]
	s_barrier
; #define PG8_STAGE(bufoff, gbase, voff) do { _Pragma("unroll") for (int _i = 0; _i < 2; ++_i) \
;         __builtin_amdgcn_global_load_lds((const unsigned*)((const char*)(gbase) + (voff)[_i]), (LAS unsigned*)(lds + (bufoff) + ldsw + _i * 8192), 16, 0, 0); } while (0)
; #define PG8_LDA(dst, b, h) do { _Pragma("unroll") for (int m = 0; m < 4; ++m) _Pragma("unroll") for (int k = 0; k < 2; ++k) dst[m][k] = *(const LAS bf16x8*)(lds + PG8_SA(b, h) + aoff + m * 2048 + k * 1024); } while (0)
; #define PG8_LDB(dst, b, h) do { _Pragma("unroll") for (int n = 0; n < 2; ++n) _Pragma("unroll") for (int k = 0; k < 2; ++k) dst[n][k] = *(const LAS bf16x8*)(lds + PG8_SB(b, h) + boff + n * 2048 + k * 1024); } while (0)
; #define PG8_MMA(ai, bj, At, Bt) do { __builtin_amdgcn_s_setprio(1); _Pragma("unroll") for (int m = 0; m < 4; ++m) _Pragma("unroll") for (int n = 0; n < 2; ++n) _Pragma("unroll") for (int k = 0; k < 2; ++k) \
;         acc[ai][bj][m][n] = __builtin_amdgcn_mfma_f32_16x16x32_bf16(Bt[n][k], At[m][k], acc[ai][bj][m][n], 0, 0, 0); __builtin_amdgcn_s_setprio(0); } while (0)
; #define PG8_WAIT_V(n) asm volatile("s_waitcnt vmcnt(" #n ")" ::: "memory")
; #define PG8_WAIT_L(n) asm volatile("s_waitcnt lgkmcnt(" #n ")" ::: "memory")
; #define PG8_BAR __builtin_amdgcn_s_barrier()
; #define PG8_SCHED __builtin_amdgcn_sched_barrier(0)
; template <class Epi, class Sched>
; __device__ __forceinline__ void gemm_phase(LAS unsigned char* lds, const Gemm g, const Sched& S, const Epi& E) {
;     ...
;             PG8_LDB(B0, 1, 0); PG8_LDB(B1, 1, 1); PG8_SCHED; PG8_LDA(At, 1, 0); PG8_STAGE(PG8_SA(0, 1), a2 + hstepA, voffA);
;             PG8_WAIT_V(8); PG8_WAIT_L(0); PG8_BAR; PG8_MMA(0, 0, At, B0); PG8_MMA(0, 1, At, B1); PG8_BAR; PG8_SCHED;
;             PG8_LDA(At, 1, 1); PG8_STAGE(PG8_SB(1, 0), b3, voffB); PG8_STAGE(PG8_SB(1, 1), b3 + hstepB, voffB); PG8_STAGE(PG8_SA(1, 0), a3, voffA);
;             PG8_WAIT_V(8); PG8_WAIT_L(0); PG8_BAR; PG8_MMA(1, 0, At, B0); PG8_MMA(1, 1, At, B1); PG8_BAR; PG8_SCHED;
;         }
;         if (wr == 0) PG8_BAR;
	ds_read_b128 v[146:149], v255 offset:32768
	ds_read_b128 v[150:153], v255 offset:33792
	ds_read_b128 v[154:157], v255 offset:34816
	ds_read_b128 v[158:161], v255 offset:35840
	ds_read_b128 v[162:165], v255 offset:49152
	ds_read_b128 v[166:169], v255 offset:50176
	ds_read_b128 v[170:173], v255 offset:51200
	ds_read_b128 v[190:193], v255 offset:52224
	s_add_u32 s20, s20, s54
	s_addc_u32 s21, s21, 0
	s_mov_b32 m0, s34
	ds_read_b128 v[194:197], v144 offset:32768
	ds_read_b128 v[198:201], v144 offset:33792
	ds_read_b128 v[202:205], v144 offset:34816
	ds_read_b128 v[206:209], v144 offset:35840
	ds_read_b128 v[218:221], v144 offset:36864
	ds_read_b128 v[222:225], v144 offset:37888
	ds_read_b128 v[226:229], v144 offset:38912
	ds_read_b128 v[230:233], v144 offset:39936
	global_load_lds_dwordx4 v130, s[20:21]
	s_mov_b32 m0, s35
	s_nop 0
	global_load_lds_dwordx4 v134, s[20:21]
	s_waitcnt vmcnt(8)
	s_waitcnt lgkmcnt(0)
	s_barrier
	s_waitcnt lgkmcnt(0)
	v_mfma_f32_16x16x32_bf16 v[2:5], v[146:149], v[194:197], v[2:5]
	v_mfma_f32_16x16x32_bf16 v[6:9], v[154:157], v[194:197], v[6:9]
	v_mfma_f32_16x16x32_bf16 v[10:13], v[146:149], v[202:205], v[10:13]
	v_mfma_f32_16x16x32_bf16 v[14:17], v[154:157], v[202:205], v[14:17]
	v_mfma_f32_16x16x32_bf16 v[26:29], v[146:149], v[218:221], v[26:29]
	v_mfma_f32_16x16x32_bf16 v[30:33], v[154:157], v[218:221], v[30:33]
	v_mfma_f32_16x16x32_bf16 v[42:45], v[146:149], v[226:229], v[42:45]
	v_mfma_f32_16x16x32_bf16 v[46:49], v[154:157], v[226:229], v[46:49]
	v_mfma_f32_16x16x32_bf16 v[2:5], v[150:153], v[198:201], v[2:5]
	v_mfma_f32_16x16x32_bf16 v[6:9], v[158:161], v[198:201], v[6:9]
	v_mfma_f32_16x16x32_bf16 v[10:13], v[150:153], v[206:209], v[10:13]
	v_mfma_f32_16x16x32_bf16 v[14:17], v[158:161], v[206:209], v[14:17]
	v_mfma_f32_16x16x32_bf16 v[26:29], v[150:153], v[222:225], v[26:29]
	v_mfma_f32_16x16x32_bf16 v[30:33], v[158:161], v[222:225], v[30:33]
	v_mfma_f32_16x16x32_bf16 v[42:45], v[150:153], v[230:233], v[42:45]
	v_mfma_f32_16x16x32_bf16 v[46:49], v[158:161], v[230:233], v[46:49]
	v_mfma_f32_16x16x32_bf16 v[18:21], v[162:165], v[194:197], v[18:21]
	v_mfma_f32_16x16x32_bf16 v[22:25], v[170:173], v[194:197], v[22:25]
	v_mfma_f32_16x16x32_bf16 v[34:37], v[162:165], v[202:205], v[34:37]
	v_mfma_f32_16x16x32_bf16 v[38:41], v[170:173], v[202:205], v[38:41]
	v_mfma_f32_16x16x32_bf16 v[50:53], v[162:165], v[218:221], v[50:53]
	v_mfma_f32_16x16x32_bf16 v[54:57], v[170:173], v[218:221], v[54:57]
	v_mfma_f32_16x16x32_bf16 v[58:61], v[162:165], v[226:229], v[58:61]
	v_mfma_f32_16x16x32_bf16 v[66:69], v[170:173], v[226:229], v[66:69]
	v_mfma_f32_16x16x32_bf16 v[18:21], v[166:169], v[198:201], v[18:21]
	v_mfma_f32_16x16x32_bf16 v[22:25], v[190:193], v[198:201], v[22:25]
	v_mfma_f32_16x16x32_bf16 v[34:37], v[166:169], v[206:209], v[34:37]
	v_mfma_f32_16x16x32_bf16 v[38:41], v[190:193], v[206:209], v[38:41]
	v_mfma_f32_16x16x32_bf16 v[50:53], v[166:169], v[222:225], v[50:53]
	v_mfma_f32_16x16x32_bf16 v[54:57], v[190:193], v[222:225], v[54:57]
	v_mfma_f32_16x16x32_bf16 v[58:61], v[166:169], v[230:233], v[58:61]
	v_mfma_f32_16x16x32_bf16 v[66:69], v[190:193], v[230:233], v[66:69]
	s_barrier
	s_add_i32 s20, s29, 0x18000
	s_mov_b32 m0, s20
	ds_read_b128 v[194:197], v144 offset:49152
	ds_read_b128 v[198:201], v144 offset:50176
	ds_read_b128 v[202:205], v144 offset:51200
	ds_read_b128 v[206:209], v144 offset:52224
	ds_read_b128 v[218:221], v144 offset:53248
	ds_read_b128 v[222:225], v144 offset:54272
	ds_read_b128 v[226:229], v144 offset:55296
	ds_read_b128 v[230:233], v144 offset:56320
	global_load_lds_dwordx4 v132, s[98:99]
	s_add_i32 m0, s20, 0x2000
	s_add_i32 s20, s29, 0x1c000
	global_load_lds_dwordx4 v136, s[98:99]
	s_add_u32 s98, s98, s8
	s_addc_u32 s99, s99, 0
	s_mov_b32 m0, s20
	s_nop 0
	global_load_lds_dwordx4 v132, s[98:99]
	s_add_i32 m0, s20, 0x2000
	s_nop 0
	global_load_lds_dwordx4 v136, s[98:99]
	s_mov_b32 m0, s40
	s_nop 0
	global_load_lds_dwordx4 v130, s[100:101]
	s_mov_b32 m0, s41
	s_nop 0
	global_load_lds_dwordx4 v134, s[100:101]
	s_waitcnt vmcnt(8)
	s_waitcnt lgkmcnt(0)
	s_barrier
	s_waitcnt lgkmcnt(0)
	v_mfma_f32_16x16x32_bf16 v[62:65], v[146:149], v[194:197], v[62:65]
	v_mfma_f32_16x16x32_bf16 v[70:73], v[154:157], v[194:197], v[70:73]
	v_mfma_f32_16x16x32_bf16 v[78:81], v[146:149], v[202:205], v[78:81]
	v_mfma_f32_16x16x32_bf16 v[82:85], v[154:157], v[202:205], v[82:85]
	v_mfma_f32_16x16x32_bf16 v[90:93], v[146:149], v[218:221], v[90:93]
	v_mfma_f32_16x16x32_bf16 v[94:97], v[154:157], v[218:221], v[94:97]
	v_mfma_f32_16x16x32_bf16 v[106:109], v[146:149], v[226:229], v[106:109]
	v_mfma_f32_16x16x32_bf16 v[110:113], v[154:157], v[226:229], v[110:113]
	v_mfma_f32_16x16x32_bf16 v[62:65], v[150:153], v[198:201], v[62:65]
	v_mfma_f32_16x16x32_bf16 v[70:73], v[158:161], v[198:201], v[70:73]
	v_mfma_f32_16x16x32_bf16 v[78:81], v[150:153], v[206:209], v[78:81]
	v_mfma_f32_16x16x32_bf16 v[82:85], v[158:161], v[206:209], v[82:85]
	v_mfma_f32_16x16x32_bf16 v[90:93], v[150:153], v[222:225], v[90:93]
	v_mfma_f32_16x16x32_bf16 v[94:97], v[158:161], v[222:225], v[94:97]
	v_mfma_f32_16x16x32_bf16 v[106:109], v[150:153], v[230:233], v[106:109]
	v_mfma_f32_16x16x32_bf16 v[110:113], v[158:161], v[230:233], v[110:113]
	v_mfma_f32_16x16x32_bf16 v[74:77], v[162:165], v[194:197], v[74:77]
	v_mfma_f32_16x16x32_bf16 v[86:89], v[170:173], v[194:197], v[86:89]
	v_mfma_f32_16x16x32_bf16 v[98:101], v[162:165], v[202:205], v[98:101]
	v_mfma_f32_16x16x32_bf16 v[102:105], v[170:173], v[202:205], v[102:105]
	v_mfma_f32_16x16x32_bf16 v[114:117], v[162:165], v[218:221], v[114:117]
	v_mfma_f32_16x16x32_bf16 v[118:121], v[170:173], v[218:221], v[118:121]
	v_mfma_f32_16x16x32_bf16 v[122:125], v[162:165], v[226:229], v[122:125]
	v_mfma_f32_16x16x32_bf16 v[126:129], v[170:173], v[226:229], v[126:129]
	v_mfma_f32_16x16x32_bf16 v[74:77], v[166:169], v[198:201], v[74:77]
	v_mfma_f32_16x16x32_bf16 v[86:89], v[190:193], v[198:201], v[86:89]
	v_mfma_f32_16x16x32_bf16 v[98:101], v[166:169], v[206:209], v[98:101]
	v_mfma_f32_16x16x32_bf16 v[102:105], v[190:193], v[206:209], v[102:105]
	v_mfma_f32_16x16x32_bf16 v[114:117], v[166:169], v[222:225], v[114:117]
	v_mfma_f32_16x16x32_bf16 v[118:121], v[190:193], v[222:225], v[118:121]
	v_mfma_f32_16x16x32_bf16 v[122:125], v[166:169], v[230:233], v[122:125]
	v_mfma_f32_16x16x32_bf16 v[126:129], v[190:193], v[230:233], v[126:129]
	s_barrier
	s_add_u32 s18, s18, 0x100
	s_addc_u32 s19, s19, 0
	s_add_u32 s82, s82, 0x100
	s_addc_u32 s83, s83, 0
	s_cmp_ge_u32 s87, s42
	s_mov_b32 s20, s87
	s_cbranch_scc0 .LBB0_640
	s_and_b64 vcc, exec, s[70:71]
	s_cbranch_vccz .LBB0_643
	s_barrier
